# strategy 4 on all GEMM phases: waves 4-7 at static priority 1, per-cluster s_setprio flips neutralised (on v6)
# baseline (speedup 1.0000x reference)
; #define KA_DEF const __attribute__((address_space(4))) KArgs* ka_ = (const __attribute__((address_space(4))) KArgs*)__builtin_amdgcn_kernarg_segment_ptr(); asm volatile("" : "+s"(ka_));
; #define MEMSSQ ((float*)WSP(WS_MEMSSQ))
;     __host__ __device__ bool next(int i, Unit& u) const {
;         const long L = (long)i * G + c; if (L >= nwg) return false;
;         int wgid = (int)L; { const int q = nwg / NXCD, r = nwg % NXCD, xcd = wgid % NXCD, off = wgid / NXCD; wgid = (xcd < r ? xcd * (q + 1) : r * (q + 1) + (xcd - r) * q) + off; }
;         const int nig = WGM * nN, gid = wgid / nig, fm = gid * WGM, gsz = (nM - fm) < WGM ? (nM - fm) : WGM;
;         u.pm = fm + ((wgid % nig) % gsz); u.pn = (wgid % nig) / gsz; return true;
; __global__ void __launch_bounds__(512, 2) mega_fwd(KArgs a) {
;     ...
;     { KA_DEF pg8::EpiBf16S E{KVRAW, 8192, MEMSSQ}; run_gemm(TIDX, lds, MEMB, XKV, NBATCH * MEMLEN, 8192, 1024, E); }
.LBB0_1621:
	s_or_b64 exec, exec, s[0:1]
	s_mov_b64 s[0:1], s[88:89]
	s_waitcnt lgkmcnt(0)
	s_barrier
	v_readfirstlane_b32 vcc_lo, v220
	s_nop 1
	s_bitcmp1_b32 vcc_lo, 8
	s_cbranch_scc0 .Lmy_prio_skip_1
	s_setprio 1
.Lmy_prio_skip_1:
	s_load_dwordx2 s[0:1], s[0:1], 0x100
	s_movk_i32 s4, 0x800
	s_movk_i32 s5, 0x2000
	s_movk_i32 s18, 0x400
	s_waitcnt lgkmcnt(0)
	s_add_u32 s2, s0, 0x8100000
	s_addc_u32 s3, s1, 0
	s_add_u32 s6, s0, 0x3000000
	s_addc_u32 s7, s1, 0
	s_ashr_i32 s8, s4, 31
	s_lshr_b32 s8, s8, 24
	s_add_i32 s4, s4, s8
	s_ashr_i32 s28, s4, 8
	s_ashr_i32 s4, s5, 31
	s_lshr_b32 s4, s4, 24
	s_add_i32 s5, s5, s4
	s_ashr_i32 s12, s5, 8
	s_mul_i32 s4, s12, s28
	v_mov_b32_e32 v12, v220
	s_cmp_ge_i32 s86, s4
	v_readfirstlane_b32 s20, v12
	s_cbranch_scc1 .LBB0_1650
	s_ashr_i32 s5, s4, 31
	s_lshr_b32 s8, s5, 29
	s_add_i32 s8, s4, s8
	s_ashr_i32 s29, s8, 3
	s_and_b32 s8, s8, -8
	s_ashr_i32 s31, s86, 31
	s_sub_i32 s30, s4, s8
	s_lshr_b32 s8, s31, 29
	s_add_i32 s10, s86, s8
	s_and_b32 s8, s10, -8
	s_sub_i32 s11, s86, s8
	s_add_i32 s34, s29, 1
	s_cmp_ge_i32 s11, s30
	s_mul_i32 s35, s34, s30
	s_cbranch_scc0 .LBB0_1624
	s_sub_i32 s8, s11, s30
	s_mul_i32 s8, s8, s29
	s_add_i32 s13, s8, s35
	s_cbranch_execz .LBB0_1625
	s_branch .LBB0_1626

; #define PG8_STAGE(bufoff, gbase, voff) do { _Pragma("unroll") for (int _i = 0; _i < 2; ++_i) \
;         __builtin_amdgcn_global_load_lds((const unsigned*)((const char*)(gbase) + (voff)[_i]), (PG8_LAS unsigned*)(lds + (bufoff) + ldsw + _i * 8192), 16, 0, 0); } while (0)
; #define PG8_LDA(dst, b, h) do { _Pragma("unroll") for (int m = 0; m < 4; ++m) _Pragma("unroll") for (int k = 0; k < 2; ++k) dst[m][k] = *(const PG8_LAS bf16x8*)(lds + PG8_SA(b, h) + aoff + m * 2048 + k * 1024); } while (0)
; #define PG8_LDB(dst, b, h) do { _Pragma("unroll") for (int n = 0; n < 2; ++n) _Pragma("unroll") for (int k = 0; k < 2; ++k) dst[n][k] = *(const PG8_LAS bf16x8*)(lds + PG8_SB(b, h) + boff + n * 2048 + k * 1024); } while (0)
; #define PG8_MMA(ai, bj, At, Bt) do { __builtin_amdgcn_s_setprio(1); _Pragma("unroll") for (int m = 0; m < 4; ++m) _Pragma("unroll") for (int n = 0; n < 2; ++n) _Pragma("unroll") for (int k = 0; k < 2; ++k) \
;         acc[ai][bj][m][n] = __builtin_amdgcn_mfma_f32_16x16x32_bf16(Bt[n][k], At[m][k], acc[ai][bj][m][n], 0, 0, 0); __builtin_amdgcn_s_setprio(0); } while (0)
; #define PG8_WAIT_V(n) asm volatile("s_waitcnt vmcnt(" #n ")" ::: "memory")
; #define PG8_WAIT_L(n) asm volatile("s_waitcnt lgkmcnt(" #n ")" ::: "memory")
; #define PG8_BAR __builtin_amdgcn_s_barrier()
; #define PG8_SCHED __builtin_amdgcn_sched_barrier(0)
; template <class Epi, class Sched, bool ALIGN_EPI = false, bool SP2 = false>
; __device__ __forceinline__ void gemm_phase(PG8_LAS unsigned char* lds, const Gemm g, const Sched& S, const Epi& E) {
;     ...
;             PG8_LDB(B0, 0, 0); PG8_LDB(B1, 0, 1); PG8_SCHED; PG8_LDA(At, 0, 0); PG8_STAGE(PG8_SA(1, 1), a1 + hstep, voffA);
;             PG8_WAIT_V(8); PG8_WAIT_L(0); PG8_BAR; PG8_MMA(0, 0, At, B0); PG8_MMA(0, 1, At, B1); PG8_BAR; PG8_SCHED;
;             PG8_LDA(At, 0, 1); PG8_STAGE(PG8_SB(0, 0), b2, voffB); PG8_STAGE(PG8_SB(0, 1), b2 + hstep, voffB); PG8_STAGE(PG8_SA(0, 0), a2, voffA);
;             PG8_WAIT_V(8); PG8_WAIT_L(0); PG8_BAR; PG8_MMA(1, 0, At, B0); PG8_MMA(1, 1, At, B1); PG8_BAR; PG8_SCHED;
.LBB0_1643:
	ds_read_b128 v[144:147], v178
	ds_read_b128 v[150:153], v178 offset:1024
	ds_read_b128 v[156:159], v178 offset:2048
	ds_read_b128 v[182:185], v178 offset:3072
	ds_read_b128 v[186:189], v179
	ds_read_b128 v[190:193], v179 offset:1024
	ds_read_b128 v[194:197], v179 offset:2048
	ds_read_b128 v[198:201], v179 offset:3072
	s_add_i32 s60, s26, 2
	s_add_u32 s61, s24, 0x80
	s_addc_u32 s27, s25, 0
	s_cmp_eq_u32 s49, s26
	s_cselect_b32 s26, s0, s61
	s_cselect_b32 s27, s1, s27
	s_cselect_b32 s63, s23, s59
	s_cselect_b32 s62, s22, s58
	v_lshl_add_u64 v[162:163], s[24:25], 0, v[140:141]
	s_add_i32 m0, s41, 0xc000
	ds_read_b128 v[202:205], v180
	ds_read_b128 v[206:209], v180 offset:1024
	ds_read_b128 v[210:213], v180 offset:2048
	ds_read_b128 v[214:217], v180 offset:3072
	ds_read_b128 v[222:225], v180 offset:4096
	ds_read_b128 v[226:229], v180 offset:5120
	ds_read_b128 v[230:233], v180 offset:6144
	ds_read_b128 v[234:237], v180 offset:7168
	global_load_lds_dwordx4 v[162:163], off
	v_lshl_add_u64 v[162:163], s[24:25], 0, v[138:139]
	s_add_i32 m0, s41, 0xe000
	s_nop 0
	global_load_lds_dwordx4 v[162:163], off
	s_waitcnt vmcnt(8)
	s_waitcnt lgkmcnt(0)
	s_barrier
	s_nop 0
	s_waitcnt lgkmcnt(0)
	v_mfma_f32_16x16x32_bf16 v[124:127], v[144:147], v[202:205], v[124:127]
	v_mfma_f32_16x16x32_bf16 v[120:123], v[156:159], v[202:205], v[120:123]
	v_mfma_f32_16x16x32_bf16 v[108:111], v[144:147], v[210:213], v[108:111]
	v_mfma_f32_16x16x32_bf16 v[104:107], v[156:159], v[210:213], v[104:107]
	v_mfma_f32_16x16x32_bf16 v[92:95], v[144:147], v[222:225], v[92:95]
	v_mfma_f32_16x16x32_bf16 v[88:91], v[156:159], v[222:225], v[88:91]
	v_mfma_f32_16x16x32_bf16 v[76:79], v[144:147], v[230:233], v[76:79]
	v_mfma_f32_16x16x32_bf16 v[72:75], v[156:159], v[230:233], v[72:75]
	v_mfma_f32_16x16x32_bf16 v[124:127], v[150:153], v[206:209], v[124:127]
	v_mfma_f32_16x16x32_bf16 v[120:123], v[182:185], v[206:209], v[120:123]
	v_mfma_f32_16x16x32_bf16 v[108:111], v[150:153], v[214:217], v[108:111]
	v_mfma_f32_16x16x32_bf16 v[104:107], v[182:185], v[214:217], v[104:107]
	v_mfma_f32_16x16x32_bf16 v[92:95], v[150:153], v[226:229], v[92:95]
	v_mfma_f32_16x16x32_bf16 v[88:91], v[182:185], v[226:229], v[88:91]
	v_mfma_f32_16x16x32_bf16 v[76:79], v[150:153], v[234:237], v[76:79]
	v_mfma_f32_16x16x32_bf16 v[72:75], v[182:185], v[234:237], v[72:75]
	s_nop 0
	s_nop 0
	v_mfma_f32_16x16x32_bf16 v[116:119], v[186:189], v[202:205], v[116:119]
	v_mfma_f32_16x16x32_bf16 v[112:115], v[194:197], v[202:205], v[112:115]
	v_mfma_f32_16x16x32_bf16 v[100:103], v[186:189], v[210:213], v[100:103]
	v_mfma_f32_16x16x32_bf16 v[96:99], v[194:197], v[210:213], v[96:99]
	v_mfma_f32_16x16x32_bf16 v[84:87], v[186:189], v[222:225], v[84:87]
	v_mfma_f32_16x16x32_bf16 v[80:83], v[194:197], v[222:225], v[80:83]
	v_mfma_f32_16x16x32_bf16 v[68:71], v[186:189], v[230:233], v[68:71]
	v_mfma_f32_16x16x32_bf16 v[64:67], v[194:197], v[230:233], v[64:67]
	v_mfma_f32_16x16x32_bf16 v[116:119], v[190:193], v[206:209], v[116:119]
	v_mfma_f32_16x16x32_bf16 v[112:115], v[198:201], v[206:209], v[112:115]
	v_mfma_f32_16x16x32_bf16 v[100:103], v[190:193], v[214:217], v[100:103]
	v_mfma_f32_16x16x32_bf16 v[96:99], v[198:201], v[214:217], v[96:99]
	v_mfma_f32_16x16x32_bf16 v[84:87], v[190:193], v[226:229], v[84:87]
	v_mfma_f32_16x16x32_bf16 v[80:83], v[198:201], v[226:229], v[80:83]
	v_mfma_f32_16x16x32_bf16 v[68:71], v[190:193], v[234:237], v[68:71]
	v_mfma_f32_16x16x32_bf16 v[64:67], v[198:201], v[234:237], v[64:67]
	s_nop 0
	s_barrier
	s_add_i32 s61, s52, s38
	v_lshl_add_u64 v[162:163], s[62:63], 0, v[130:131]
	s_mov_b32 m0, s61
	ds_read_b128 v[202:205], v180 offset:16384
	ds_read_b128 v[206:209], v180 offset:17408
	ds_read_b128 v[210:213], v180 offset:18432
	ds_read_b128 v[214:217], v180 offset:19456
	ds_read_b128 v[222:225], v180 offset:20480
	ds_read_b128 v[226:229], v180 offset:21504
	ds_read_b128 v[230:233], v180 offset:22528
	ds_read_b128 v[234:237], v180 offset:23552
	global_load_lds_dwordx4 v[162:163], off
	s_add_i32 m0, s61, 0x2000
	v_lshl_add_u64 v[166:167], s[62:63], 0, v[134:135]
	s_add_u32 s62, s62, s8
	s_addc_u32 s63, s63, s9
	s_add_i32 s61, s53, s38
	global_load_lds_dwordx4 v[166:167], off
	v_lshl_add_u64 v[218:219], s[62:63], 0, v[130:131]
	s_mov_b32 m0, s61
	v_lshl_add_u64 v[238:239], s[62:63], 0, v[134:135]
	global_load_lds_dwordx4 v[218:219], off
	s_add_i32 m0, s61, 0x2000
	v_lshl_add_u64 v[240:241], s[26:27], 0, v[128:129]
	global_load_lds_dwordx4 v[238:239], off
	s_mov_b32 m0, s41
	v_lshl_add_u64 v[242:243], s[26:27], 0, v[132:133]
	global_load_lds_dwordx4 v[240:241], off
	s_mov_b32 m0, s42
	s_nop 0
	global_load_lds_dwordx4 v[242:243], off
	s_waitcnt vmcnt(8)
	s_waitcnt lgkmcnt(0)
	s_barrier
; #define PG8_STAGE(bufoff, gbase, voff) do { _Pragma("unroll") for (int _i = 0; _i < 2; ++_i) \
;         __builtin_amdgcn_global_load_lds((const unsigned*)((const char*)(gbase) + (voff)[_i]), (PG8_LAS unsigned*)(lds + (bufoff) + ldsw + _i * 8192), 16, 0, 0); } while (0)
; #define PG8_LDA(dst, b, h) do { _Pragma("unroll") for (int m = 0; m < 4; ++m) _Pragma("unroll") for (int k = 0; k < 2; ++k) dst[m][k] = *(const PG8_LAS bf16x8*)(lds + PG8_SA(b, h) + aoff + m * 2048 + k * 1024); } while (0)
; #define PG8_LDB(dst, b, h) do { _Pragma("unroll") for (int n = 0; n < 2; ++n) _Pragma("unroll") for (int k = 0; k < 2; ++k) dst[n][k] = *(const PG8_LAS bf16x8*)(lds + PG8_SB(b, h) + boff + n * 2048 + k * 1024); } while (0)
; #define PG8_MMA(ai, bj, At, Bt) do { __builtin_amdgcn_s_setprio(1); _Pragma("unroll") for (int m = 0; m < 4; ++m) _Pragma("unroll") for (int n = 0; n < 2; ++n) _Pragma("unroll") for (int k = 0; k < 2; ++k) \
;         acc[ai][bj][m][n] = __builtin_amdgcn_mfma_f32_16x16x32_bf16(Bt[n][k], At[m][k], acc[ai][bj][m][n], 0, 0, 0); __builtin_amdgcn_s_setprio(0); } while (0)
; #define PG8_WAIT_V(n) asm volatile("s_waitcnt vmcnt(" #n ")" ::: "memory")
; #define PG8_WAIT_L(n) asm volatile("s_waitcnt lgkmcnt(" #n ")" ::: "memory")
; #define PG8_BAR __builtin_amdgcn_s_barrier()
; #define PG8_SCHED __builtin_amdgcn_sched_barrier(0)
; template <class Epi, class Sched, bool ALIGN_EPI = false, bool SP2 = false>
; __device__ __forceinline__ void gemm_phase(PG8_LAS unsigned char* lds, const Gemm g, const Sched& S, const Epi& E) {
;     ...
;             PG8_WAIT_V(8); PG8_WAIT_L(0); PG8_BAR; PG8_MMA(1, 0, At, B0); PG8_MMA(1, 1, At, B1); PG8_BAR; PG8_SCHED;
;             PG8_LDB(B0, 1, 0); PG8_LDB(B1, 1, 1); PG8_SCHED; PG8_LDA(At, 1, 0); PG8_STAGE(PG8_SA(0, 1), a2 + hstep, voffA);
;             PG8_WAIT_V(8); PG8_WAIT_L(0); PG8_BAR; PG8_MMA(0, 0, At, B0); PG8_MMA(0, 1, At, B1); PG8_BAR; PG8_SCHED;
	s_nop 0
	s_waitcnt lgkmcnt(0)
	v_mfma_f32_16x16x32_bf16 v[60:63], v[144:147], v[202:205], v[60:63]
	v_mfma_f32_16x16x32_bf16 v[56:59], v[156:159], v[202:205], v[56:59]
	v_mfma_f32_16x16x32_bf16 v[44:47], v[144:147], v[210:213], v[44:47]
	v_mfma_f32_16x16x32_bf16 v[40:43], v[156:159], v[210:213], v[40:43]
	v_mfma_f32_16x16x32_bf16 v[28:31], v[144:147], v[222:225], v[28:31]
	v_mfma_f32_16x16x32_bf16 v[24:27], v[156:159], v[222:225], v[24:27]
	v_mfma_f32_16x16x32_bf16 v[12:15], v[144:147], v[230:233], v[12:15]
	v_mfma_f32_16x16x32_bf16 v[8:11], v[156:159], v[230:233], v[8:11]
	v_mfma_f32_16x16x32_bf16 v[60:63], v[150:153], v[206:209], v[60:63]
	v_mfma_f32_16x16x32_bf16 v[56:59], v[182:185], v[206:209], v[56:59]
	v_mfma_f32_16x16x32_bf16 v[44:47], v[150:153], v[214:217], v[44:47]
	v_mfma_f32_16x16x32_bf16 v[40:43], v[182:185], v[214:217], v[40:43]
	v_mfma_f32_16x16x32_bf16 v[28:31], v[150:153], v[226:229], v[28:31]
	v_mfma_f32_16x16x32_bf16 v[24:27], v[182:185], v[226:229], v[24:27]
	v_mfma_f32_16x16x32_bf16 v[12:15], v[150:153], v[234:237], v[12:15]
	v_mfma_f32_16x16x32_bf16 v[8:11], v[182:185], v[234:237], v[8:11]
	s_nop 0
	s_nop 0
	v_mfma_f32_16x16x32_bf16 v[52:55], v[186:189], v[202:205], v[52:55]
	v_mfma_f32_16x16x32_bf16 v[48:51], v[194:197], v[202:205], v[48:51]
	v_mfma_f32_16x16x32_bf16 v[36:39], v[186:189], v[210:213], v[36:39]
	v_mfma_f32_16x16x32_bf16 v[32:35], v[194:197], v[210:213], v[32:35]
	v_mfma_f32_16x16x32_bf16 v[20:23], v[186:189], v[222:225], v[20:23]
	v_mfma_f32_16x16x32_bf16 v[16:19], v[194:197], v[222:225], v[16:19]
	v_mfma_f32_16x16x32_bf16 v[4:7], v[186:189], v[230:233], v[4:7]
	v_mfma_f32_16x16x32_bf16 v[0:3], v[194:197], v[230:233], v[0:3]
	v_mfma_f32_16x16x32_bf16 v[52:55], v[190:193], v[206:209], v[52:55]
	v_mfma_f32_16x16x32_bf16 v[48:51], v[198:201], v[206:209], v[48:51]
	v_mfma_f32_16x16x32_bf16 v[36:39], v[190:193], v[214:217], v[36:39]
	v_mfma_f32_16x16x32_bf16 v[32:35], v[198:201], v[214:217], v[32:35]
	v_mfma_f32_16x16x32_bf16 v[20:23], v[190:193], v[226:229], v[20:23]
	v_mfma_f32_16x16x32_bf16 v[16:19], v[198:201], v[226:229], v[16:19]
	v_mfma_f32_16x16x32_bf16 v[4:7], v[190:193], v[234:237], v[4:7]
	v_mfma_f32_16x16x32_bf16 v[0:3], v[198:201], v[234:237], v[0:3]
	s_nop 0
	s_barrier
	s_add_i32 s61, 0, 0x18000
	v_add_u32_e32 v148, s61, v174
	s_add_i32 s62, 0, 0x1c000
	ds_read_b128 v[144:147], v148
	ds_read_b128 v[150:153], v148 offset:1024
	ds_read_b128 v[156:159], v148 offset:2048
	ds_read_b128 v[182:185], v148 offset:3072
	v_add_u32_e32 v148, s62, v174
	ds_read_b128 v[186:189], v148
	ds_read_b128 v[190:193], v148 offset:1024
	ds_read_b128 v[194:197], v148 offset:2048
	ds_read_b128 v[198:201], v148 offset:3072
	s_add_u32 s26, s26, s8
	s_addc_u32 s27, s27, s9
	s_mov_b32 m0, s43
	v_lshl_add_u64 v[244:245], s[26:27], 0, v[128:129]
	ds_read_b128 v[202:205], v180 offset:32768
	ds_read_b128 v[206:209], v180 offset:33792
	ds_read_b128 v[210:213], v180 offset:34816
	ds_read_b128 v[214:217], v180 offset:35840
	ds_read_b128 v[222:225], v180 offset:36864
	ds_read_b128 v[226:229], v180 offset:37888
	ds_read_b128 v[230:233], v180 offset:38912
	ds_read_b128 v[234:237], v180 offset:39936
	global_load_lds_dwordx4 v[244:245], off
	v_lshl_add_u64 v[244:245], s[26:27], 0, v[132:133]
	s_mov_b32 m0, s44
	s_nop 0
	global_load_lds_dwordx4 v[244:245], off
	s_waitcnt vmcnt(8)
	s_waitcnt lgkmcnt(0)
	s_barrier
	s_nop 0
	s_waitcnt lgkmcnt(0)
	v_mfma_f32_16x16x32_bf16 v[124:127], v[144:147], v[202:205], v[124:127]
	v_mfma_f32_16x16x32_bf16 v[120:123], v[156:159], v[202:205], v[120:123]
	v_mfma_f32_16x16x32_bf16 v[108:111], v[144:147], v[210:213], v[108:111]
	v_mfma_f32_16x16x32_bf16 v[104:107], v[156:159], v[210:213], v[104:107]
	v_mfma_f32_16x16x32_bf16 v[92:95], v[144:147], v[222:225], v[92:95]
	v_mfma_f32_16x16x32_bf16 v[88:91], v[156:159], v[222:225], v[88:91]
	v_mfma_f32_16x16x32_bf16 v[76:79], v[144:147], v[230:233], v[76:79]
	v_mfma_f32_16x16x32_bf16 v[72:75], v[156:159], v[230:233], v[72:75]
	v_mfma_f32_16x16x32_bf16 v[124:127], v[150:153], v[206:209], v[124:127]
	v_mfma_f32_16x16x32_bf16 v[120:123], v[182:185], v[206:209], v[120:123]
	v_mfma_f32_16x16x32_bf16 v[108:111], v[150:153], v[214:217], v[108:111]
	v_mfma_f32_16x16x32_bf16 v[104:107], v[182:185], v[214:217], v[104:107]
	v_mfma_f32_16x16x32_bf16 v[92:95], v[150:153], v[226:229], v[92:95]
	v_mfma_f32_16x16x32_bf16 v[88:91], v[182:185], v[226:229], v[88:91]
	v_mfma_f32_16x16x32_bf16 v[76:79], v[150:153], v[234:237], v[76:79]
	v_mfma_f32_16x16x32_bf16 v[72:75], v[182:185], v[234:237], v[72:75]
	s_nop 0
	s_nop 0
	v_mfma_f32_16x16x32_bf16 v[116:119], v[186:189], v[202:205], v[116:119]
	v_mfma_f32_16x16x32_bf16 v[112:115], v[194:197], v[202:205], v[112:115]
	v_mfma_f32_16x16x32_bf16 v[100:103], v[186:189], v[210:213], v[100:103]
	v_mfma_f32_16x16x32_bf16 v[96:99], v[194:197], v[210:213], v[96:99]
	v_mfma_f32_16x16x32_bf16 v[84:87], v[186:189], v[222:225], v[84:87]
	v_mfma_f32_16x16x32_bf16 v[80:83], v[194:197], v[222:225], v[80:83]
	v_mfma_f32_16x16x32_bf16 v[68:71], v[186:189], v[230:233], v[68:71]
	v_mfma_f32_16x16x32_bf16 v[64:67], v[194:197], v[230:233], v[64:67]
	v_mfma_f32_16x16x32_bf16 v[116:119], v[190:193], v[206:209], v[116:119]
	v_mfma_f32_16x16x32_bf16 v[112:115], v[198:201], v[206:209], v[112:115]
	v_mfma_f32_16x16x32_bf16 v[100:103], v[190:193], v[214:217], v[100:103]
	v_mfma_f32_16x16x32_bf16 v[96:99], v[198:201], v[214:217], v[96:99]
	v_mfma_f32_16x16x32_bf16 v[84:87], v[190:193], v[226:229], v[84:87]
	v_mfma_f32_16x16x32_bf16 v[80:83], v[198:201], v[226:229], v[80:83]
	v_mfma_f32_16x16x32_bf16 v[68:71], v[190:193], v[234:237], v[68:71]
	v_mfma_f32_16x16x32_bf16 v[64:67], v[198:201], v[234:237], v[64:67]
	s_nop 0
	s_barrier
; #define PG8_STAGE(bufoff, gbase, voff) do { _Pragma("unroll") for (int _i = 0; _i < 2; ++_i) \
;         __builtin_amdgcn_global_load_lds((const unsigned*)((const char*)(gbase) + (voff)[_i]), (PG8_LAS unsigned*)(lds + (bufoff) + ldsw + _i * 8192), 16, 0, 0); } while (0)
; #define PG8_LDA(dst, b, h) do { _Pragma("unroll") for (int m = 0; m < 4; ++m) _Pragma("unroll") for (int k = 0; k < 2; ++k) dst[m][k] = *(const PG8_LAS bf16x8*)(lds + PG8_SA(b, h) + aoff + m * 2048 + k * 1024); } while (0)
; #define PG8_MMA(ai, bj, At, Bt) do { __builtin_amdgcn_s_setprio(1); _Pragma("unroll") for (int m = 0; m < 4; ++m) _Pragma("unroll") for (int n = 0; n < 2; ++n) _Pragma("unroll") for (int k = 0; k < 2; ++k) \
;         acc[ai][bj][m][n] = __builtin_amdgcn_mfma_f32_16x16x32_bf16(Bt[n][k], At[m][k], acc[ai][bj][m][n], 0, 0, 0); __builtin_amdgcn_s_setprio(0); } while (0)
; #define PG8_WAIT_V(n) asm volatile("s_waitcnt vmcnt(" #n ")" ::: "memory")
; #define PG8_WAIT_L(n) asm volatile("s_waitcnt lgkmcnt(" #n ")" ::: "memory")
; #define PG8_BAR __builtin_amdgcn_s_barrier()
; #define PG8_SCHED __builtin_amdgcn_sched_barrier(0)
; template <class Epi, class Sched, bool ALIGN_EPI = false, bool SP2 = false>
; __device__ __forceinline__ void gemm_phase(PG8_LAS unsigned char* lds, const Gemm g, const Sched& S, const Epi& E) {
;     ...
;         for (int t = 0; t < nt; t += 2) {
;             const bool last = (t == nt - 2);
;             const char* a1 = cA + (size_t)(t + 1) * kstep;
;             const char* a2 = last ? nA : cA + (size_t)(t + 2) * kstep; const char* b2 = last ? nB : cB + (size_t)(t + 2) * kstep;
;             const char* a3 = a2 + kstep; const char* b3 = b2 + kstep;
;     ...
;             PG8_LDA(At, 1, 1); PG8_STAGE(PG8_SB(1, 0), b3, voffB); PG8_STAGE(PG8_SB(1, 1), b3 + hstep, voffB); PG8_STAGE(PG8_SA(1, 0), a3, voffA);
;             PG8_WAIT_V(8); PG8_WAIT_L(0); PG8_BAR; PG8_MMA(1, 0, At, B0); PG8_MMA(1, 1, At, B1); PG8_BAR; PG8_SCHED;
	s_add_i32 s26, s61, s38
	v_lshl_add_u64 v[162:163], v[162:163], 0, s[16:17]
	s_mov_b32 m0, s26
	ds_read_b128 v[202:205], v180 offset:49152
	ds_read_b128 v[206:209], v180 offset:50176
	ds_read_b128 v[210:213], v180 offset:51200
	ds_read_b128 v[214:217], v180 offset:52224
	ds_read_b128 v[222:225], v180 offset:53248
	ds_read_b128 v[226:229], v180 offset:54272
	ds_read_b128 v[230:233], v180 offset:55296
	ds_read_b128 v[234:237], v180 offset:56320
	global_load_lds_dwordx4 v[162:163], off
	v_lshl_add_u64 v[162:163], v[166:167], 0, s[16:17]
	s_add_i32 m0, s26, 0x2000
	s_add_i32 s26, s62, s38
	global_load_lds_dwordx4 v[162:163], off
	v_lshl_add_u64 v[162:163], v[218:219], 0, s[16:17]
	s_mov_b32 m0, s26
	s_nop 0
	global_load_lds_dwordx4 v[162:163], off
	v_lshl_add_u64 v[162:163], v[238:239], 0, s[16:17]
	s_add_i32 m0, s26, 0x2000
	s_nop 0
	global_load_lds_dwordx4 v[162:163], off
	v_lshl_add_u64 v[162:163], v[240:241], 0, s[16:17]
	s_mov_b32 m0, s46
	s_nop 0
	global_load_lds_dwordx4 v[162:163], off
	v_lshl_add_u64 v[162:163], v[242:243], 0, s[16:17]
	s_mov_b32 m0, s47
	s_nop 0
	global_load_lds_dwordx4 v[162:163], off
	s_waitcnt vmcnt(8)
	s_waitcnt lgkmcnt(0)
	s_barrier
	s_nop 0
	s_waitcnt lgkmcnt(0)
	v_mfma_f32_16x16x32_bf16 v[60:63], v[144:147], v[202:205], v[60:63]
	v_mfma_f32_16x16x32_bf16 v[56:59], v[156:159], v[202:205], v[56:59]
	v_mfma_f32_16x16x32_bf16 v[44:47], v[144:147], v[210:213], v[44:47]
	v_mfma_f32_16x16x32_bf16 v[40:43], v[156:159], v[210:213], v[40:43]
	v_mfma_f32_16x16x32_bf16 v[28:31], v[144:147], v[222:225], v[28:31]
	v_mfma_f32_16x16x32_bf16 v[24:27], v[156:159], v[222:225], v[24:27]
	v_mfma_f32_16x16x32_bf16 v[12:15], v[144:147], v[230:233], v[12:15]
	v_mfma_f32_16x16x32_bf16 v[8:11], v[156:159], v[230:233], v[8:11]
	v_mfma_f32_16x16x32_bf16 v[60:63], v[150:153], v[206:209], v[60:63]
	v_mfma_f32_16x16x32_bf16 v[56:59], v[182:185], v[206:209], v[56:59]
	v_mfma_f32_16x16x32_bf16 v[44:47], v[150:153], v[214:217], v[44:47]
	v_mfma_f32_16x16x32_bf16 v[40:43], v[182:185], v[214:217], v[40:43]
	v_mfma_f32_16x16x32_bf16 v[28:31], v[150:153], v[226:229], v[28:31]
	v_mfma_f32_16x16x32_bf16 v[24:27], v[182:185], v[226:229], v[24:27]
	v_mfma_f32_16x16x32_bf16 v[12:15], v[150:153], v[234:237], v[12:15]
	v_mfma_f32_16x16x32_bf16 v[8:11], v[182:185], v[234:237], v[8:11]
	s_nop 0
	s_nop 0
	v_mfma_f32_16x16x32_bf16 v[52:55], v[186:189], v[202:205], v[52:55]
	v_mfma_f32_16x16x32_bf16 v[48:51], v[194:197], v[202:205], v[48:51]
	v_mfma_f32_16x16x32_bf16 v[36:39], v[186:189], v[210:213], v[36:39]
	v_mfma_f32_16x16x32_bf16 v[32:35], v[194:197], v[210:213], v[32:35]
	v_mfma_f32_16x16x32_bf16 v[20:23], v[186:189], v[222:225], v[20:23]
	v_mfma_f32_16x16x32_bf16 v[16:19], v[194:197], v[222:225], v[16:19]
	v_mfma_f32_16x16x32_bf16 v[4:7], v[186:189], v[230:233], v[4:7]
	v_mfma_f32_16x16x32_bf16 v[0:3], v[194:197], v[230:233], v[0:3]
	v_mfma_f32_16x16x32_bf16 v[52:55], v[190:193], v[206:209], v[52:55]
	v_mfma_f32_16x16x32_bf16 v[48:51], v[198:201], v[206:209], v[48:51]
	v_mfma_f32_16x16x32_bf16 v[36:39], v[190:193], v[214:217], v[36:39]
	v_mfma_f32_16x16x32_bf16 v[32:35], v[198:201], v[214:217], v[32:35]
	v_mfma_f32_16x16x32_bf16 v[20:23], v[190:193], v[226:229], v[20:23]
	v_mfma_f32_16x16x32_bf16 v[16:19], v[198:201], v[226:229], v[16:19]
	v_mfma_f32_16x16x32_bf16 v[4:7], v[190:193], v[234:237], v[4:7]
	v_mfma_f32_16x16x32_bf16 v[0:3], v[198:201], v[234:237], v[0:3]
	s_nop 0
	s_barrier
	s_add_u32 s58, s58, 0x100
	s_addc_u32 s59, s59, 0
	s_add_u32 s24, s24, 0x100
	s_addc_u32 s25, s25, 0
	s_cmp_ge_i32 s60, s48
	s_mov_b32 s26, s60
	s_cbranch_scc0 .LBB0_1643

; #define PG8_WAIT_V(n) asm volatile("s_waitcnt vmcnt(" #n ")" ::: "memory")
; #define PG8_BAR __builtin_amdgcn_s_barrier()
; __device__ __forceinline__ unsigned xb_add(unsigned* p, unsigned v) { return __hip_atomic_fetch_add(p, v, __ATOMIC_RELAXED, __HIP_MEMORY_SCOPE_AGENT); }
; template <class Epi, class Sched, bool ALIGN_EPI = false, bool SP2 = false>
; __device__ __forceinline__ void gemm_phase(PG8_LAS unsigned char* lds, const Gemm g, const Sched& S, const Epi& E) {
;     ...
;     PG8_WAIT_V(0);
;     if constexpr (!ALIGN_EPI) { if (wr == 0) PG8_BAR; }
;     PG8_BAR;
; __device__ __forceinline__ void xcd_barrier(const XcdBarrier& b) {
;     asm volatile("s_waitcnt vmcnt(0)" ::: "memory");
;     __syncthreads();
;     if (b.tid == 0u) {
;         unsigned* bar = b.bar;
;         __builtin_amdgcn_s_waitcnt(0);
;         unsigned nloc = b.st[0], nx = b.st[1];
;         if (nloc == 0u) { xcd_barrier_complete(bar, b.x, nloc, nx); b.st[0] = nloc; b.st[1] = nx; }
;         const unsigned old = xb_add(&bar[XB_XSUB(b.x)], 1u);
.LBB0_1650:
	s_mov_b64 s[2:3], s[88:89]
	s_getreg_b32 s4, hwreg(HW_REG_XCC_ID, 0, 4)
	s_waitcnt vmcnt(0)
	s_setprio 0
	s_barrier
	s_mov_b64 s[0:1], exec
	v_readlane_b32 s6, v252, 2
	v_readlane_b32 s7, v252, 3
	s_and_b64 s[6:7], s[0:1], s[6:7]
	s_mov_b64 exec, s[6:7]
	s_cbranch_execz .LBB0_1702
	s_add_i32 s5, 0, 0x20160
	v_mov_b32_e32 v0, s5
	s_load_dwordx2 s[2:3], s[2:3], 0x100
	s_waitcnt vmcnt(0) expcnt(0) lgkmcnt(0)
	ds_read_b32 v2, v0
	s_add_i32 s5, 0, 0x20164
	v_mov_b32_e32 v0, s5
	ds_read_b32 v0, v0
	s_and_b32 s46, s4, 15
	s_waitcnt lgkmcnt(1)
	v_cmp_ne_u32_e32 vcc, 0, v2
	s_cbranch_vccnz .LBB0_1666
	s_add_u32 s4, s2, 0x17900200
	s_addc_u32 s5, s3, 0
	s_add_u32 s6, s2, 0x17900400
	s_addc_u32 s7, s3, 0
	s_add_u32 s8, s2, 0x17900500
	s_addc_u32 s9, s3, 0
	s_add_u32 s10, s2, 0x17900600
	s_addc_u32 s11, s3, 0
	s_add_u32 s12, s2, 0x17900700
	s_addc_u32 s13, s3, 0
	s_add_u32 s14, s2, 0x17900800
	s_addc_u32 s15, s3, 0
	s_add_u32 s16, s2, 0x17900900
	s_addc_u32 s17, s3, 0
	s_add_u32 s18, s2, 0x17900a00
	s_addc_u32 s19, s3, 0
	s_add_u32 s20, s2, 0x17900b00
	s_addc_u32 s21, s3, 0
	s_add_u32 s22, s2, 0x17900c00
	s_addc_u32 s23, s3, 0
	s_add_u32 s24, s2, 0x17900d00
	s_addc_u32 s25, s3, 0
	s_add_u32 s26, s2, 0x17900e00
	s_addc_u32 s27, s3, 0
	s_add_u32 s28, s2, 0x17900f00
	s_addc_u32 s29, s3, 0
	s_add_u32 s30, s2, 0x17901000
	s_addc_u32 s31, s3, 0
	s_add_u32 s34, s2, 0x17901100
	s_addc_u32 s35, s3, 0
	s_add_u32 s36, s2, 0x17901200
	s_addc_u32 s37, s3, 0
	s_mul_i32 s47, s91, s33
	s_add_u32 s38, s2, 0x17901300
	s_mul_i32 s47, s47, s90
	s_addc_u32 s39, s3, 0
	s_mov_b32 s48, 1
	v_mov_b32_e32 v16, 0
	s_branch .LBB0_1654

; #define EWA_REP for (int rep_ = 0; rep_ < 2; ++rep_)
; #define KA_DEF const __attribute__((address_space(4))) KArgs* ka_ = (const __attribute__((address_space(4))) KArgs*)__builtin_amdgcn_kernarg_segment_ptr(); asm volatile("" : "+s"(ka_));
; #define SSQ ((float*)WSP(WS_SSQ))
; __device__ __forceinline__ void xcd_barrier(const XcdBarrier& b) {
;     ...
;     __syncthreads();
; __global__ void __launch_bounds__(512, 2) mega_fwd(KArgs a) {
;     ...
;         if (l > 0) { { PH_VARS EWA_REP { CONV_LAYER(l); } } GSYNC(); }
;         { KA_DEF pg8::EpiSwiGLU E{RA, FF, SSQ}; run_gemm(TIDX, lds, XB, Wl + WO_13A, T_, 2 * FF, 1024, E); }
.LBB0_3142:
	s_or_b64 exec, exec, s[0:1]
	s_waitcnt lgkmcnt(0)
	s_barrier
	v_readfirstlane_b32 vcc_lo, v220
	s_nop 1
	s_bitcmp1_b32 vcc_lo, 8
	s_cbranch_scc0 .Lmy_prio_skip_4
	s_setprio 1
.Lmy_prio_skip_4:
	s_cmpk_lt_u32 s86, 0x80
	s_cbranch_scc1 .LBB0_3143
	v_writelane_b32 v254, 1, 40
	v_readlane_b32 s1, v252, 26
	s_nop 1
	s_branch .LBB0_1764

; #define PG8_STAGE(bufoff, gbase, voff) do { _Pragma("unroll") for (int _i = 0; _i < 2; ++_i) \
;         __builtin_amdgcn_global_load_lds((const unsigned*)((const char*)(gbase) + (voff)[_i]), (PG8_LAS unsigned*)(lds + (bufoff) + ldsw + _i * 8192), 16, 0, 0); } while (0)
; #define PG8_LDA(dst, b, h) do { _Pragma("unroll") for (int m = 0; m < 4; ++m) _Pragma("unroll") for (int k = 0; k < 2; ++k) dst[m][k] = *(const PG8_LAS bf16x8*)(lds + PG8_SA(b, h) + aoff + m * 2048 + k * 1024); } while (0)
; #define PG8_LDB(dst, b, h) do { _Pragma("unroll") for (int n = 0; n < 2; ++n) _Pragma("unroll") for (int k = 0; k < 2; ++k) dst[n][k] = *(const PG8_LAS bf16x8*)(lds + PG8_SB(b, h) + boff + n * 2048 + k * 1024); } while (0)
; #define PG8_MMA(ai, bj, At, Bt) do { __builtin_amdgcn_s_setprio(1); _Pragma("unroll") for (int m = 0; m < 4; ++m) _Pragma("unroll") for (int n = 0; n < 2; ++n) _Pragma("unroll") for (int k = 0; k < 2; ++k) \
;         acc[ai][bj][m][n] = __builtin_amdgcn_mfma_f32_16x16x32_bf16(Bt[n][k], At[m][k], acc[ai][bj][m][n], 0, 0, 0); __builtin_amdgcn_s_setprio(0); } while (0)
; #define PG8_WAIT_V(n) asm volatile("s_waitcnt vmcnt(" #n ")" ::: "memory")
; #define PG8_WAIT_L(n) asm volatile("s_waitcnt lgkmcnt(" #n ")" ::: "memory")
; #define PG8_BAR __builtin_amdgcn_s_barrier()
; #define PG8_SCHED __builtin_amdgcn_sched_barrier(0)
; template <class Epi, class Sched, bool ALIGN_EPI = false, bool SP2 = false>
; __device__ __forceinline__ void gemm_phase(PG8_LAS unsigned char* lds, const Gemm g, const Sched& S, const Epi& E) {
;     ...
;             PG8_LDB(B0, 0, 0); PG8_LDB(B1, 0, 1); PG8_SCHED; PG8_LDA(At, 0, 0); PG8_STAGE(PG8_SA(1, 1), a1 + hstep, voffA);
;             PG8_WAIT_V(8); PG8_WAIT_L(0); PG8_BAR; PG8_MMA(0, 0, At, B0); PG8_MMA(0, 1, At, B1); PG8_BAR; PG8_SCHED;
;             PG8_LDA(At, 0, 1); PG8_STAGE(PG8_SB(0, 0), b2, voffB); PG8_STAGE(PG8_SB(0, 1), b2 + hstep, voffB); PG8_STAGE(PG8_SA(0, 0), a2, voffA);
;             PG8_WAIT_V(8); PG8_WAIT_L(0); PG8_BAR; PG8_MMA(1, 0, At, B0); PG8_MMA(1, 1, At, B1); PG8_BAR; PG8_SCHED;
.LBB0_3165:
	s_add_i32 s61, s34, 2
	s_add_u32 s62, s30, 0x80
	s_addc_u32 s35, s31, 0
	s_add_i32 s64, 0, 0x10000
	s_cmp_eq_u32 s53, s34
	s_cselect_b32 s35, s1, s35
	s_cselect_b32 s34, s0, s62
	v_add_u32_e32 v148, s64, v151
	s_cselect_b32 s63, s29, s60
	s_cselect_b32 s62, s28, s59
	s_add_i32 s65, 0, 0x14000
	ds_read_b128 v[130:133], v148
	ds_read_b128 v[156:159], v148 offset:1024
	ds_read_b128 v[162:165], v148 offset:2048
	ds_read_b128 v[166:169], v148 offset:3072
	v_add_u32_e32 v148, s65, v151
	ds_read_b128 v[170:173], v148
	ds_read_b128 v[174:177], v148 offset:1024
	ds_read_b128 v[178:181], v148 offset:2048
	ds_read_b128 v[182:185], v148 offset:3072
	v_lshl_add_u64 v[148:149], s[30:31], 0, v[146:147]
	s_add_i32 m0, s46, 0xc000
	ds_read_b128 v[186:189], v161
	ds_read_b128 v[190:193], v161 offset:1024
	ds_read_b128 v[194:197], v161 offset:2048
	ds_read_b128 v[198:201], v161 offset:3072
	ds_read_b128 v[202:205], v161 offset:4096
	ds_read_b128 v[206:209], v161 offset:5120
	ds_read_b128 v[210:213], v161 offset:6144
	ds_read_b128 v[214:217], v161 offset:7168
	global_load_lds_dwordx4 v[148:149], off
	v_lshl_add_u64 v[148:149], s[30:31], 0, v[144:145]
	s_add_i32 m0, s46, 0xe000
	s_nop 0
	global_load_lds_dwordx4 v[148:149], off
	s_waitcnt vmcnt(8)
	s_waitcnt lgkmcnt(0)
	s_barrier
	s_nop 0
	s_waitcnt lgkmcnt(0)
	v_mfma_f32_16x16x32_bf16 v[122:125], v[130:133], v[186:189], v[122:125]
	v_mfma_f32_16x16x32_bf16 v[126:129], v[162:165], v[186:189], v[126:129]
	v_mfma_f32_16x16x32_bf16 v[110:113], v[130:133], v[194:197], v[110:113]
	v_mfma_f32_16x16x32_bf16 v[106:109], v[162:165], v[194:197], v[106:109]
	v_mfma_f32_16x16x32_bf16 v[94:97], v[130:133], v[202:205], v[94:97]
	v_mfma_f32_16x16x32_bf16 v[90:93], v[162:165], v[202:205], v[90:93]
	v_mfma_f32_16x16x32_bf16 v[78:81], v[130:133], v[210:213], v[78:81]
	v_mfma_f32_16x16x32_bf16 v[74:77], v[162:165], v[210:213], v[74:77]
	v_mfma_f32_16x16x32_bf16 v[122:125], v[156:159], v[190:193], v[122:125]
	v_mfma_f32_16x16x32_bf16 v[126:129], v[166:169], v[190:193], v[126:129]
	v_mfma_f32_16x16x32_bf16 v[110:113], v[156:159], v[198:201], v[110:113]
	v_mfma_f32_16x16x32_bf16 v[106:109], v[166:169], v[198:201], v[106:109]
	v_mfma_f32_16x16x32_bf16 v[94:97], v[156:159], v[206:209], v[94:97]
	v_mfma_f32_16x16x32_bf16 v[90:93], v[166:169], v[206:209], v[90:93]
	v_mfma_f32_16x16x32_bf16 v[78:81], v[156:159], v[214:217], v[78:81]
	v_mfma_f32_16x16x32_bf16 v[74:77], v[166:169], v[214:217], v[74:77]
	s_nop 0
	s_nop 0
	v_mfma_f32_16x16x32_bf16 v[118:121], v[170:173], v[186:189], v[118:121]
	v_mfma_f32_16x16x32_bf16 v[114:117], v[178:181], v[186:189], v[114:117]
	v_mfma_f32_16x16x32_bf16 v[102:105], v[170:173], v[194:197], v[102:105]
	v_mfma_f32_16x16x32_bf16 v[98:101], v[178:181], v[194:197], v[98:101]
	v_mfma_f32_16x16x32_bf16 v[86:89], v[170:173], v[202:205], v[86:89]
	v_mfma_f32_16x16x32_bf16 v[82:85], v[178:181], v[202:205], v[82:85]
	v_mfma_f32_16x16x32_bf16 v[70:73], v[170:173], v[210:213], v[70:73]
	v_mfma_f32_16x16x32_bf16 v[66:69], v[178:181], v[210:213], v[66:69]
	v_mfma_f32_16x16x32_bf16 v[118:121], v[174:177], v[190:193], v[118:121]
	v_mfma_f32_16x16x32_bf16 v[114:117], v[182:185], v[190:193], v[114:117]
	v_mfma_f32_16x16x32_bf16 v[102:105], v[174:177], v[198:201], v[102:105]
	v_mfma_f32_16x16x32_bf16 v[98:101], v[182:185], v[198:201], v[98:101]
	v_mfma_f32_16x16x32_bf16 v[86:89], v[174:177], v[206:209], v[86:89]
	v_mfma_f32_16x16x32_bf16 v[82:85], v[182:185], v[206:209], v[82:85]
	v_mfma_f32_16x16x32_bf16 v[70:73], v[174:177], v[214:217], v[70:73]
	v_mfma_f32_16x16x32_bf16 v[66:69], v[182:185], v[214:217], v[66:69]
	s_nop 0
	s_barrier
	s_add_i32 s64, s64, s41
	v_lshl_add_u64 v[148:149], s[62:63], 0, v[136:137]
	s_mov_b32 m0, s64
	ds_read_b128 v[186:189], v161 offset:16384
	ds_read_b128 v[190:193], v161 offset:17408
	ds_read_b128 v[194:197], v161 offset:18432
	ds_read_b128 v[198:201], v161 offset:19456
	ds_read_b128 v[202:205], v161 offset:20480
	ds_read_b128 v[206:209], v161 offset:21504
	ds_read_b128 v[210:213], v161 offset:22528
	ds_read_b128 v[214:217], v161 offset:23552
	global_load_lds_dwordx4 v[148:149], off
	s_add_i32 m0, s64, 0x2000
	v_lshl_add_u64 v[152:153], s[62:63], 0, v[140:141]
	s_add_u32 s62, s62, s16
	s_addc_u32 s63, s63, s17
	s_add_i32 s64, s65, s41
	global_load_lds_dwordx4 v[152:153], off
	v_lshl_add_u64 v[218:219], s[62:63], 0, v[136:137]
	s_mov_b32 m0, s64
	v_lshl_add_u64 v[242:243], s[62:63], 0, v[140:141]
	global_load_lds_dwordx4 v[218:219], off
	s_add_i32 m0, s64, 0x2000
	v_lshl_add_u64 v[244:245], s[34:35], 0, v[134:135]
	global_load_lds_dwordx4 v[242:243], off
	s_mov_b32 m0, s46
	v_lshl_add_u64 v[246:247], s[34:35], 0, v[138:139]
	global_load_lds_dwordx4 v[244:245], off
	s_mov_b32 m0, s47
	s_nop 0
	global_load_lds_dwordx4 v[246:247], off
	s_waitcnt vmcnt(8)
	s_waitcnt lgkmcnt(0)
	s_barrier
; #define PG8_STAGE(bufoff, gbase, voff) do { _Pragma("unroll") for (int _i = 0; _i < 2; ++_i) \
;         __builtin_amdgcn_global_load_lds((const unsigned*)((const char*)(gbase) + (voff)[_i]), (PG8_LAS unsigned*)(lds + (bufoff) + ldsw + _i * 8192), 16, 0, 0); } while (0)
; #define PG8_LDA(dst, b, h) do { _Pragma("unroll") for (int m = 0; m < 4; ++m) _Pragma("unroll") for (int k = 0; k < 2; ++k) dst[m][k] = *(const PG8_LAS bf16x8*)(lds + PG8_SA(b, h) + aoff + m * 2048 + k * 1024); } while (0)
; #define PG8_LDB(dst, b, h) do { _Pragma("unroll") for (int n = 0; n < 2; ++n) _Pragma("unroll") for (int k = 0; k < 2; ++k) dst[n][k] = *(const PG8_LAS bf16x8*)(lds + PG8_SB(b, h) + boff + n * 2048 + k * 1024); } while (0)
; #define PG8_MMA(ai, bj, At, Bt) do { __builtin_amdgcn_s_setprio(1); _Pragma("unroll") for (int m = 0; m < 4; ++m) _Pragma("unroll") for (int n = 0; n < 2; ++n) _Pragma("unroll") for (int k = 0; k < 2; ++k) \
;         acc[ai][bj][m][n] = __builtin_amdgcn_mfma_f32_16x16x32_bf16(Bt[n][k], At[m][k], acc[ai][bj][m][n], 0, 0, 0); __builtin_amdgcn_s_setprio(0); } while (0)
; #define PG8_WAIT_V(n) asm volatile("s_waitcnt vmcnt(" #n ")" ::: "memory")
; #define PG8_WAIT_L(n) asm volatile("s_waitcnt lgkmcnt(" #n ")" ::: "memory")
; #define PG8_BAR __builtin_amdgcn_s_barrier()
; #define PG8_SCHED __builtin_amdgcn_sched_barrier(0)
; template <class Epi, class Sched, bool ALIGN_EPI = false, bool SP2 = false>
; __device__ __forceinline__ void gemm_phase(PG8_LAS unsigned char* lds, const Gemm g, const Sched& S, const Epi& E) {
;     ...
;             PG8_WAIT_V(8); PG8_WAIT_L(0); PG8_BAR; PG8_MMA(1, 0, At, B0); PG8_MMA(1, 1, At, B1); PG8_BAR; PG8_SCHED;
;             PG8_LDB(B0, 1, 0); PG8_LDB(B1, 1, 1); PG8_SCHED; PG8_LDA(At, 1, 0); PG8_STAGE(PG8_SA(0, 1), a2 + hstep, voffA);
;             PG8_WAIT_V(8); PG8_WAIT_L(0); PG8_BAR; PG8_MMA(0, 0, At, B0); PG8_MMA(0, 1, At, B1); PG8_BAR; PG8_SCHED;
	s_nop 0
	s_waitcnt lgkmcnt(0)
	v_mfma_f32_16x16x32_bf16 v[62:65], v[130:133], v[186:189], v[62:65]
	v_mfma_f32_16x16x32_bf16 v[58:61], v[162:165], v[186:189], v[58:61]
	v_mfma_f32_16x16x32_bf16 v[46:49], v[130:133], v[194:197], v[46:49]
	v_mfma_f32_16x16x32_bf16 v[42:45], v[162:165], v[194:197], v[42:45]
	v_mfma_f32_16x16x32_bf16 v[30:33], v[130:133], v[202:205], v[30:33]
	v_mfma_f32_16x16x32_bf16 v[26:29], v[162:165], v[202:205], v[26:29]
	v_mfma_f32_16x16x32_bf16 v[14:17], v[130:133], v[210:213], v[14:17]
	v_mfma_f32_16x16x32_bf16 v[10:13], v[162:165], v[210:213], v[10:13]
	v_mfma_f32_16x16x32_bf16 v[62:65], v[156:159], v[190:193], v[62:65]
	v_mfma_f32_16x16x32_bf16 v[58:61], v[166:169], v[190:193], v[58:61]
	v_mfma_f32_16x16x32_bf16 v[46:49], v[156:159], v[198:201], v[46:49]
	v_mfma_f32_16x16x32_bf16 v[42:45], v[166:169], v[198:201], v[42:45]
	v_mfma_f32_16x16x32_bf16 v[30:33], v[156:159], v[206:209], v[30:33]
	v_mfma_f32_16x16x32_bf16 v[26:29], v[166:169], v[206:209], v[26:29]
	v_mfma_f32_16x16x32_bf16 v[14:17], v[156:159], v[214:217], v[14:17]
	v_mfma_f32_16x16x32_bf16 v[10:13], v[166:169], v[214:217], v[10:13]
	s_nop 0
	s_nop 0
	v_mfma_f32_16x16x32_bf16 v[54:57], v[170:173], v[186:189], v[54:57]
	v_mfma_f32_16x16x32_bf16 v[50:53], v[178:181], v[186:189], v[50:53]
	v_mfma_f32_16x16x32_bf16 v[38:41], v[170:173], v[194:197], v[38:41]
	v_mfma_f32_16x16x32_bf16 v[34:37], v[178:181], v[194:197], v[34:37]
	v_mfma_f32_16x16x32_bf16 v[22:25], v[170:173], v[202:205], v[22:25]
	v_mfma_f32_16x16x32_bf16 v[18:21], v[178:181], v[202:205], v[18:21]
	v_mfma_f32_16x16x32_bf16 v[6:9], v[170:173], v[210:213], v[6:9]
	v_mfma_f32_16x16x32_bf16 v[2:5], v[178:181], v[210:213], v[2:5]
	v_mfma_f32_16x16x32_bf16 v[54:57], v[174:177], v[190:193], v[54:57]
	v_mfma_f32_16x16x32_bf16 v[50:53], v[182:185], v[190:193], v[50:53]
	v_mfma_f32_16x16x32_bf16 v[38:41], v[174:177], v[198:201], v[38:41]
	v_mfma_f32_16x16x32_bf16 v[34:37], v[182:185], v[198:201], v[34:37]
	v_mfma_f32_16x16x32_bf16 v[22:25], v[174:177], v[206:209], v[22:25]
	v_mfma_f32_16x16x32_bf16 v[18:21], v[182:185], v[206:209], v[18:21]
	v_mfma_f32_16x16x32_bf16 v[6:9], v[174:177], v[214:217], v[6:9]
	v_mfma_f32_16x16x32_bf16 v[2:5], v[182:185], v[214:217], v[2:5]
	s_nop 0
	s_barrier
	s_add_i32 s62, 0, 0x18000
	v_add_u32_e32 v150, s62, v151
	s_add_i32 s63, 0, 0x1c000
	ds_read_b128 v[130:133], v150
	ds_read_b128 v[156:159], v150 offset:1024
	ds_read_b128 v[162:165], v150 offset:2048
	ds_read_b128 v[166:169], v150 offset:3072
	v_add_u32_e32 v150, s63, v151
	ds_read_b128 v[170:173], v150
	ds_read_b128 v[174:177], v150 offset:1024
	ds_read_b128 v[178:181], v150 offset:2048
	ds_read_b128 v[182:185], v150 offset:3072
	s_add_u32 s34, s34, s16
	s_addc_u32 s35, s35, s17
	s_mov_b32 m0, s48
	v_lshl_add_u64 v[248:249], s[34:35], 0, v[134:135]
	ds_read_b128 v[186:189], v161 offset:32768
	ds_read_b128 v[190:193], v161 offset:33792
	ds_read_b128 v[194:197], v161 offset:34816
	ds_read_b128 v[198:201], v161 offset:35840
	ds_read_b128 v[202:205], v161 offset:36864
	ds_read_b128 v[206:209], v161 offset:37888
	ds_read_b128 v[210:213], v161 offset:38912
	ds_read_b128 v[214:217], v161 offset:39936
	global_load_lds_dwordx4 v[248:249], off
	v_lshl_add_u64 v[248:249], s[34:35], 0, v[138:139]
	s_mov_b32 m0, s49
	s_nop 0
	global_load_lds_dwordx4 v[248:249], off
	s_waitcnt vmcnt(8)
	s_waitcnt lgkmcnt(0)
	s_barrier
	s_nop 0
	s_waitcnt lgkmcnt(0)
	v_mfma_f32_16x16x32_bf16 v[122:125], v[130:133], v[186:189], v[122:125]
	v_mfma_f32_16x16x32_bf16 v[126:129], v[162:165], v[186:189], v[126:129]
	v_mfma_f32_16x16x32_bf16 v[110:113], v[130:133], v[194:197], v[110:113]
	v_mfma_f32_16x16x32_bf16 v[106:109], v[162:165], v[194:197], v[106:109]
	v_mfma_f32_16x16x32_bf16 v[94:97], v[130:133], v[202:205], v[94:97]
	v_mfma_f32_16x16x32_bf16 v[90:93], v[162:165], v[202:205], v[90:93]
	v_mfma_f32_16x16x32_bf16 v[78:81], v[130:133], v[210:213], v[78:81]
	v_mfma_f32_16x16x32_bf16 v[74:77], v[162:165], v[210:213], v[74:77]
	v_mfma_f32_16x16x32_bf16 v[122:125], v[156:159], v[190:193], v[122:125]
	v_mfma_f32_16x16x32_bf16 v[126:129], v[166:169], v[190:193], v[126:129]
	v_mfma_f32_16x16x32_bf16 v[110:113], v[156:159], v[198:201], v[110:113]
	v_mfma_f32_16x16x32_bf16 v[106:109], v[166:169], v[198:201], v[106:109]
	v_mfma_f32_16x16x32_bf16 v[94:97], v[156:159], v[206:209], v[94:97]
	v_mfma_f32_16x16x32_bf16 v[90:93], v[166:169], v[206:209], v[90:93]
	v_mfma_f32_16x16x32_bf16 v[78:81], v[156:159], v[214:217], v[78:81]
	v_mfma_f32_16x16x32_bf16 v[74:77], v[166:169], v[214:217], v[74:77]
	s_nop 0
	s_nop 0
	v_mfma_f32_16x16x32_bf16 v[118:121], v[170:173], v[186:189], v[118:121]
	v_mfma_f32_16x16x32_bf16 v[114:117], v[178:181], v[186:189], v[114:117]
	v_mfma_f32_16x16x32_bf16 v[102:105], v[170:173], v[194:197], v[102:105]
	v_mfma_f32_16x16x32_bf16 v[98:101], v[178:181], v[194:197], v[98:101]
	v_mfma_f32_16x16x32_bf16 v[86:89], v[170:173], v[202:205], v[86:89]
	v_mfma_f32_16x16x32_bf16 v[82:85], v[178:181], v[202:205], v[82:85]
	v_mfma_f32_16x16x32_bf16 v[70:73], v[170:173], v[210:213], v[70:73]
	v_mfma_f32_16x16x32_bf16 v[66:69], v[178:181], v[210:213], v[66:69]
	v_mfma_f32_16x16x32_bf16 v[118:121], v[174:177], v[190:193], v[118:121]
	v_mfma_f32_16x16x32_bf16 v[114:117], v[182:185], v[190:193], v[114:117]
	v_mfma_f32_16x16x32_bf16 v[102:105], v[174:177], v[198:201], v[102:105]
	v_mfma_f32_16x16x32_bf16 v[98:101], v[182:185], v[198:201], v[98:101]
	v_mfma_f32_16x16x32_bf16 v[86:89], v[174:177], v[206:209], v[86:89]
	v_mfma_f32_16x16x32_bf16 v[82:85], v[182:185], v[206:209], v[82:85]
	v_mfma_f32_16x16x32_bf16 v[70:73], v[174:177], v[214:217], v[70:73]
	v_mfma_f32_16x16x32_bf16 v[66:69], v[182:185], v[214:217], v[66:69]
	s_nop 0
	s_barrier
; #define PG8_STAGE(bufoff, gbase, voff) do { _Pragma("unroll") for (int _i = 0; _i < 2; ++_i) \
;         __builtin_amdgcn_global_load_lds((const unsigned*)((const char*)(gbase) + (voff)[_i]), (PG8_LAS unsigned*)(lds + (bufoff) + ldsw + _i * 8192), 16, 0, 0); } while (0)
; #define PG8_LDA(dst, b, h) do { _Pragma("unroll") for (int m = 0; m < 4; ++m) _Pragma("unroll") for (int k = 0; k < 2; ++k) dst[m][k] = *(const PG8_LAS bf16x8*)(lds + PG8_SA(b, h) + aoff + m * 2048 + k * 1024); } while (0)
; #define PG8_MMA(ai, bj, At, Bt) do { __builtin_amdgcn_s_setprio(1); _Pragma("unroll") for (int m = 0; m < 4; ++m) _Pragma("unroll") for (int n = 0; n < 2; ++n) _Pragma("unroll") for (int k = 0; k < 2; ++k) \
;         acc[ai][bj][m][n] = __builtin_amdgcn_mfma_f32_16x16x32_bf16(Bt[n][k], At[m][k], acc[ai][bj][m][n], 0, 0, 0); __builtin_amdgcn_s_setprio(0); } while (0)
; #define PG8_WAIT_V(n) asm volatile("s_waitcnt vmcnt(" #n ")" ::: "memory")
; #define PG8_WAIT_L(n) asm volatile("s_waitcnt lgkmcnt(" #n ")" ::: "memory")
; #define PG8_BAR __builtin_amdgcn_s_barrier()
; #define PG8_SCHED __builtin_amdgcn_sched_barrier(0)
; template <class Epi, class Sched, bool ALIGN_EPI = false, bool SP2 = false>
; __device__ __forceinline__ void gemm_phase(PG8_LAS unsigned char* lds, const Gemm g, const Sched& S, const Epi& E) {
;     ...
;         for (int t = 0; t < nt; t += 2) {
;             const bool last = (t == nt - 2);
;             const char* a1 = cA + (size_t)(t + 1) * kstep;
;             const char* a2 = last ? nA : cA + (size_t)(t + 2) * kstep; const char* b2 = last ? nB : cB + (size_t)(t + 2) * kstep;
;             const char* a3 = a2 + kstep; const char* b3 = b2 + kstep;
;     ...
;             PG8_LDA(At, 1, 1); PG8_STAGE(PG8_SB(1, 0), b3, voffB); PG8_STAGE(PG8_SB(1, 1), b3 + hstep, voffB); PG8_STAGE(PG8_SA(1, 0), a3, voffA);
;             PG8_WAIT_V(8); PG8_WAIT_L(0); PG8_BAR; PG8_MMA(1, 0, At, B0); PG8_MMA(1, 1, At, B1); PG8_BAR; PG8_SCHED;
	s_add_i32 s34, s62, s41
	v_lshl_add_u64 v[148:149], v[148:149], 0, s[92:93]
	s_mov_b32 m0, s34
	ds_read_b128 v[186:189], v161 offset:49152
	ds_read_b128 v[190:193], v161 offset:50176
	ds_read_b128 v[194:197], v161 offset:51200
	ds_read_b128 v[198:201], v161 offset:52224
	ds_read_b128 v[202:205], v161 offset:53248
	ds_read_b128 v[206:209], v161 offset:54272
	ds_read_b128 v[210:213], v161 offset:55296
	ds_read_b128 v[214:217], v161 offset:56320
	global_load_lds_dwordx4 v[148:149], off
	v_lshl_add_u64 v[148:149], v[152:153], 0, s[92:93]
	s_add_i32 m0, s34, 0x2000
	s_add_i32 s34, s63, s41
	global_load_lds_dwordx4 v[148:149], off
	v_lshl_add_u64 v[148:149], v[218:219], 0, s[92:93]
	s_mov_b32 m0, s34
	s_nop 0
	global_load_lds_dwordx4 v[148:149], off
	v_lshl_add_u64 v[148:149], v[242:243], 0, s[92:93]
	s_add_i32 m0, s34, 0x2000
	s_nop 0
	global_load_lds_dwordx4 v[148:149], off
	v_lshl_add_u64 v[148:149], v[244:245], 0, s[92:93]
	s_mov_b32 m0, s50
	s_nop 0
	global_load_lds_dwordx4 v[148:149], off
	v_lshl_add_u64 v[148:149], v[246:247], 0, s[92:93]
	s_mov_b32 m0, s51
	s_nop 0
	global_load_lds_dwordx4 v[148:149], off
	s_waitcnt vmcnt(8)
	s_waitcnt lgkmcnt(0)
	s_barrier
	s_nop 0
	s_waitcnt lgkmcnt(0)
	v_mfma_f32_16x16x32_bf16 v[62:65], v[130:133], v[186:189], v[62:65]
	v_mfma_f32_16x16x32_bf16 v[58:61], v[162:165], v[186:189], v[58:61]
	v_mfma_f32_16x16x32_bf16 v[46:49], v[130:133], v[194:197], v[46:49]
	v_mfma_f32_16x16x32_bf16 v[42:45], v[162:165], v[194:197], v[42:45]
	v_mfma_f32_16x16x32_bf16 v[30:33], v[130:133], v[202:205], v[30:33]
	v_mfma_f32_16x16x32_bf16 v[26:29], v[162:165], v[202:205], v[26:29]
	v_mfma_f32_16x16x32_bf16 v[14:17], v[130:133], v[210:213], v[14:17]
	v_mfma_f32_16x16x32_bf16 v[10:13], v[162:165], v[210:213], v[10:13]
	v_mfma_f32_16x16x32_bf16 v[62:65], v[156:159], v[190:193], v[62:65]
	v_mfma_f32_16x16x32_bf16 v[58:61], v[166:169], v[190:193], v[58:61]
	v_mfma_f32_16x16x32_bf16 v[46:49], v[156:159], v[198:201], v[46:49]
	v_mfma_f32_16x16x32_bf16 v[42:45], v[166:169], v[198:201], v[42:45]
	v_mfma_f32_16x16x32_bf16 v[30:33], v[156:159], v[206:209], v[30:33]
	v_mfma_f32_16x16x32_bf16 v[26:29], v[166:169], v[206:209], v[26:29]
	v_mfma_f32_16x16x32_bf16 v[14:17], v[156:159], v[214:217], v[14:17]
	v_mfma_f32_16x16x32_bf16 v[10:13], v[166:169], v[214:217], v[10:13]
	s_nop 0
	s_nop 0
	v_mfma_f32_16x16x32_bf16 v[54:57], v[170:173], v[186:189], v[54:57]
	v_mfma_f32_16x16x32_bf16 v[50:53], v[178:181], v[186:189], v[50:53]
	v_mfma_f32_16x16x32_bf16 v[38:41], v[170:173], v[194:197], v[38:41]
	v_mfma_f32_16x16x32_bf16 v[34:37], v[178:181], v[194:197], v[34:37]
	v_mfma_f32_16x16x32_bf16 v[22:25], v[170:173], v[202:205], v[22:25]
	v_mfma_f32_16x16x32_bf16 v[18:21], v[178:181], v[202:205], v[18:21]
	v_mfma_f32_16x16x32_bf16 v[6:9], v[170:173], v[210:213], v[6:9]
	v_mfma_f32_16x16x32_bf16 v[2:5], v[178:181], v[210:213], v[2:5]
	v_mfma_f32_16x16x32_bf16 v[54:57], v[174:177], v[190:193], v[54:57]
	v_mfma_f32_16x16x32_bf16 v[50:53], v[182:185], v[190:193], v[50:53]
	v_mfma_f32_16x16x32_bf16 v[38:41], v[174:177], v[198:201], v[38:41]
	v_mfma_f32_16x16x32_bf16 v[34:37], v[182:185], v[198:201], v[34:37]
	v_mfma_f32_16x16x32_bf16 v[22:25], v[174:177], v[206:209], v[22:25]
	v_mfma_f32_16x16x32_bf16 v[18:21], v[182:185], v[206:209], v[18:21]
	v_mfma_f32_16x16x32_bf16 v[6:9], v[174:177], v[214:217], v[6:9]
	v_mfma_f32_16x16x32_bf16 v[2:5], v[182:185], v[214:217], v[2:5]
	s_nop 0
	s_barrier
	s_add_u32 s59, s59, 0x100
	s_addc_u32 s60, s60, 0
	s_add_u32 s30, s30, 0x100
	s_addc_u32 s31, s31, 0
	s_cmp_ge_i32 s61, s52
	s_mov_b32 s34, s61
	s_cbranch_scc0 .LBB0_3165

; #define PG8_WAIT_V(n) asm volatile("s_waitcnt vmcnt(" #n ")" ::: "memory")
; #define PG8_BAR __builtin_amdgcn_s_barrier()
; __device__ __forceinline__ unsigned xb_add(unsigned* p, unsigned v) { return __hip_atomic_fetch_add(p, v, __ATOMIC_RELAXED, __HIP_MEMORY_SCOPE_AGENT); }
; template <class Epi, class Sched, bool ALIGN_EPI = false, bool SP2 = false>
; __device__ __forceinline__ void gemm_phase(PG8_LAS unsigned char* lds, const Gemm g, const Sched& S, const Epi& E) {
;     ...
;     PG8_WAIT_V(0);
;     if constexpr (!ALIGN_EPI) { if (wr == 0) PG8_BAR; }
;     PG8_BAR;
; __device__ __forceinline__ void xcd_barrier(const XcdBarrier& b) {
;     asm volatile("s_waitcnt vmcnt(0)" ::: "memory");
;     __syncthreads();
;     if (b.tid == 0u) {
;         unsigned* bar = b.bar;
;         __builtin_amdgcn_s_waitcnt(0);
;         unsigned nloc = b.st[0], nx = b.st[1];
;         if (nloc == 0u) { xcd_barrier_complete(bar, b.x, nloc, nx); b.st[0] = nloc; b.st[1] = nx; }
;         const unsigned old = xb_add(&bar[XB_XSUB(b.x)], 1u);
.LBB0_3172:
	s_mov_b64 s[4:5], s[88:89]
	s_getreg_b32 s8, hwreg(HW_REG_XCC_ID, 0, 4)
	s_waitcnt vmcnt(0)
	s_setprio 0
	s_barrier
	s_mov_b64 s[0:1], exec
	v_readlane_b32 s10, v252, 2
	v_readlane_b32 s11, v252, 3
	s_and_b64 s[10:11], s[0:1], s[10:11]
	s_mov_b64 exec, s[10:11]
	s_cbranch_execz .LBB0_3224
	v_readlane_b32 s9, v252, 13
	s_load_dwordx2 s[4:5], s[4:5], 0x100
	s_waitcnt vmcnt(0) expcnt(0) lgkmcnt(0)
	v_mov_b32_e32 v1, s9
	ds_read_b32 v3, v1
	v_readlane_b32 s9, v252, 14
	s_and_b32 s52, s8, 15
	s_waitcnt lgkmcnt(0)
	v_cmp_ne_u32_e32 vcc, 0, v3
	v_mov_b32_e32 v1, s9
	ds_read_b32 v2, v1
	s_cbranch_vccnz .LBB0_3188
	s_add_u32 s8, s4, 0x17900200
	s_addc_u32 s9, s5, 0
	s_add_u32 s10, s4, 0x17900400
	s_addc_u32 s11, s5, 0
	s_add_u32 s14, s4, 0x17900500
	s_addc_u32 s15, s5, 0
	s_add_u32 s16, s4, 0x17900600
	s_addc_u32 s17, s5, 0
	s_add_u32 s18, s4, 0x17900700
	s_addc_u32 s19, s5, 0
	s_add_u32 s20, s4, 0x17900800
	s_addc_u32 s21, s5, 0
	s_add_u32 s22, s4, 0x17900900
	s_addc_u32 s23, s5, 0
	s_add_u32 s24, s4, 0x17900a00
	s_addc_u32 s25, s5, 0
	s_add_u32 s26, s4, 0x17900b00
	s_addc_u32 s27, s5, 0
	s_add_u32 s28, s4, 0x17900c00
	s_addc_u32 s29, s5, 0
	s_add_u32 s30, s4, 0x17900d00
	s_addc_u32 s31, s5, 0
	s_add_u32 s34, s4, 0x17900e00
	s_addc_u32 s35, s5, 0
	s_add_u32 s36, s4, 0x17900f00
	s_addc_u32 s37, s5, 0
	s_add_u32 s38, s4, 0x17901000
	s_addc_u32 s39, s5, 0
	s_add_u32 s40, s4, 0x17901100
	s_addc_u32 s41, s5, 0
	s_add_u32 s42, s4, 0x17901200
	s_addc_u32 s43, s5, 0
	s_add_u32 s44, s4, 0x17901300
	s_addc_u32 s45, s5, 0
	s_mov_b32 s53, 1
	s_branch .LBB0_3176

; #define KA_DEF const __attribute__((address_space(4))) KArgs* ka_ = (const __attribute__((address_space(4))) KArgs*)__builtin_amdgcn_kernarg_segment_ptr(); asm volatile("" : "+s"(ka_));
; #define x_in INF(0)
; #define SSQ ((float*)WSP(WS_SSQ))
;     __host__ __device__ bool next(int i, Unit& u) const {
;         const long L = (long)i * G + c; if (L >= nwg) return false;
;         int wgid = (int)L; { const int q = nwg / NXCD, r = nwg % NXCD, xcd = wgid % NXCD, off = wgid / NXCD; wgid = (xcd < r ? xcd * (q + 1) : r * (q + 1) + (xcd - r) * q) + off; }
;         const int nig = WGM * nN, gid = wgid / nig, fm = gid * WGM, gsz = (nM - fm) < WGM ? (nM - fm) : WGM;
;         u.pm = fm + ((wgid % nig) % gsz); u.pn = (wgid % nig) / gsz; return true;
; __global__ void __launch_bounds__(512, 2) mega_fwd(KArgs a) {
;     ...
;         { KA_DEF pg8::EpiResid E{(l == 0) ? x_in : (const float*)X, X, XB, SSQ, 0.5f}; run_gemm(TIDX, lds, RA, Wl + WO_2A, T_, 1024, FF, E); }
.Lmy_prio_skip_5:
	s_load_dwordx4 s[8:11], s[0:1], 0xf8
	s_and_b64 s[4:5], exec, s[6:7]
	s_cselect_b32 s4, 0, 0xf8
	s_add_u32 s0, s0, s4
	s_addc_u32 s1, s1, 0
	s_waitcnt lgkmcnt(0)
	s_add_u32 s16, s10, 0x8c00000
	s_addc_u32 s17, s11, 0
	s_load_dwordx2 s[14:15], s[0:1], 0x0
	s_add_u32 s18, s10, 0xb00000
	s_movk_i32 s1, 0x400
	s_movk_i32 s0, 0xb00
	s_movk_i32 s4, 0x4000
	s_addc_u32 s19, s11, 0
	s_ashr_i32 s5, s4, 31
	s_lshr_b32 s5, s5, 24
	s_add_i32 s4, s4, s5
	s_ashr_i32 s42, s4, 8
	s_ashr_i32 s4, s1, 31
	s_lshr_b32 s4, s4, 24
	s_add_i32 s1, s1, s4
	s_ashr_i32 s36, s1, 8
	s_mul_i32 s20, s36, s42
	v_mov_b32_e32 v14, v220
	s_cmp_lt_i32 s86, s20
	s_cselect_b64 s[4:5], -1, 0
	s_cmp_ge_i32 s86, s20
	v_readfirstlane_b32 s21, v14
	s_cbranch_scc1 .LBB0_3230
	s_ashr_i32 s1, s20, 31
	s_lshr_b32 s1, s1, 29
	s_add_i32 s1, s20, s1
	s_ashr_i32 s23, s1, 3
	s_and_b32 s1, s1, -8
	s_sub_i32 s24, s20, s1
	s_add_i32 s22, s23, 1
	v_readlane_b32 s1, v252, 5
	s_cmp_ge_i32 s1, s24
	s_mov_b64 s[6:7], -1
	s_cbranch_scc0 .LBB0_3227
	v_readlane_b32 s6, v252, 5
	s_sub_i32 s6, s6, s24
	s_mul_i32 s1, s22, s24
	s_mul_i32 s6, s6, s23
	s_add_i32 s1, s6, s1
	s_mov_b64 s[6:7], 0

; #define PG8_STAGE(bufoff, gbase, voff) do { _Pragma("unroll") for (int _i = 0; _i < 2; ++_i) \
;         __builtin_amdgcn_global_load_lds((const unsigned*)((const char*)(gbase) + (voff)[_i]), (PG8_LAS unsigned*)(lds + (bufoff) + ldsw + _i * 8192), 16, 0, 0); } while (0)
; #define PG8_LDA(dst, b, h) do { _Pragma("unroll") for (int m = 0; m < 4; ++m) _Pragma("unroll") for (int k = 0; k < 2; ++k) dst[m][k] = *(const PG8_LAS bf16x8*)(lds + PG8_SA(b, h) + aoff + m * 2048 + k * 1024); } while (0)
; #define PG8_LDB(dst, b, h) do { _Pragma("unroll") for (int n = 0; n < 2; ++n) _Pragma("unroll") for (int k = 0; k < 2; ++k) dst[n][k] = *(const PG8_LAS bf16x8*)(lds + PG8_SB(b, h) + boff + n * 2048 + k * 1024); } while (0)
; #define PG8_MMA(ai, bj, At, Bt) do { __builtin_amdgcn_s_setprio(1); _Pragma("unroll") for (int m = 0; m < 4; ++m) _Pragma("unroll") for (int n = 0; n < 2; ++n) _Pragma("unroll") for (int k = 0; k < 2; ++k) \
;         acc[ai][bj][m][n] = __builtin_amdgcn_mfma_f32_16x16x32_bf16(Bt[n][k], At[m][k], acc[ai][bj][m][n], 0, 0, 0); __builtin_amdgcn_s_setprio(0); } while (0)
; #define PG8_WAIT_V(n) asm volatile("s_waitcnt vmcnt(" #n ")" ::: "memory")
; #define PG8_WAIT_L(n) asm volatile("s_waitcnt lgkmcnt(" #n ")" ::: "memory")
; #define PG8_BAR __builtin_amdgcn_s_barrier()
; #define PG8_SCHED __builtin_amdgcn_sched_barrier(0)
; template <class Epi, class Sched, bool ALIGN_EPI = false, bool SP2 = false>
; __device__ __forceinline__ void gemm_phase(PG8_LAS unsigned char* lds, const Gemm g, const Sched& S, const Epi& E) {
;     ...
;             PG8_LDB(B0, 0, 0); PG8_LDB(B1, 0, 1); PG8_SCHED; PG8_LDA(At, 0, 0); PG8_STAGE(PG8_SA(1, 1), a1 + hstep, voffA);
;             PG8_WAIT_V(8); PG8_WAIT_L(0); PG8_BAR; PG8_MMA(0, 0, At, B0); PG8_MMA(0, 1, At, B1); PG8_BAR; PG8_SCHED;
;             PG8_LDA(At, 0, 1); PG8_STAGE(PG8_SB(0, 0), b2, voffB); PG8_STAGE(PG8_SB(0, 1), b2 + hstep, voffB); PG8_STAGE(PG8_SA(0, 0), a2, voffA);
;             PG8_WAIT_V(8); PG8_WAIT_L(0); PG8_BAR; PG8_MMA(1, 0, At, B0); PG8_MMA(1, 1, At, B1); PG8_BAR; PG8_SCHED;
.LBB0_3248:
	s_add_i32 s67, s40, 2
	s_add_u32 s68, s38, 0x80
	s_addc_u32 s41, s39, 0
	s_add_i32 s70, 0, 0x10000
	s_cmp_eq_u32 s52, s40
	s_cselect_b32 s41, s1, s41
	s_cselect_b32 s40, s0, s68
	s_cselect_b32 s69, s37, s66
	s_cselect_b32 s68, s36, s65
	s_add_i32 s71, 0, 0x14000
	v_add_u32_e32 v154, s70, v242
	v_add_u32_e32 v170, s71, v242
	ds_read_b128 v[142:145], v154
	ds_read_b128 v[146:149], v154 offset:1024
	ds_read_b128 v[150:153], v154 offset:2048
	ds_read_b128 v[154:157], v154 offset:3072
	ds_read_b128 v[158:161], v170
	ds_read_b128 v[162:165], v170 offset:1024
	ds_read_b128 v[166:169], v170 offset:2048
	ds_read_b128 v[170:173], v170 offset:3072
	v_lshl_add_u64 v[206:207], s[38:39], 0, v[140:141]
	s_add_i32 m0, s44, 0xc000
	ds_read_b128 v[174:177], v244
	ds_read_b128 v[178:181], v244 offset:1024
	ds_read_b128 v[182:185], v244 offset:2048
	ds_read_b128 v[186:189], v244 offset:3072
	ds_read_b128 v[190:193], v244 offset:4096
	ds_read_b128 v[194:197], v244 offset:5120
	ds_read_b128 v[198:201], v244 offset:6144
	ds_read_b128 v[202:205], v244 offset:7168
	global_load_lds_dwordx4 v[206:207], off
	v_lshl_add_u64 v[206:207], s[38:39], 0, v[138:139]
	s_add_i32 m0, s44, 0xe000
	s_nop 0
	global_load_lds_dwordx4 v[206:207], off
	s_waitcnt vmcnt(8)
	s_waitcnt lgkmcnt(0)
	s_barrier
	s_nop 0
	s_waitcnt lgkmcnt(0)
	v_mfma_f32_16x16x32_bf16 v[126:129], v[142:145], v[174:177], v[126:129]
	v_mfma_f32_16x16x32_bf16 v[122:125], v[150:153], v[174:177], v[122:125]
	v_mfma_f32_16x16x32_bf16 v[118:121], v[142:145], v[182:185], v[118:121]
	v_mfma_f32_16x16x32_bf16 v[114:117], v[150:153], v[182:185], v[114:117]
	v_mfma_f32_16x16x32_bf16 v[106:109], v[142:145], v[190:193], v[106:109]
	v_mfma_f32_16x16x32_bf16 v[98:101], v[150:153], v[190:193], v[98:101]
	v_mfma_f32_16x16x32_bf16 v[90:93], v[142:145], v[198:201], v[90:93]
	v_mfma_f32_16x16x32_bf16 v[82:85], v[150:153], v[198:201], v[82:85]
	v_mfma_f32_16x16x32_bf16 v[126:129], v[146:149], v[178:181], v[126:129]
	v_mfma_f32_16x16x32_bf16 v[122:125], v[154:157], v[178:181], v[122:125]
	v_mfma_f32_16x16x32_bf16 v[118:121], v[146:149], v[186:189], v[118:121]
	v_mfma_f32_16x16x32_bf16 v[114:117], v[154:157], v[186:189], v[114:117]
	v_mfma_f32_16x16x32_bf16 v[106:109], v[146:149], v[194:197], v[106:109]
	v_mfma_f32_16x16x32_bf16 v[98:101], v[154:157], v[194:197], v[98:101]
	v_mfma_f32_16x16x32_bf16 v[90:93], v[146:149], v[202:205], v[90:93]
	v_mfma_f32_16x16x32_bf16 v[82:85], v[154:157], v[202:205], v[82:85]
	s_nop 0
	s_nop 0
	v_mfma_f32_16x16x32_bf16 v[110:113], v[158:161], v[174:177], v[110:113]
	v_mfma_f32_16x16x32_bf16 v[102:105], v[166:169], v[174:177], v[102:105]
	v_mfma_f32_16x16x32_bf16 v[94:97], v[158:161], v[182:185], v[94:97]
	v_mfma_f32_16x16x32_bf16 v[86:89], v[166:169], v[182:185], v[86:89]
	v_mfma_f32_16x16x32_bf16 v[78:81], v[158:161], v[190:193], v[78:81]
	v_mfma_f32_16x16x32_bf16 v[74:77], v[166:169], v[190:193], v[74:77]
	v_mfma_f32_16x16x32_bf16 v[70:73], v[158:161], v[198:201], v[70:73]
	v_mfma_f32_16x16x32_bf16 v[66:69], v[166:169], v[198:201], v[66:69]
	v_mfma_f32_16x16x32_bf16 v[110:113], v[162:165], v[178:181], v[110:113]
	v_mfma_f32_16x16x32_bf16 v[102:105], v[170:173], v[178:181], v[102:105]
	v_mfma_f32_16x16x32_bf16 v[94:97], v[162:165], v[186:189], v[94:97]
	v_mfma_f32_16x16x32_bf16 v[86:89], v[170:173], v[186:189], v[86:89]
	v_mfma_f32_16x16x32_bf16 v[78:81], v[162:165], v[194:197], v[78:81]
	v_mfma_f32_16x16x32_bf16 v[74:77], v[170:173], v[194:197], v[74:77]
	v_mfma_f32_16x16x32_bf16 v[70:73], v[162:165], v[202:205], v[70:73]
	v_mfma_f32_16x16x32_bf16 v[66:69], v[170:173], v[202:205], v[66:69]
	s_nop 0
	s_barrier
	s_add_i32 s70, s70, s43
	v_lshl_add_u64 v[206:207], s[68:69], 0, v[132:133]
	s_mov_b32 m0, s70
	ds_read_b128 v[174:177], v244 offset:16384
	ds_read_b128 v[178:181], v244 offset:17408
	ds_read_b128 v[182:185], v244 offset:18432
	ds_read_b128 v[186:189], v244 offset:19456
	ds_read_b128 v[190:193], v244 offset:20480
	ds_read_b128 v[194:197], v244 offset:21504
	ds_read_b128 v[198:201], v244 offset:22528
	ds_read_b128 v[202:205], v244 offset:23552
	global_load_lds_dwordx4 v[206:207], off
	s_add_i32 m0, s70, 0x2000
	v_lshl_add_u64 v[208:209], s[68:69], 0, v[136:137]
	s_add_u32 s68, s68, s22
	s_addc_u32 s69, s69, s23
	s_add_i32 s70, s71, s43
	global_load_lds_dwordx4 v[208:209], off
	v_lshl_add_u64 v[210:211], s[68:69], 0, v[132:133]
	s_mov_b32 m0, s70
	v_lshl_add_u64 v[212:213], s[68:69], 0, v[136:137]
	global_load_lds_dwordx4 v[210:211], off
	s_add_i32 m0, s70, 0x2000
	v_lshl_add_u64 v[214:215], s[40:41], 0, v[130:131]
	global_load_lds_dwordx4 v[212:213], off
	s_mov_b32 m0, s44
	v_lshl_add_u64 v[216:217], s[40:41], 0, v[134:135]
	global_load_lds_dwordx4 v[214:215], off
	s_mov_b32 m0, s45
	s_nop 0
	global_load_lds_dwordx4 v[216:217], off
	s_waitcnt vmcnt(8)
	s_waitcnt lgkmcnt(0)
	s_barrier
; #define PG8_STAGE(bufoff, gbase, voff) do { _Pragma("unroll") for (int _i = 0; _i < 2; ++_i) \
;         __builtin_amdgcn_global_load_lds((const unsigned*)((const char*)(gbase) + (voff)[_i]), (PG8_LAS unsigned*)(lds + (bufoff) + ldsw + _i * 8192), 16, 0, 0); } while (0)
; #define PG8_LDA(dst, b, h) do { _Pragma("unroll") for (int m = 0; m < 4; ++m) _Pragma("unroll") for (int k = 0; k < 2; ++k) dst[m][k] = *(const PG8_LAS bf16x8*)(lds + PG8_SA(b, h) + aoff + m * 2048 + k * 1024); } while (0)
; #define PG8_LDB(dst, b, h) do { _Pragma("unroll") for (int n = 0; n < 2; ++n) _Pragma("unroll") for (int k = 0; k < 2; ++k) dst[n][k] = *(const PG8_LAS bf16x8*)(lds + PG8_SB(b, h) + boff + n * 2048 + k * 1024); } while (0)
; #define PG8_MMA(ai, bj, At, Bt) do { __builtin_amdgcn_s_setprio(1); _Pragma("unroll") for (int m = 0; m < 4; ++m) _Pragma("unroll") for (int n = 0; n < 2; ++n) _Pragma("unroll") for (int k = 0; k < 2; ++k) \
;         acc[ai][bj][m][n] = __builtin_amdgcn_mfma_f32_16x16x32_bf16(Bt[n][k], At[m][k], acc[ai][bj][m][n], 0, 0, 0); __builtin_amdgcn_s_setprio(0); } while (0)
; #define PG8_WAIT_V(n) asm volatile("s_waitcnt vmcnt(" #n ")" ::: "memory")
; #define PG8_WAIT_L(n) asm volatile("s_waitcnt lgkmcnt(" #n ")" ::: "memory")
; #define PG8_BAR __builtin_amdgcn_s_barrier()
; #define PG8_SCHED __builtin_amdgcn_sched_barrier(0)
; template <class Epi, class Sched, bool ALIGN_EPI = false, bool SP2 = false>
; __device__ __forceinline__ void gemm_phase(PG8_LAS unsigned char* lds, const Gemm g, const Sched& S, const Epi& E) {
;     ...
;             PG8_WAIT_V(8); PG8_WAIT_L(0); PG8_BAR; PG8_MMA(1, 0, At, B0); PG8_MMA(1, 1, At, B1); PG8_BAR; PG8_SCHED;
;             PG8_LDB(B0, 1, 0); PG8_LDB(B1, 1, 1); PG8_SCHED; PG8_LDA(At, 1, 0); PG8_STAGE(PG8_SA(0, 1), a2 + hstep, voffA);
;             PG8_WAIT_V(8); PG8_WAIT_L(0); PG8_BAR; PG8_MMA(0, 0, At, B0); PG8_MMA(0, 1, At, B1); PG8_BAR; PG8_SCHED;
	s_nop 0
	s_waitcnt lgkmcnt(0)
	v_mfma_f32_16x16x32_bf16 v[62:65], v[142:145], v[174:177], v[62:65]
	v_mfma_f32_16x16x32_bf16 v[58:61], v[150:153], v[174:177], v[58:61]
	v_mfma_f32_16x16x32_bf16 v[54:57], v[142:145], v[182:185], v[54:57]
	v_mfma_f32_16x16x32_bf16 v[50:53], v[150:153], v[182:185], v[50:53]
	v_mfma_f32_16x16x32_bf16 v[42:45], v[142:145], v[190:193], v[42:45]
	v_mfma_f32_16x16x32_bf16 v[34:37], v[150:153], v[190:193], v[34:37]
	v_mfma_f32_16x16x32_bf16 v[26:29], v[142:145], v[198:201], v[26:29]
	v_mfma_f32_16x16x32_bf16 v[18:21], v[150:153], v[198:201], v[18:21]
	v_mfma_f32_16x16x32_bf16 v[62:65], v[146:149], v[178:181], v[62:65]
	v_mfma_f32_16x16x32_bf16 v[58:61], v[154:157], v[178:181], v[58:61]
	v_mfma_f32_16x16x32_bf16 v[54:57], v[146:149], v[186:189], v[54:57]
	v_mfma_f32_16x16x32_bf16 v[50:53], v[154:157], v[186:189], v[50:53]
	v_mfma_f32_16x16x32_bf16 v[42:45], v[146:149], v[194:197], v[42:45]
	v_mfma_f32_16x16x32_bf16 v[34:37], v[154:157], v[194:197], v[34:37]
	v_mfma_f32_16x16x32_bf16 v[26:29], v[146:149], v[202:205], v[26:29]
	v_mfma_f32_16x16x32_bf16 v[18:21], v[154:157], v[202:205], v[18:21]
	s_nop 0
	s_nop 0
	v_mfma_f32_16x16x32_bf16 v[46:49], v[158:161], v[174:177], v[46:49]
	v_mfma_f32_16x16x32_bf16 v[38:41], v[166:169], v[174:177], v[38:41]
	v_mfma_f32_16x16x32_bf16 v[30:33], v[158:161], v[182:185], v[30:33]
	v_mfma_f32_16x16x32_bf16 v[22:25], v[166:169], v[182:185], v[22:25]
	v_mfma_f32_16x16x32_bf16 v[14:17], v[158:161], v[190:193], v[14:17]
	v_mfma_f32_16x16x32_bf16 v[10:13], v[166:169], v[190:193], v[10:13]
	v_mfma_f32_16x16x32_bf16 v[6:9], v[158:161], v[198:201], v[6:9]
	v_mfma_f32_16x16x32_bf16 v[2:5], v[166:169], v[198:201], v[2:5]
	v_mfma_f32_16x16x32_bf16 v[46:49], v[162:165], v[178:181], v[46:49]
	v_mfma_f32_16x16x32_bf16 v[38:41], v[170:173], v[178:181], v[38:41]
	v_mfma_f32_16x16x32_bf16 v[30:33], v[162:165], v[186:189], v[30:33]
	v_mfma_f32_16x16x32_bf16 v[22:25], v[170:173], v[186:189], v[22:25]
	v_mfma_f32_16x16x32_bf16 v[14:17], v[162:165], v[194:197], v[14:17]
	v_mfma_f32_16x16x32_bf16 v[10:13], v[170:173], v[194:197], v[10:13]
	v_mfma_f32_16x16x32_bf16 v[6:9], v[162:165], v[202:205], v[6:9]
	v_mfma_f32_16x16x32_bf16 v[2:5], v[170:173], v[202:205], v[2:5]
	s_nop 0
	s_barrier
	s_add_i32 s68, 0, 0x18000
	s_add_i32 s69, 0, 0x1c000
	v_add_u32_e32 v154, s68, v242
	v_add_u32_e32 v170, s69, v242
	ds_read_b128 v[142:145], v154
	ds_read_b128 v[146:149], v154 offset:1024
	ds_read_b128 v[150:153], v154 offset:2048
	ds_read_b128 v[154:157], v154 offset:3072
	ds_read_b128 v[158:161], v170
	ds_read_b128 v[162:165], v170 offset:1024
	ds_read_b128 v[166:169], v170 offset:2048
	ds_read_b128 v[170:173], v170 offset:3072
	s_add_u32 s40, s40, s22
	s_addc_u32 s41, s41, s23
	s_mov_b32 m0, s46
	v_lshl_add_u64 v[218:219], s[40:41], 0, v[130:131]
	ds_read_b128 v[174:177], v244 offset:32768
	ds_read_b128 v[178:181], v244 offset:33792
	ds_read_b128 v[182:185], v244 offset:34816
	ds_read_b128 v[186:189], v244 offset:35840
	ds_read_b128 v[190:193], v244 offset:36864
	ds_read_b128 v[194:197], v244 offset:37888
	ds_read_b128 v[198:201], v244 offset:38912
	ds_read_b128 v[202:205], v244 offset:39936
	global_load_lds_dwordx4 v[218:219], off
	v_lshl_add_u64 v[218:219], s[40:41], 0, v[134:135]
	s_mov_b32 m0, s47
	s_nop 0
	global_load_lds_dwordx4 v[218:219], off
	s_waitcnt vmcnt(8)
	s_waitcnt lgkmcnt(0)
	s_barrier
	s_nop 0
	s_waitcnt lgkmcnt(0)
	v_mfma_f32_16x16x32_bf16 v[126:129], v[142:145], v[174:177], v[126:129]
	v_mfma_f32_16x16x32_bf16 v[122:125], v[150:153], v[174:177], v[122:125]
	v_mfma_f32_16x16x32_bf16 v[118:121], v[142:145], v[182:185], v[118:121]
	v_mfma_f32_16x16x32_bf16 v[114:117], v[150:153], v[182:185], v[114:117]
	v_mfma_f32_16x16x32_bf16 v[106:109], v[142:145], v[190:193], v[106:109]
	v_mfma_f32_16x16x32_bf16 v[98:101], v[150:153], v[190:193], v[98:101]
	v_mfma_f32_16x16x32_bf16 v[90:93], v[142:145], v[198:201], v[90:93]
	v_mfma_f32_16x16x32_bf16 v[82:85], v[150:153], v[198:201], v[82:85]
	v_mfma_f32_16x16x32_bf16 v[126:129], v[146:149], v[178:181], v[126:129]
	v_mfma_f32_16x16x32_bf16 v[122:125], v[154:157], v[178:181], v[122:125]
	v_mfma_f32_16x16x32_bf16 v[118:121], v[146:149], v[186:189], v[118:121]
	v_mfma_f32_16x16x32_bf16 v[114:117], v[154:157], v[186:189], v[114:117]
	v_mfma_f32_16x16x32_bf16 v[106:109], v[146:149], v[194:197], v[106:109]
	v_mfma_f32_16x16x32_bf16 v[98:101], v[154:157], v[194:197], v[98:101]
	v_mfma_f32_16x16x32_bf16 v[90:93], v[146:149], v[202:205], v[90:93]
	v_mfma_f32_16x16x32_bf16 v[82:85], v[154:157], v[202:205], v[82:85]
	s_nop 0
	s_nop 0
	v_mfma_f32_16x16x32_bf16 v[110:113], v[158:161], v[174:177], v[110:113]
	v_mfma_f32_16x16x32_bf16 v[102:105], v[166:169], v[174:177], v[102:105]
	v_mfma_f32_16x16x32_bf16 v[94:97], v[158:161], v[182:185], v[94:97]
	v_mfma_f32_16x16x32_bf16 v[86:89], v[166:169], v[182:185], v[86:89]
	v_mfma_f32_16x16x32_bf16 v[78:81], v[158:161], v[190:193], v[78:81]
	v_mfma_f32_16x16x32_bf16 v[74:77], v[166:169], v[190:193], v[74:77]
	v_mfma_f32_16x16x32_bf16 v[70:73], v[158:161], v[198:201], v[70:73]
	v_mfma_f32_16x16x32_bf16 v[66:69], v[166:169], v[198:201], v[66:69]
	v_mfma_f32_16x16x32_bf16 v[110:113], v[162:165], v[178:181], v[110:113]
	v_mfma_f32_16x16x32_bf16 v[102:105], v[170:173], v[178:181], v[102:105]
	v_mfma_f32_16x16x32_bf16 v[94:97], v[162:165], v[186:189], v[94:97]
	v_mfma_f32_16x16x32_bf16 v[86:89], v[170:173], v[186:189], v[86:89]
	v_mfma_f32_16x16x32_bf16 v[78:81], v[162:165], v[194:197], v[78:81]
	v_mfma_f32_16x16x32_bf16 v[74:77], v[170:173], v[194:197], v[74:77]
	v_mfma_f32_16x16x32_bf16 v[70:73], v[162:165], v[202:205], v[70:73]
	v_mfma_f32_16x16x32_bf16 v[66:69], v[170:173], v[202:205], v[66:69]
	s_nop 0
	s_barrier
; #define PG8_STAGE(bufoff, gbase, voff) do { _Pragma("unroll") for (int _i = 0; _i < 2; ++_i) \
;         __builtin_amdgcn_global_load_lds((const unsigned*)((const char*)(gbase) + (voff)[_i]), (PG8_LAS unsigned*)(lds + (bufoff) + ldsw + _i * 8192), 16, 0, 0); } while (0)
; #define PG8_LDA(dst, b, h) do { _Pragma("unroll") for (int m = 0; m < 4; ++m) _Pragma("unroll") for (int k = 0; k < 2; ++k) dst[m][k] = *(const PG8_LAS bf16x8*)(lds + PG8_SA(b, h) + aoff + m * 2048 + k * 1024); } while (0)
; #define PG8_MMA(ai, bj, At, Bt) do { __builtin_amdgcn_s_setprio(1); _Pragma("unroll") for (int m = 0; m < 4; ++m) _Pragma("unroll") for (int n = 0; n < 2; ++n) _Pragma("unroll") for (int k = 0; k < 2; ++k) \
;         acc[ai][bj][m][n] = __builtin_amdgcn_mfma_f32_16x16x32_bf16(Bt[n][k], At[m][k], acc[ai][bj][m][n], 0, 0, 0); __builtin_amdgcn_s_setprio(0); } while (0)
; #define PG8_WAIT_V(n) asm volatile("s_waitcnt vmcnt(" #n ")" ::: "memory")
; #define PG8_WAIT_L(n) asm volatile("s_waitcnt lgkmcnt(" #n ")" ::: "memory")
; #define PG8_BAR __builtin_amdgcn_s_barrier()
; #define PG8_SCHED __builtin_amdgcn_sched_barrier(0)
; template <class Epi, class Sched, bool ALIGN_EPI = false, bool SP2 = false>
; __device__ __forceinline__ void gemm_phase(PG8_LAS unsigned char* lds, const Gemm g, const Sched& S, const Epi& E) {
;     ...
;         for (int t = 0; t < nt; t += 2) {
;             const bool last = (t == nt - 2);
;             const char* a1 = cA + (size_t)(t + 1) * kstep;
;             const char* a2 = last ? nA : cA + (size_t)(t + 2) * kstep; const char* b2 = last ? nB : cB + (size_t)(t + 2) * kstep;
;             const char* a3 = a2 + kstep; const char* b3 = b2 + kstep;
;     ...
;             PG8_LDA(At, 1, 1); PG8_STAGE(PG8_SB(1, 0), b3, voffB); PG8_STAGE(PG8_SB(1, 1), b3 + hstep, voffB); PG8_STAGE(PG8_SA(1, 0), a3, voffA);
;             PG8_WAIT_V(8); PG8_WAIT_L(0); PG8_BAR; PG8_MMA(1, 0, At, B0); PG8_MMA(1, 1, At, B1); PG8_BAR; PG8_SCHED;
	s_add_i32 s40, s68, s43
	v_lshl_add_u64 v[206:207], v[206:207], 0, s[92:93]
	s_mov_b32 m0, s40
	ds_read_b128 v[174:177], v244 offset:49152
	ds_read_b128 v[178:181], v244 offset:50176
	ds_read_b128 v[182:185], v244 offset:51200
	ds_read_b128 v[186:189], v244 offset:52224
	ds_read_b128 v[190:193], v244 offset:53248
	ds_read_b128 v[194:197], v244 offset:54272
	ds_read_b128 v[198:201], v244 offset:55296
	ds_read_b128 v[202:205], v244 offset:56320
	global_load_lds_dwordx4 v[206:207], off
	v_lshl_add_u64 v[206:207], v[208:209], 0, s[92:93]
	s_add_i32 m0, s40, 0x2000
	s_add_i32 s40, s69, s43
	global_load_lds_dwordx4 v[206:207], off
	v_lshl_add_u64 v[206:207], v[210:211], 0, s[92:93]
	s_mov_b32 m0, s40
	s_nop 0
	global_load_lds_dwordx4 v[206:207], off
	v_lshl_add_u64 v[206:207], v[212:213], 0, s[92:93]
	s_add_i32 m0, s40, 0x2000
	s_nop 0
	global_load_lds_dwordx4 v[206:207], off
	v_lshl_add_u64 v[206:207], v[214:215], 0, s[92:93]
	s_mov_b32 m0, s48
	s_nop 0
	global_load_lds_dwordx4 v[206:207], off
	v_lshl_add_u64 v[206:207], v[216:217], 0, s[92:93]
	s_mov_b32 m0, s49
	s_nop 0
	global_load_lds_dwordx4 v[206:207], off
	s_waitcnt vmcnt(8)
	s_waitcnt lgkmcnt(0)
	s_barrier
	s_nop 0
	s_waitcnt lgkmcnt(0)
	v_mfma_f32_16x16x32_bf16 v[62:65], v[142:145], v[174:177], v[62:65]
	v_mfma_f32_16x16x32_bf16 v[58:61], v[150:153], v[174:177], v[58:61]
	v_mfma_f32_16x16x32_bf16 v[54:57], v[142:145], v[182:185], v[54:57]
	v_mfma_f32_16x16x32_bf16 v[50:53], v[150:153], v[182:185], v[50:53]
	v_mfma_f32_16x16x32_bf16 v[42:45], v[142:145], v[190:193], v[42:45]
	v_mfma_f32_16x16x32_bf16 v[34:37], v[150:153], v[190:193], v[34:37]
	v_mfma_f32_16x16x32_bf16 v[26:29], v[142:145], v[198:201], v[26:29]
	v_mfma_f32_16x16x32_bf16 v[18:21], v[150:153], v[198:201], v[18:21]
	v_mfma_f32_16x16x32_bf16 v[62:65], v[146:149], v[178:181], v[62:65]
	v_mfma_f32_16x16x32_bf16 v[58:61], v[154:157], v[178:181], v[58:61]
	v_mfma_f32_16x16x32_bf16 v[54:57], v[146:149], v[186:189], v[54:57]
	v_mfma_f32_16x16x32_bf16 v[50:53], v[154:157], v[186:189], v[50:53]
	v_mfma_f32_16x16x32_bf16 v[42:45], v[146:149], v[194:197], v[42:45]
	v_mfma_f32_16x16x32_bf16 v[34:37], v[154:157], v[194:197], v[34:37]
	v_mfma_f32_16x16x32_bf16 v[26:29], v[146:149], v[202:205], v[26:29]
	v_mfma_f32_16x16x32_bf16 v[18:21], v[154:157], v[202:205], v[18:21]
	s_nop 0
	s_nop 0
	v_mfma_f32_16x16x32_bf16 v[46:49], v[158:161], v[174:177], v[46:49]
	v_mfma_f32_16x16x32_bf16 v[38:41], v[166:169], v[174:177], v[38:41]
	v_mfma_f32_16x16x32_bf16 v[30:33], v[158:161], v[182:185], v[30:33]
	v_mfma_f32_16x16x32_bf16 v[22:25], v[166:169], v[182:185], v[22:25]
	v_mfma_f32_16x16x32_bf16 v[14:17], v[158:161], v[190:193], v[14:17]
	v_mfma_f32_16x16x32_bf16 v[10:13], v[166:169], v[190:193], v[10:13]
	v_mfma_f32_16x16x32_bf16 v[6:9], v[158:161], v[198:201], v[6:9]
	v_mfma_f32_16x16x32_bf16 v[2:5], v[166:169], v[198:201], v[2:5]
	v_mfma_f32_16x16x32_bf16 v[46:49], v[162:165], v[178:181], v[46:49]
	v_mfma_f32_16x16x32_bf16 v[38:41], v[170:173], v[178:181], v[38:41]
	v_mfma_f32_16x16x32_bf16 v[30:33], v[162:165], v[186:189], v[30:33]
	v_mfma_f32_16x16x32_bf16 v[22:25], v[170:173], v[186:189], v[22:25]
	v_mfma_f32_16x16x32_bf16 v[14:17], v[162:165], v[194:197], v[14:17]
	v_mfma_f32_16x16x32_bf16 v[10:13], v[170:173], v[194:197], v[10:13]
	v_mfma_f32_16x16x32_bf16 v[6:9], v[162:165], v[202:205], v[6:9]
	v_mfma_f32_16x16x32_bf16 v[2:5], v[170:173], v[202:205], v[2:5]
	s_nop 0
	s_barrier
	s_add_u32 s65, s65, 0x100
	s_addc_u32 s66, s66, 0
	s_add_u32 s38, s38, 0x100
	s_addc_u32 s39, s39, 0
	s_cmp_ge_i32 s67, s51
	s_mov_b32 s40, s67
	s_cbranch_scc0 .LBB0_3248
; __device__ __forceinline__ unsigned cvt_pk_bf16(float lo, float hi) { unsigned r; asm volatile("v_cvt_pk_bf16_f32 %0, %1, %2" : "=v"(r) : "v"(lo), "v"(hi)); return r; }
;     __device__ __forceinline__ void operator()(const f32x4 (&acc)[2][2][4][2], const Unit& u, int wr, int wc, int fr, int fq) const {
;     ...
;                 for (int bj = 0; bj < 2; ++bj) {
;                     f32x4* p = (f32x4*)(xr + bj * HALF);
;                     const f32x4 o0 = xv[g & 1][rr][bj][0] + acc[ai][bj][m][0] * scale, o1 = xv[g & 1][rr][bj][1] + acc[ai][bj][m][1] * scale;
;                     p[0] = o0; p[1] = o1;
;                     u32x4 w; w.x = cvt_pk_bf16(o0[0], o0[1]); w.y = cvt_pk_bf16(o0[2], o0[3]); w.z = cvt_pk_bf16(o1[0], o1[1]); w.w = cvt_pk_bf16(o1[2], o1[3]);
;                     *(u32x4*)(br + bj * HALF) = w;
;                     ss += (o0[0] * o0[0] + o0[1] * o0[1]) + (o0[2] * o0[2] + o0[3] * o0[3]) + (o1[0] * o1[0] + o1[1] * o1[1]) + (o1[2] * o1[2] + o1[3] * o1[3]);
	v_pk_mul_f32 v[206:207], v[128:129], 0.5 op_sel_hi:[1,0]
	v_pk_mul_f32 v[212:213], v[126:127], 0.5 op_sel_hi:[1,0]
	v_pk_mul_f32 v[210:211], v[124:125], 0.5 op_sel_hi:[1,0]
	v_pk_mul_f32 v[208:209], v[122:123], 0.5 op_sel_hi:[1,0]
	v_pk_mul_f32 v[202:203], v[112:113], 0.5 op_sel_hi:[1,0]
	v_pk_mul_f32 v[200:201], v[110:111], 0.5 op_sel_hi:[1,0]
	v_pk_mul_f32 v[198:199], v[104:105], 0.5 op_sel_hi:[1,0]
	v_pk_mul_f32 v[196:197], v[102:103], 0.5 op_sel_hi:[1,0]
	v_pk_mul_f32 v[190:191], v[120:121], 0.5 op_sel_hi:[1,0]
	v_pk_mul_f32 v[188:189], v[118:119], 0.5 op_sel_hi:[1,0]
	v_pk_mul_f32 v[186:187], v[116:117], 0.5 op_sel_hi:[1,0]
	v_pk_mul_f32 v[184:185], v[114:115], 0.5 op_sel_hi:[1,0]
	v_pk_mul_f32 v[182:183], v[96:97], 0.5 op_sel_hi:[1,0]
	v_pk_mul_f32 v[180:181], v[94:95], 0.5 op_sel_hi:[1,0]
	v_pk_mul_f32 v[178:179], v[88:89], 0.5 op_sel_hi:[1,0]
	v_pk_mul_f32 v[176:177], v[86:87], 0.5 op_sel_hi:[1,0]
	v_pk_mul_f32 v[174:175], v[108:109], 0.5 op_sel_hi:[1,0]
	v_pk_mul_f32 v[172:173], v[106:107], 0.5 op_sel_hi:[1,0]
	v_pk_mul_f32 v[170:171], v[100:101], 0.5 op_sel_hi:[1,0]
	v_pk_mul_f32 v[168:169], v[98:99], 0.5 op_sel_hi:[1,0]
	v_pk_mul_f32 v[166:167], v[80:81], 0.5 op_sel_hi:[1,0]
	v_pk_mul_f32 v[164:165], v[78:79], 0.5 op_sel_hi:[1,0]
	v_pk_mul_f32 v[162:163], v[76:77], 0.5 op_sel_hi:[1,0]
	v_pk_mul_f32 v[160:161], v[74:75], 0.5 op_sel_hi:[1,0]
	v_pk_mul_f32 v[158:159], v[92:93], 0.5 op_sel_hi:[1,0]
	v_pk_mul_f32 v[156:157], v[90:91], 0.5 op_sel_hi:[1,0]
	v_pk_mul_f32 v[154:155], v[84:85], 0.5 op_sel_hi:[1,0]
	v_pk_mul_f32 v[152:153], v[82:83], 0.5 op_sel_hi:[1,0]
	v_pk_mul_f32 v[150:151], v[72:73], 0.5 op_sel_hi:[1,0]
	v_pk_mul_f32 v[148:149], v[70:71], 0.5 op_sel_hi:[1,0]
	v_pk_mul_f32 v[146:147], v[68:69], 0.5 op_sel_hi:[1,0]
	v_pk_mul_f32 v[144:145], v[66:67], 0.5 op_sel_hi:[1,0]
	v_pk_mul_f32 v[128:129], v[64:65], 0.5 op_sel_hi:[1,0]
	v_pk_mul_f32 v[126:127], v[62:63], 0.5 op_sel_hi:[1,0]
	v_pk_mul_f32 v[124:125], v[60:61], 0.5 op_sel_hi:[1,0]
	v_pk_mul_f32 v[122:123], v[58:59], 0.5 op_sel_hi:[1,0]
	v_pk_mul_f32 v[120:121], v[48:49], 0.5 op_sel_hi:[1,0]
	v_pk_mul_f32 v[118:119], v[46:47], 0.5 op_sel_hi:[1,0]
	v_pk_mul_f32 v[116:117], v[40:41], 0.5 op_sel_hi:[1,0]
	v_pk_mul_f32 v[114:115], v[38:39], 0.5 op_sel_hi:[1,0]
	v_pk_mul_f32 v[112:113], v[56:57], 0.5 op_sel_hi:[1,0]
	v_pk_mul_f32 v[110:111], v[54:55], 0.5 op_sel_hi:[1,0]
	v_pk_mul_f32 v[108:109], v[52:53], 0.5 op_sel_hi:[1,0]
	v_pk_mul_f32 v[106:107], v[50:51], 0.5 op_sel_hi:[1,0]
	v_pk_mul_f32 v[104:105], v[32:33], 0.5 op_sel_hi:[1,0]
	v_pk_mul_f32 v[102:103], v[30:31], 0.5 op_sel_hi:[1,0]
	v_pk_mul_f32 v[100:101], v[24:25], 0.5 op_sel_hi:[1,0]
	v_pk_mul_f32 v[98:99], v[22:23], 0.5 op_sel_hi:[1,0]
	v_pk_mul_f32 v[96:97], v[44:45], 0.5 op_sel_hi:[1,0]
	v_pk_mul_f32 v[94:95], v[42:43], 0.5 op_sel_hi:[1,0]
	v_pk_mul_f32 v[92:93], v[36:37], 0.5 op_sel_hi:[1,0]
	v_pk_mul_f32 v[90:91], v[34:35], 0.5 op_sel_hi:[1,0]
	v_pk_mul_f32 v[88:89], v[16:17], 0.5 op_sel_hi:[1,0]
	v_pk_mul_f32 v[86:87], v[14:15], 0.5 op_sel_hi:[1,0]
	v_pk_mul_f32 v[84:85], v[12:13], 0.5 op_sel_hi:[1,0]
	v_pk_mul_f32 v[82:83], v[10:11], 0.5 op_sel_hi:[1,0]
	v_pk_mul_f32 v[80:81], v[28:29], 0.5 op_sel_hi:[1,0]
	v_pk_mul_f32 v[78:79], v[26:27], 0.5 op_sel_hi:[1,0]
	v_pk_mul_f32 v[76:77], v[20:21], 0.5 op_sel_hi:[1,0]
	v_pk_mul_f32 v[74:75], v[18:19], 0.5 op_sel_hi:[1,0]
	v_pk_mul_f32 v[72:73], v[8:9], 0.5 op_sel_hi:[1,0]
	v_pk_mul_f32 v[70:71], v[6:7], 0.5 op_sel_hi:[1,0]
	v_pk_mul_f32 v[68:69], v[4:5], 0.5 op_sel_hi:[1,0]
	v_pk_mul_f32 v[66:67], v[2:3], 0.5 op_sel_hi:[1,0]
	v_readlane_b32 s68, v252, 27
	v_readlane_b32 s69, v252, 28
	v_readlane_b32 s70, v252, 29
	v_readlane_b32 s71, v252, 30

; #define PG8_WAIT_V(n) asm volatile("s_waitcnt vmcnt(" #n ")" ::: "memory")
; #define PG8_BAR __builtin_amdgcn_s_barrier()
; __device__ __forceinline__ unsigned xb_add(unsigned* p, unsigned v) { return __hip_atomic_fetch_add(p, v, __ATOMIC_RELAXED, __HIP_MEMORY_SCOPE_AGENT); }
; template <class Epi, class Sched, bool ALIGN_EPI = false, bool SP2 = false>
; __device__ __forceinline__ void gemm_phase(PG8_LAS unsigned char* lds, const Gemm g, const Sched& S, const Epi& E) {
;     ...
;     PG8_WAIT_V(0);
;     if constexpr (!ALIGN_EPI) { if (wr == 0) PG8_BAR; }
;     PG8_BAR;
; __device__ __forceinline__ void xcd_barrier(const XcdBarrier& b) {
;     asm volatile("s_waitcnt vmcnt(0)" ::: "memory");
;     __syncthreads();
;     if (b.tid == 0u) {
;         unsigned* bar = b.bar;
;         __builtin_amdgcn_s_waitcnt(0);
;         unsigned nloc = b.st[0], nx = b.st[1];
;         if (nloc == 0u) { xcd_barrier_complete(bar, b.x, nloc, nx); b.st[0] = nloc; b.st[1] = nx; }
;         const unsigned old = xb_add(&bar[XB_XSUB(b.x)], 1u);
.LBB0_3272:
	s_mov_b64 s[4:5], s[88:89]
	s_getreg_b32 s6, hwreg(HW_REG_XCC_ID, 0, 4)
	s_waitcnt vmcnt(0)
	s_waitcnt lgkmcnt(0)
	s_setprio 0
	s_barrier
	s_mov_b64 s[0:1], exec
	v_readlane_b32 s8, v252, 2
	v_readlane_b32 s9, v252, 3
	s_and_b64 s[8:9], s[0:1], s[8:9]
	s_movk_i32 s29, 0x600
	s_mov_b32 s34, 0x5ffff
	s_movk_i32 s35, 0xffe8
	s_mov_b64 s[36:37], 0x8c00340
	s_mov_b64 exec, s[8:9]
	s_cbranch_execz .LBB0_3324
	v_readlane_b32 s7, v252, 13
	s_load_dwordx2 s[4:5], s[4:5], 0x100
	s_waitcnt vmcnt(0) expcnt(0) lgkmcnt(0)
	v_mov_b32_e32 v1, s7
	ds_read_b32 v3, v1
	v_readlane_b32 s7, v252, 14
	s_and_b32 s50, s6, 15
	s_waitcnt lgkmcnt(0)
	v_cmp_ne_u32_e32 vcc, 0, v3
	v_mov_b32_e32 v1, s7
	ds_read_b32 v2, v1
	s_cbranch_vccnz .LBB0_3288
	s_add_u32 s6, s4, 0x17900200
	s_addc_u32 s7, s5, 0
	s_add_u32 s8, s4, 0x17900400
	s_addc_u32 s9, s5, 0
	s_add_u32 s10, s4, 0x17900500
	s_addc_u32 s11, s5, 0
	s_add_u32 s14, s4, 0x17900600
	s_addc_u32 s15, s5, 0
	s_add_u32 s16, s4, 0x17900700
	s_addc_u32 s17, s5, 0
	s_add_u32 s18, s4, 0x17900800
	s_addc_u32 s19, s5, 0
	s_add_u32 s20, s4, 0x17900900
	s_addc_u32 s21, s5, 0
	s_add_u32 s22, s4, 0x17900a00
	s_addc_u32 s23, s5, 0
	s_add_u32 s24, s4, 0x17900b00
	s_addc_u32 s25, s5, 0
	s_add_u32 s26, s4, 0x17900c00
	s_addc_u32 s27, s5, 0
	s_add_u32 s28, s4, 0x17900d00
	s_addc_u32 s29, s5, 0
	s_add_u32 s30, s4, 0x17900e00
	s_addc_u32 s31, s5, 0
	s_add_u32 s34, s4, 0x17900f00
	s_addc_u32 s35, s5, 0
	s_add_u32 s36, s4, 0x17901000
	s_addc_u32 s37, s5, 0
	s_add_u32 s38, s4, 0x17901100
	s_addc_u32 s39, s5, 0
	s_add_u32 s40, s4, 0x17901200
	s_addc_u32 s41, s5, 0
	s_add_u32 s42, s4, 0x17901300
	s_addc_u32 s43, s5, 0
	s_mov_b32 s51, 1
	s_branch .LBB0_3276

; #define PG8_STAGE(bufoff, gbase, voff) do { _Pragma("unroll") for (int _i = 0; _i < 2; ++_i) \
;         __builtin_amdgcn_global_load_lds((const unsigned*)((const char*)(gbase) + (voff)[_i]), (PG8_LAS unsigned*)(lds + (bufoff) + ldsw + _i * 8192), 16, 0, 0); } while (0)
; #define PG8_LDA(dst, b, h) do { _Pragma("unroll") for (int m = 0; m < 4; ++m) _Pragma("unroll") for (int k = 0; k < 2; ++k) dst[m][k] = *(const PG8_LAS bf16x8*)(lds + PG8_SA(b, h) + aoff + m * 2048 + k * 1024); } while (0)
; #define PG8_LDB(dst, b, h) do { _Pragma("unroll") for (int n = 0; n < 2; ++n) _Pragma("unroll") for (int k = 0; k < 2; ++k) dst[n][k] = *(const PG8_LAS bf16x8*)(lds + PG8_SB(b, h) + boff + n * 2048 + k * 1024); } while (0)
; #define PG8_MMA(ai, bj, At, Bt) do { __builtin_amdgcn_s_setprio(1); _Pragma("unroll") for (int m = 0; m < 4; ++m) _Pragma("unroll") for (int n = 0; n < 2; ++n) _Pragma("unroll") for (int k = 0; k < 2; ++k) \
;         acc[ai][bj][m][n] = __builtin_amdgcn_mfma_f32_16x16x32_bf16(Bt[n][k], At[m][k], acc[ai][bj][m][n], 0, 0, 0); __builtin_amdgcn_s_setprio(0); } while (0)
; #define PG8_WAIT_V(n) asm volatile("s_waitcnt vmcnt(" #n ")" ::: "memory")
; #define PG8_WAIT_L(n) asm volatile("s_waitcnt lgkmcnt(" #n ")" ::: "memory")
; #define PG8_BAR __builtin_amdgcn_s_barrier()
; #define PG8_SCHED __builtin_amdgcn_sched_barrier(0)
; template <class Epi, class Sched, bool ALIGN_EPI = false, bool SP2 = false>
; __device__ __forceinline__ void gemm_phase(PG8_LAS unsigned char* lds, const Gemm g, const Sched& S, const Epi& E) {
;     ...
;             PG8_LDB(B0, 0, 0); PG8_LDB(B1, 0, 1); PG8_SCHED; PG8_LDA(At, 0, 0); PG8_STAGE(PG8_SA(1, 1), a1 + hstep, voffA);
;             PG8_WAIT_V(8); PG8_WAIT_L(0); PG8_BAR; PG8_MMA(0, 0, At, B0); PG8_MMA(0, 1, At, B1); PG8_BAR; PG8_SCHED;
;             PG8_LDA(At, 0, 1); PG8_STAGE(PG8_SB(0, 0), b2, voffB); PG8_STAGE(PG8_SB(0, 1), b2 + hstep, voffB); PG8_STAGE(PG8_SA(0, 0), a2, voffA);
;             PG8_WAIT_V(8); PG8_WAIT_L(0); PG8_BAR; PG8_MMA(1, 0, At, B0); PG8_MMA(1, 1, At, B1); PG8_BAR; PG8_SCHED;
.LBB0_3346:
	s_add_i32 s58, s28, 2
	s_add_u32 s59, s26, 0x80
	s_addc_u32 s29, s27, 0
	s_add_i32 s62, 0, 0x10000
	s_cmp_eq_u32 s50, s28
	s_cselect_b32 s29, s1, s29
	s_cselect_b32 s28, s0, s59
	v_add_u32_e32 v148, s62, v149
	s_cselect_b32 s61, s25, s57
	s_cselect_b32 s60, s24, s56
	s_add_i32 s59, 0, 0x14000
	ds_read_b128 v[130:133], v148
	ds_read_b128 v[154:157], v148 offset:1024
	ds_read_b128 v[158:161], v148 offset:2048
	ds_read_b128 v[162:165], v148 offset:3072
	v_add_u32_e32 v148, s59, v149
	ds_read_b128 v[166:169], v148
	ds_read_b128 v[170:173], v148 offset:1024
	ds_read_b128 v[174:177], v148 offset:2048
	ds_read_b128 v[178:181], v148 offset:3072
	v_lshl_add_u64 v[214:215], s[26:27], 0, v[146:147]
	s_add_i32 m0, s43, 0xc000
	ds_read_b128 v[182:185], v153
	ds_read_b128 v[186:189], v153 offset:1024
	ds_read_b128 v[190:193], v153 offset:2048
	ds_read_b128 v[194:197], v153 offset:3072
	ds_read_b128 v[198:201], v153 offset:4096
	ds_read_b128 v[202:205], v153 offset:5120
	ds_read_b128 v[206:209], v153 offset:6144
	ds_read_b128 v[210:213], v153 offset:7168
	global_load_lds_dwordx4 v[214:215], off
	v_lshl_add_u64 v[214:215], s[26:27], 0, v[144:145]
	s_add_i32 m0, s43, 0xe000
	s_nop 0
	global_load_lds_dwordx4 v[214:215], off
	s_waitcnt vmcnt(8)
	s_waitcnt lgkmcnt(0)
	s_barrier
	s_nop 0
	s_waitcnt lgkmcnt(0)
	v_mfma_f32_16x16x32_bf16 v[126:129], v[130:133], v[182:185], v[126:129]
	v_mfma_f32_16x16x32_bf16 v[122:125], v[158:161], v[182:185], v[122:125]
	v_mfma_f32_16x16x32_bf16 v[110:113], v[130:133], v[190:193], v[110:113]
	v_mfma_f32_16x16x32_bf16 v[106:109], v[158:161], v[190:193], v[106:109]
	v_mfma_f32_16x16x32_bf16 v[94:97], v[130:133], v[198:201], v[94:97]
	v_mfma_f32_16x16x32_bf16 v[90:93], v[158:161], v[198:201], v[90:93]
	v_mfma_f32_16x16x32_bf16 v[78:81], v[130:133], v[206:209], v[78:81]
	v_mfma_f32_16x16x32_bf16 v[74:77], v[158:161], v[206:209], v[74:77]
	v_mfma_f32_16x16x32_bf16 v[126:129], v[154:157], v[186:189], v[126:129]
	v_mfma_f32_16x16x32_bf16 v[122:125], v[162:165], v[186:189], v[122:125]
	v_mfma_f32_16x16x32_bf16 v[110:113], v[154:157], v[194:197], v[110:113]
	v_mfma_f32_16x16x32_bf16 v[106:109], v[162:165], v[194:197], v[106:109]
	v_mfma_f32_16x16x32_bf16 v[94:97], v[154:157], v[202:205], v[94:97]
	v_mfma_f32_16x16x32_bf16 v[90:93], v[162:165], v[202:205], v[90:93]
	v_mfma_f32_16x16x32_bf16 v[78:81], v[154:157], v[210:213], v[78:81]
	v_mfma_f32_16x16x32_bf16 v[74:77], v[162:165], v[210:213], v[74:77]
	s_nop 0
	s_nop 0
	v_mfma_f32_16x16x32_bf16 v[118:121], v[166:169], v[182:185], v[118:121]
	v_mfma_f32_16x16x32_bf16 v[114:117], v[174:177], v[182:185], v[114:117]
	v_mfma_f32_16x16x32_bf16 v[102:105], v[166:169], v[190:193], v[102:105]
	v_mfma_f32_16x16x32_bf16 v[98:101], v[174:177], v[190:193], v[98:101]
	v_mfma_f32_16x16x32_bf16 v[86:89], v[166:169], v[198:201], v[86:89]
	v_mfma_f32_16x16x32_bf16 v[82:85], v[174:177], v[198:201], v[82:85]
	v_mfma_f32_16x16x32_bf16 v[70:73], v[166:169], v[206:209], v[70:73]
	v_mfma_f32_16x16x32_bf16 v[66:69], v[174:177], v[206:209], v[66:69]
	v_mfma_f32_16x16x32_bf16 v[118:121], v[170:173], v[186:189], v[118:121]
	v_mfma_f32_16x16x32_bf16 v[114:117], v[178:181], v[186:189], v[114:117]
	v_mfma_f32_16x16x32_bf16 v[102:105], v[170:173], v[194:197], v[102:105]
	v_mfma_f32_16x16x32_bf16 v[98:101], v[178:181], v[194:197], v[98:101]
	v_mfma_f32_16x16x32_bf16 v[86:89], v[170:173], v[202:205], v[86:89]
	v_mfma_f32_16x16x32_bf16 v[82:85], v[178:181], v[202:205], v[82:85]
	v_mfma_f32_16x16x32_bf16 v[70:73], v[170:173], v[210:213], v[70:73]
	v_mfma_f32_16x16x32_bf16 v[66:69], v[178:181], v[210:213], v[66:69]
	s_nop 0
	s_barrier
	s_add_i32 s62, s62, s38
	v_lshl_add_u64 v[214:215], s[60:61], 0, v[136:137]
	s_mov_b32 m0, s62
	ds_read_b128 v[182:185], v153 offset:16384
	ds_read_b128 v[186:189], v153 offset:17408
	ds_read_b128 v[190:193], v153 offset:18432
	ds_read_b128 v[194:197], v153 offset:19456
	ds_read_b128 v[198:201], v153 offset:20480
	ds_read_b128 v[202:205], v153 offset:21504
	ds_read_b128 v[206:209], v153 offset:22528
	ds_read_b128 v[210:213], v153 offset:23552
	global_load_lds_dwordx4 v[214:215], off
	s_add_i32 m0, s62, 0x2000
	v_lshl_add_u64 v[216:217], s[60:61], 0, v[140:141]
	s_add_u32 s60, s60, s12
	s_addc_u32 s61, s61, s13
	s_add_i32 s59, s59, s38
	global_load_lds_dwordx4 v[216:217], off
	v_lshl_add_u64 v[218:219], s[60:61], 0, v[136:137]
	s_mov_b32 m0, s59
	v_lshl_add_u64 v[228:229], s[60:61], 0, v[140:141]
	global_load_lds_dwordx4 v[218:219], off
	s_add_i32 m0, s59, 0x2000
	v_lshl_add_u64 v[242:243], s[28:29], 0, v[134:135]
	global_load_lds_dwordx4 v[228:229], off
	s_mov_b32 m0, s43
	v_lshl_add_u64 v[244:245], s[28:29], 0, v[138:139]
	global_load_lds_dwordx4 v[242:243], off
	s_mov_b32 m0, s44
	s_nop 0
	global_load_lds_dwordx4 v[244:245], off
	s_waitcnt vmcnt(8)
	s_waitcnt lgkmcnt(0)
	s_barrier
; #define PG8_STAGE(bufoff, gbase, voff) do { _Pragma("unroll") for (int _i = 0; _i < 2; ++_i) \
;         __builtin_amdgcn_global_load_lds((const unsigned*)((const char*)(gbase) + (voff)[_i]), (PG8_LAS unsigned*)(lds + (bufoff) + ldsw + _i * 8192), 16, 0, 0); } while (0)
; #define PG8_LDA(dst, b, h) do { _Pragma("unroll") for (int m = 0; m < 4; ++m) _Pragma("unroll") for (int k = 0; k < 2; ++k) dst[m][k] = *(const PG8_LAS bf16x8*)(lds + PG8_SA(b, h) + aoff + m * 2048 + k * 1024); } while (0)
; #define PG8_LDB(dst, b, h) do { _Pragma("unroll") for (int n = 0; n < 2; ++n) _Pragma("unroll") for (int k = 0; k < 2; ++k) dst[n][k] = *(const PG8_LAS bf16x8*)(lds + PG8_SB(b, h) + boff + n * 2048 + k * 1024); } while (0)
; #define PG8_MMA(ai, bj, At, Bt) do { __builtin_amdgcn_s_setprio(1); _Pragma("unroll") for (int m = 0; m < 4; ++m) _Pragma("unroll") for (int n = 0; n < 2; ++n) _Pragma("unroll") for (int k = 0; k < 2; ++k) \
;         acc[ai][bj][m][n] = __builtin_amdgcn_mfma_f32_16x16x32_bf16(Bt[n][k], At[m][k], acc[ai][bj][m][n], 0, 0, 0); __builtin_amdgcn_s_setprio(0); } while (0)
; #define PG8_WAIT_V(n) asm volatile("s_waitcnt vmcnt(" #n ")" ::: "memory")
; #define PG8_WAIT_L(n) asm volatile("s_waitcnt lgkmcnt(" #n ")" ::: "memory")
; #define PG8_BAR __builtin_amdgcn_s_barrier()
; #define PG8_SCHED __builtin_amdgcn_sched_barrier(0)
; template <class Epi, class Sched, bool ALIGN_EPI = false, bool SP2 = false>
; __device__ __forceinline__ void gemm_phase(PG8_LAS unsigned char* lds, const Gemm g, const Sched& S, const Epi& E) {
;     ...
;             PG8_WAIT_V(8); PG8_WAIT_L(0); PG8_BAR; PG8_MMA(1, 0, At, B0); PG8_MMA(1, 1, At, B1); PG8_BAR; PG8_SCHED;
;             PG8_LDB(B0, 1, 0); PG8_LDB(B1, 1, 1); PG8_SCHED; PG8_LDA(At, 1, 0); PG8_STAGE(PG8_SA(0, 1), a2 + hstep, voffA);
;             PG8_WAIT_V(8); PG8_WAIT_L(0); PG8_BAR; PG8_MMA(0, 0, At, B0); PG8_MMA(0, 1, At, B1); PG8_BAR; PG8_SCHED;
	s_nop 0
	s_waitcnt lgkmcnt(0)
	v_mfma_f32_16x16x32_bf16 v[62:65], v[130:133], v[182:185], v[62:65]
	v_mfma_f32_16x16x32_bf16 v[58:61], v[158:161], v[182:185], v[58:61]
	v_mfma_f32_16x16x32_bf16 v[46:49], v[130:133], v[190:193], v[46:49]
	v_mfma_f32_16x16x32_bf16 v[42:45], v[158:161], v[190:193], v[42:45]
	v_mfma_f32_16x16x32_bf16 v[30:33], v[130:133], v[198:201], v[30:33]
	v_mfma_f32_16x16x32_bf16 v[26:29], v[158:161], v[198:201], v[26:29]
	v_mfma_f32_16x16x32_bf16 v[14:17], v[130:133], v[206:209], v[14:17]
	v_mfma_f32_16x16x32_bf16 v[10:13], v[158:161], v[206:209], v[10:13]
	v_mfma_f32_16x16x32_bf16 v[62:65], v[154:157], v[186:189], v[62:65]
	v_mfma_f32_16x16x32_bf16 v[58:61], v[162:165], v[186:189], v[58:61]
	v_mfma_f32_16x16x32_bf16 v[46:49], v[154:157], v[194:197], v[46:49]
	v_mfma_f32_16x16x32_bf16 v[42:45], v[162:165], v[194:197], v[42:45]
	v_mfma_f32_16x16x32_bf16 v[30:33], v[154:157], v[202:205], v[30:33]
	v_mfma_f32_16x16x32_bf16 v[26:29], v[162:165], v[202:205], v[26:29]
	v_mfma_f32_16x16x32_bf16 v[14:17], v[154:157], v[210:213], v[14:17]
	v_mfma_f32_16x16x32_bf16 v[10:13], v[162:165], v[210:213], v[10:13]
	s_nop 0
	s_nop 0
	v_mfma_f32_16x16x32_bf16 v[54:57], v[166:169], v[182:185], v[54:57]
	v_mfma_f32_16x16x32_bf16 v[50:53], v[174:177], v[182:185], v[50:53]
	v_mfma_f32_16x16x32_bf16 v[38:41], v[166:169], v[190:193], v[38:41]
	v_mfma_f32_16x16x32_bf16 v[34:37], v[174:177], v[190:193], v[34:37]
	v_mfma_f32_16x16x32_bf16 v[22:25], v[166:169], v[198:201], v[22:25]
	v_mfma_f32_16x16x32_bf16 v[18:21], v[174:177], v[198:201], v[18:21]
	v_mfma_f32_16x16x32_bf16 v[6:9], v[166:169], v[206:209], v[6:9]
	v_mfma_f32_16x16x32_bf16 v[2:5], v[174:177], v[206:209], v[2:5]
	v_mfma_f32_16x16x32_bf16 v[54:57], v[170:173], v[186:189], v[54:57]
	v_mfma_f32_16x16x32_bf16 v[50:53], v[178:181], v[186:189], v[50:53]
	v_mfma_f32_16x16x32_bf16 v[38:41], v[170:173], v[194:197], v[38:41]
	v_mfma_f32_16x16x32_bf16 v[34:37], v[178:181], v[194:197], v[34:37]
	v_mfma_f32_16x16x32_bf16 v[22:25], v[170:173], v[202:205], v[22:25]
	v_mfma_f32_16x16x32_bf16 v[18:21], v[178:181], v[202:205], v[18:21]
	v_mfma_f32_16x16x32_bf16 v[6:9], v[170:173], v[210:213], v[6:9]
	v_mfma_f32_16x16x32_bf16 v[2:5], v[178:181], v[210:213], v[2:5]
	s_nop 0
	s_barrier
	s_add_i32 s59, 0, 0x18000
	v_add_u32_e32 v148, s59, v149
	s_add_i32 s60, 0, 0x1c000
	ds_read_b128 v[130:133], v148
	ds_read_b128 v[154:157], v148 offset:1024
	ds_read_b128 v[158:161], v148 offset:2048
	ds_read_b128 v[162:165], v148 offset:3072
	v_add_u32_e32 v148, s60, v149
	ds_read_b128 v[166:169], v148
	ds_read_b128 v[170:173], v148 offset:1024
	ds_read_b128 v[174:177], v148 offset:2048
	ds_read_b128 v[178:181], v148 offset:3072
	s_add_u32 s28, s28, s12
	s_addc_u32 s29, s29, s13
	s_mov_b32 m0, s45
	v_lshl_add_u64 v[246:247], s[28:29], 0, v[134:135]
	ds_read_b128 v[182:185], v153 offset:32768
	ds_read_b128 v[186:189], v153 offset:33792
	ds_read_b128 v[190:193], v153 offset:34816
	ds_read_b128 v[194:197], v153 offset:35840
	ds_read_b128 v[198:201], v153 offset:36864
	ds_read_b128 v[202:205], v153 offset:37888
	ds_read_b128 v[206:209], v153 offset:38912
	ds_read_b128 v[210:213], v153 offset:39936
	global_load_lds_dwordx4 v[246:247], off
	v_lshl_add_u64 v[246:247], s[28:29], 0, v[138:139]
	s_mov_b32 m0, s46
	s_nop 0
	global_load_lds_dwordx4 v[246:247], off
	s_waitcnt vmcnt(8)
	s_waitcnt lgkmcnt(0)
	s_barrier
	s_nop 0
	s_waitcnt lgkmcnt(0)
	v_mfma_f32_16x16x32_bf16 v[126:129], v[130:133], v[182:185], v[126:129]
	v_mfma_f32_16x16x32_bf16 v[122:125], v[158:161], v[182:185], v[122:125]
	v_mfma_f32_16x16x32_bf16 v[110:113], v[130:133], v[190:193], v[110:113]
	v_mfma_f32_16x16x32_bf16 v[106:109], v[158:161], v[190:193], v[106:109]
	v_mfma_f32_16x16x32_bf16 v[94:97], v[130:133], v[198:201], v[94:97]
	v_mfma_f32_16x16x32_bf16 v[90:93], v[158:161], v[198:201], v[90:93]
	v_mfma_f32_16x16x32_bf16 v[78:81], v[130:133], v[206:209], v[78:81]
	v_mfma_f32_16x16x32_bf16 v[74:77], v[158:161], v[206:209], v[74:77]
	v_mfma_f32_16x16x32_bf16 v[126:129], v[154:157], v[186:189], v[126:129]
	v_mfma_f32_16x16x32_bf16 v[122:125], v[162:165], v[186:189], v[122:125]
	v_mfma_f32_16x16x32_bf16 v[110:113], v[154:157], v[194:197], v[110:113]
	v_mfma_f32_16x16x32_bf16 v[106:109], v[162:165], v[194:197], v[106:109]
	v_mfma_f32_16x16x32_bf16 v[94:97], v[154:157], v[202:205], v[94:97]
	v_mfma_f32_16x16x32_bf16 v[90:93], v[162:165], v[202:205], v[90:93]
	v_mfma_f32_16x16x32_bf16 v[78:81], v[154:157], v[210:213], v[78:81]
	v_mfma_f32_16x16x32_bf16 v[74:77], v[162:165], v[210:213], v[74:77]
	s_nop 0
	s_nop 0
	v_mfma_f32_16x16x32_bf16 v[118:121], v[166:169], v[182:185], v[118:121]
	v_mfma_f32_16x16x32_bf16 v[114:117], v[174:177], v[182:185], v[114:117]
	v_mfma_f32_16x16x32_bf16 v[102:105], v[166:169], v[190:193], v[102:105]
	v_mfma_f32_16x16x32_bf16 v[98:101], v[174:177], v[190:193], v[98:101]
	v_mfma_f32_16x16x32_bf16 v[86:89], v[166:169], v[198:201], v[86:89]
	v_mfma_f32_16x16x32_bf16 v[82:85], v[174:177], v[198:201], v[82:85]
	v_mfma_f32_16x16x32_bf16 v[70:73], v[166:169], v[206:209], v[70:73]
	v_mfma_f32_16x16x32_bf16 v[66:69], v[174:177], v[206:209], v[66:69]
	v_mfma_f32_16x16x32_bf16 v[118:121], v[170:173], v[186:189], v[118:121]
	v_mfma_f32_16x16x32_bf16 v[114:117], v[178:181], v[186:189], v[114:117]
	v_mfma_f32_16x16x32_bf16 v[102:105], v[170:173], v[194:197], v[102:105]
	v_mfma_f32_16x16x32_bf16 v[98:101], v[178:181], v[194:197], v[98:101]
	v_mfma_f32_16x16x32_bf16 v[86:89], v[170:173], v[202:205], v[86:89]
	v_mfma_f32_16x16x32_bf16 v[82:85], v[178:181], v[202:205], v[82:85]
	v_mfma_f32_16x16x32_bf16 v[70:73], v[170:173], v[210:213], v[70:73]
	v_mfma_f32_16x16x32_bf16 v[66:69], v[178:181], v[210:213], v[66:69]
	s_nop 0
	s_barrier
; #define PG8_STAGE(bufoff, gbase, voff) do { _Pragma("unroll") for (int _i = 0; _i < 2; ++_i) \
;         __builtin_amdgcn_global_load_lds((const unsigned*)((const char*)(gbase) + (voff)[_i]), (PG8_LAS unsigned*)(lds + (bufoff) + ldsw + _i * 8192), 16, 0, 0); } while (0)
; #define PG8_LDA(dst, b, h) do { _Pragma("unroll") for (int m = 0; m < 4; ++m) _Pragma("unroll") for (int k = 0; k < 2; ++k) dst[m][k] = *(const PG8_LAS bf16x8*)(lds + PG8_SA(b, h) + aoff + m * 2048 + k * 1024); } while (0)
; #define PG8_MMA(ai, bj, At, Bt) do { __builtin_amdgcn_s_setprio(1); _Pragma("unroll") for (int m = 0; m < 4; ++m) _Pragma("unroll") for (int n = 0; n < 2; ++n) _Pragma("unroll") for (int k = 0; k < 2; ++k) \
;         acc[ai][bj][m][n] = __builtin_amdgcn_mfma_f32_16x16x32_bf16(Bt[n][k], At[m][k], acc[ai][bj][m][n], 0, 0, 0); __builtin_amdgcn_s_setprio(0); } while (0)
; #define PG8_WAIT_V(n) asm volatile("s_waitcnt vmcnt(" #n ")" ::: "memory")
; #define PG8_WAIT_L(n) asm volatile("s_waitcnt lgkmcnt(" #n ")" ::: "memory")
; #define PG8_BAR __builtin_amdgcn_s_barrier()
; #define PG8_SCHED __builtin_amdgcn_sched_barrier(0)
; template <class Epi, class Sched, bool ALIGN_EPI = false, bool SP2 = false>
; __device__ __forceinline__ void gemm_phase(PG8_LAS unsigned char* lds, const Gemm g, const Sched& S, const Epi& E) {
;     ...
;         for (int t = 0; t < nt; t += 2) {
;             const bool last = (t == nt - 2);
;             const char* a1 = cA + (size_t)(t + 1) * kstep;
;             const char* a2 = last ? nA : cA + (size_t)(t + 2) * kstep; const char* b2 = last ? nB : cB + (size_t)(t + 2) * kstep;
;             const char* a3 = a2 + kstep; const char* b3 = b2 + kstep;
;     ...
;             PG8_LDA(At, 1, 1); PG8_STAGE(PG8_SB(1, 0), b3, voffB); PG8_STAGE(PG8_SB(1, 1), b3 + hstep, voffB); PG8_STAGE(PG8_SA(1, 0), a3, voffA);
;             PG8_WAIT_V(8); PG8_WAIT_L(0); PG8_BAR; PG8_MMA(1, 0, At, B0); PG8_MMA(1, 1, At, B1); PG8_BAR; PG8_SCHED;
	s_add_i32 s28, s59, s38
	v_lshl_add_u64 v[214:215], v[214:215], 0, s[92:93]
	s_mov_b32 m0, s28
	ds_read_b128 v[182:185], v153 offset:49152
	ds_read_b128 v[186:189], v153 offset:50176
	ds_read_b128 v[190:193], v153 offset:51200
	ds_read_b128 v[194:197], v153 offset:52224
	ds_read_b128 v[198:201], v153 offset:53248
	ds_read_b128 v[202:205], v153 offset:54272
	ds_read_b128 v[206:209], v153 offset:55296
	ds_read_b128 v[210:213], v153 offset:56320
	global_load_lds_dwordx4 v[214:215], off
	v_lshl_add_u64 v[214:215], v[216:217], 0, s[92:93]
	s_add_i32 m0, s28, 0x2000
	s_add_i32 s28, s60, s38
	global_load_lds_dwordx4 v[214:215], off
	v_lshl_add_u64 v[214:215], v[218:219], 0, s[92:93]
	s_mov_b32 m0, s28
	s_nop 0
	global_load_lds_dwordx4 v[214:215], off
	v_lshl_add_u64 v[214:215], v[228:229], 0, s[92:93]
	s_add_i32 m0, s28, 0x2000
	s_nop 0
	global_load_lds_dwordx4 v[214:215], off
	v_lshl_add_u64 v[214:215], v[242:243], 0, s[92:93]
	s_mov_b32 m0, s47
	s_nop 0
	global_load_lds_dwordx4 v[214:215], off
	v_lshl_add_u64 v[214:215], v[244:245], 0, s[92:93]
	s_mov_b32 m0, s48
	s_nop 0
	global_load_lds_dwordx4 v[214:215], off
	s_waitcnt vmcnt(8)
	s_waitcnt lgkmcnt(0)
	s_barrier
	s_nop 0
	s_waitcnt lgkmcnt(0)
	v_mfma_f32_16x16x32_bf16 v[62:65], v[130:133], v[182:185], v[62:65]
	v_mfma_f32_16x16x32_bf16 v[58:61], v[158:161], v[182:185], v[58:61]
	v_mfma_f32_16x16x32_bf16 v[46:49], v[130:133], v[190:193], v[46:49]
	v_mfma_f32_16x16x32_bf16 v[42:45], v[158:161], v[190:193], v[42:45]
	v_mfma_f32_16x16x32_bf16 v[30:33], v[130:133], v[198:201], v[30:33]
	v_mfma_f32_16x16x32_bf16 v[26:29], v[158:161], v[198:201], v[26:29]
	v_mfma_f32_16x16x32_bf16 v[14:17], v[130:133], v[206:209], v[14:17]
	v_mfma_f32_16x16x32_bf16 v[10:13], v[158:161], v[206:209], v[10:13]
	v_mfma_f32_16x16x32_bf16 v[62:65], v[154:157], v[186:189], v[62:65]
	v_mfma_f32_16x16x32_bf16 v[58:61], v[162:165], v[186:189], v[58:61]
	v_mfma_f32_16x16x32_bf16 v[46:49], v[154:157], v[194:197], v[46:49]
	v_mfma_f32_16x16x32_bf16 v[42:45], v[162:165], v[194:197], v[42:45]
	v_mfma_f32_16x16x32_bf16 v[30:33], v[154:157], v[202:205], v[30:33]
	v_mfma_f32_16x16x32_bf16 v[26:29], v[162:165], v[202:205], v[26:29]
	v_mfma_f32_16x16x32_bf16 v[14:17], v[154:157], v[210:213], v[14:17]
	v_mfma_f32_16x16x32_bf16 v[10:13], v[162:165], v[210:213], v[10:13]
	s_nop 0
	s_nop 0
	v_mfma_f32_16x16x32_bf16 v[54:57], v[166:169], v[182:185], v[54:57]
	v_mfma_f32_16x16x32_bf16 v[50:53], v[174:177], v[182:185], v[50:53]
	v_mfma_f32_16x16x32_bf16 v[38:41], v[166:169], v[190:193], v[38:41]
	v_mfma_f32_16x16x32_bf16 v[34:37], v[174:177], v[190:193], v[34:37]
	v_mfma_f32_16x16x32_bf16 v[22:25], v[166:169], v[198:201], v[22:25]
	v_mfma_f32_16x16x32_bf16 v[18:21], v[174:177], v[198:201], v[18:21]
	v_mfma_f32_16x16x32_bf16 v[6:9], v[166:169], v[206:209], v[6:9]
	v_mfma_f32_16x16x32_bf16 v[2:5], v[174:177], v[206:209], v[2:5]
	v_mfma_f32_16x16x32_bf16 v[54:57], v[170:173], v[186:189], v[54:57]
	v_mfma_f32_16x16x32_bf16 v[50:53], v[178:181], v[186:189], v[50:53]
	v_mfma_f32_16x16x32_bf16 v[38:41], v[170:173], v[194:197], v[38:41]
	v_mfma_f32_16x16x32_bf16 v[34:37], v[178:181], v[194:197], v[34:37]
	v_mfma_f32_16x16x32_bf16 v[22:25], v[170:173], v[202:205], v[22:25]
	v_mfma_f32_16x16x32_bf16 v[18:21], v[178:181], v[202:205], v[18:21]
	v_mfma_f32_16x16x32_bf16 v[6:9], v[170:173], v[210:213], v[6:9]
	v_mfma_f32_16x16x32_bf16 v[2:5], v[178:181], v[210:213], v[2:5]
	s_nop 0
	s_barrier
	s_add_u32 s56, s56, 0x100
	s_addc_u32 s57, s57, 0
	s_add_u32 s26, s26, 0x100
	s_addc_u32 s27, s27, 0
	s_cmp_ge_i32 s58, s49
	s_mov_b32 s28, s58
	s_cbranch_scc0 .LBB0_3346

; #define PG8_WAIT_V(n) asm volatile("s_waitcnt vmcnt(" #n ")" ::: "memory")
; #define PG8_BAR __builtin_amdgcn_s_barrier()
; __device__ __forceinline__ unsigned xb_add(unsigned* p, unsigned v) { return __hip_atomic_fetch_add(p, v, __ATOMIC_RELAXED, __HIP_MEMORY_SCOPE_AGENT); }
; template <class Epi, class Sched, bool ALIGN_EPI = false, bool SP2 = false>
; __device__ __forceinline__ void gemm_phase(PG8_LAS unsigned char* lds, const Gemm g, const Sched& S, const Epi& E) {
;     ...
;     PG8_WAIT_V(0);
;     if constexpr (!ALIGN_EPI) { if (wr == 0) PG8_BAR; }
;     PG8_BAR;
; __device__ __forceinline__ void xcd_barrier(const XcdBarrier& b) {
;     asm volatile("s_waitcnt vmcnt(0)" ::: "memory");
;     __syncthreads();
;     if (b.tid == 0u) {
;         unsigned* bar = b.bar;
;         __builtin_amdgcn_s_waitcnt(0);
;         unsigned nloc = b.st[0], nx = b.st[1];
;         if (nloc == 0u) { xcd_barrier_complete(bar, b.x, nloc, nx); b.st[0] = nloc; b.st[1] = nx; }
;         const unsigned old = xb_add(&bar[XB_XSUB(b.x)], 1u);
.LBB0_3353:
	s_mov_b64 s[4:5], s[88:89]
	s_getreg_b32 s6, hwreg(HW_REG_XCC_ID, 0, 4)
	s_waitcnt vmcnt(0)
	s_setprio 0
	s_barrier
	s_mov_b64 s[0:1], exec
	v_readlane_b32 s8, v252, 2
	v_readlane_b32 s9, v252, 3
	s_and_b64 s[8:9], s[0:1], s[8:9]
	s_mov_b64 exec, s[8:9]
	s_cbranch_execz .LBB0_3405
	v_readlane_b32 s7, v252, 13
	s_load_dwordx2 s[4:5], s[4:5], 0x100
	s_waitcnt vmcnt(0) expcnt(0) lgkmcnt(0)
	v_mov_b32_e32 v1, s7
	ds_read_b32 v3, v1
	v_readlane_b32 s7, v252, 14
	s_and_b32 s48, s6, 15
	s_waitcnt lgkmcnt(0)
	v_cmp_ne_u32_e32 vcc, 0, v3
	v_mov_b32_e32 v1, s7
	ds_read_b32 v2, v1
	s_cbranch_vccnz .LBB0_3369
	s_add_u32 s6, s4, 0x17900200
	s_addc_u32 s7, s5, 0
	s_add_u32 s8, s4, 0x17900400
	s_addc_u32 s9, s5, 0
	s_add_u32 s10, s4, 0x17900500
	s_addc_u32 s11, s5, 0
	s_add_u32 s12, s4, 0x17900600
	s_addc_u32 s13, s5, 0
	s_add_u32 s14, s4, 0x17900700
	s_addc_u32 s15, s5, 0
	s_add_u32 s16, s4, 0x17900800
	s_addc_u32 s17, s5, 0
	s_add_u32 s18, s4, 0x17900900
	s_addc_u32 s19, s5, 0
	s_add_u32 s20, s4, 0x17900a00
	s_addc_u32 s21, s5, 0
	s_add_u32 s22, s4, 0x17900b00
	s_addc_u32 s23, s5, 0
	s_add_u32 s24, s4, 0x17900c00
	s_addc_u32 s25, s5, 0
	s_add_u32 s26, s4, 0x17900d00
	s_addc_u32 s27, s5, 0
	s_add_u32 s28, s4, 0x17900e00
	s_addc_u32 s29, s5, 0
	s_add_u32 s30, s4, 0x17900f00
	s_addc_u32 s31, s5, 0
	s_add_u32 s34, s4, 0x17901000
	s_addc_u32 s35, s5, 0
	s_add_u32 s36, s4, 0x17901100
	s_addc_u32 s37, s5, 0
	s_add_u32 s38, s4, 0x17901200
	s_addc_u32 s39, s5, 0
	s_add_u32 s40, s4, 0x17901300
	s_addc_u32 s41, s5, 0
	s_mov_b32 s49, 1
	s_branch .LBB0_3357

; #define KA_DEF const __attribute__((address_space(4))) KArgs* ka_ = (const __attribute__((address_space(4))) KArgs*)__builtin_amdgcn_kernarg_segment_ptr(); asm volatile("" : "+s"(ka_));
; #define SSQ ((float*)WSP(WS_SSQ))
;     __host__ __device__ bool next(int i, Unit& u) const {
;         const long L = (long)i * G + c; if (L >= nwg) return false;
;         int wgid = (int)L; { const int q = nwg / NXCD, r = nwg % NXCD, xcd = wgid % NXCD, off = wgid / NXCD; wgid = (xcd < r ? xcd * (q + 1) : r * (q + 1) + (xcd - r) * q) + off; }
;         const int nig = WGM * nN, gid = wgid / nig, fm = gid * WGM, gsz = (nM - fm) < WGM ? (nM - fm) : WGM;
;         u.pm = fm + ((wgid % nig) % gsz); u.pn = (wgid % nig) / gsz; return true;
; __global__ void __launch_bounds__(512, 2) mega_fwd(KArgs a) {
;     ...
;             { KA_DEF pg8::EpiResid E{X, X, XB, SSQ, 1.0f}; run_gemm(TIDX, lds, MIX, Wl + WO_WOUT, T_, 1024, 1024, E); }
.Lmy_prio_skip_10:
	s_load_dwordx4 s[8:11], s[0:1], 0xf8
	s_movk_i32 s1, 0x400
	s_movk_i32 s0, 0x400
	s_movk_i32 s4, 0x4000
	s_waitcnt lgkmcnt(0)
	s_add_u32 s2, s10, 0x8c00000
	s_addc_u32 s3, s11, 0
	s_add_u32 s12, s10, 0x2bd0000
	s_addc_u32 s13, s11, 0
	s_ashr_i32 s5, s4, 31
	s_lshr_b32 s5, s5, 24
	s_add_i32 s4, s4, s5
	s_ashr_i32 s36, s4, 8
	s_ashr_i32 s4, s1, 31
	s_lshr_b32 s4, s4, 24
	s_add_i32 s1, s1, s4
	s_ashr_i32 s28, s1, 8
	s_mul_i32 s14, s28, s36
	v_mov_b32_e32 v14, v220
	s_cmp_lt_i32 s86, s14
	s_movk_i32 s74, 0xe00
	s_cselect_b64 s[4:5], -1, 0
	s_cmp_ge_i32 s86, s14
	v_readfirstlane_b32 s15, v14
	s_mov_b32 s75, 0x1ffff
	s_mov_b32 s76, 0x8c00000
	s_mov_b32 s77, 0x8c02000
	s_mov_b32 s79, 0x8c03000
	s_mov_b32 s80, 0x8c04000
	s_cbranch_scc1 .LBB0_3971
	s_ashr_i32 s1, s14, 31
	s_lshr_b32 s1, s1, 29
	s_add_i32 s1, s14, s1
	s_ashr_i32 s17, s1, 3
	s_and_b32 s1, s1, -8
	s_sub_i32 s18, s14, s1
	s_add_i32 s16, s17, 1
	v_readlane_b32 s1, v252, 5
	s_cmp_ge_i32 s1, s18
	s_mov_b64 s[6:7], -1
	s_cbranch_scc0 .LBB0_3968
	v_readlane_b32 s6, v252, 5
	s_sub_i32 s6, s6, s18
	s_mul_i32 s1, s16, s18
	s_mul_i32 s6, s6, s17
	s_add_i32 s1, s6, s1
	s_mov_b64 s[6:7], 0

; #define PG8_STAGE(bufoff, gbase, voff) do { _Pragma("unroll") for (int _i = 0; _i < 2; ++_i) \
;         __builtin_amdgcn_global_load_lds((const unsigned*)((const char*)(gbase) + (voff)[_i]), (PG8_LAS unsigned*)(lds + (bufoff) + ldsw + _i * 8192), 16, 0, 0); } while (0)
; #define PG8_LDA(dst, b, h) do { _Pragma("unroll") for (int m = 0; m < 4; ++m) _Pragma("unroll") for (int k = 0; k < 2; ++k) dst[m][k] = *(const PG8_LAS bf16x8*)(lds + PG8_SA(b, h) + aoff + m * 2048 + k * 1024); } while (0)
; #define PG8_LDB(dst, b, h) do { _Pragma("unroll") for (int n = 0; n < 2; ++n) _Pragma("unroll") for (int k = 0; k < 2; ++k) dst[n][k] = *(const PG8_LAS bf16x8*)(lds + PG8_SB(b, h) + boff + n * 2048 + k * 1024); } while (0)
; #define PG8_MMA(ai, bj, At, Bt) do { __builtin_amdgcn_s_setprio(1); _Pragma("unroll") for (int m = 0; m < 4; ++m) _Pragma("unroll") for (int n = 0; n < 2; ++n) _Pragma("unroll") for (int k = 0; k < 2; ++k) \
;         acc[ai][bj][m][n] = __builtin_amdgcn_mfma_f32_16x16x32_bf16(Bt[n][k], At[m][k], acc[ai][bj][m][n], 0, 0, 0); __builtin_amdgcn_s_setprio(0); } while (0)
; #define PG8_WAIT_V(n) asm volatile("s_waitcnt vmcnt(" #n ")" ::: "memory")
; #define PG8_WAIT_L(n) asm volatile("s_waitcnt lgkmcnt(" #n ")" ::: "memory")
; #define PG8_BAR __builtin_amdgcn_s_barrier()
; #define PG8_SCHED __builtin_amdgcn_sched_barrier(0)
; template <class Epi, class Sched, bool ALIGN_EPI = false, bool SP2 = false>
; __device__ __forceinline__ void gemm_phase(PG8_LAS unsigned char* lds, const Gemm g, const Sched& S, const Epi& E) {
;     ...
;             PG8_LDB(B0, 0, 0); PG8_LDB(B1, 0, 1); PG8_SCHED; PG8_LDA(At, 0, 0); PG8_STAGE(PG8_SA(1, 1), a1 + hstep, voffA);
;             PG8_WAIT_V(8); PG8_WAIT_L(0); PG8_BAR; PG8_MMA(0, 0, At, B0); PG8_MMA(0, 1, At, B1); PG8_BAR; PG8_SCHED;
;             PG8_LDA(At, 0, 1); PG8_STAGE(PG8_SB(0, 0), b2, voffB); PG8_STAGE(PG8_SB(0, 1), b2 + hstep, voffB); PG8_STAGE(PG8_SA(0, 0), a2, voffA);
;             PG8_WAIT_V(8); PG8_WAIT_L(0); PG8_BAR; PG8_MMA(1, 0, At, B0); PG8_MMA(1, 1, At, B1); PG8_BAR; PG8_SCHED;
.LBB0_3989:
	s_add_i32 s61, s34, 2
	s_add_u32 s62, s30, 0x80
	s_addc_u32 s35, s31, 0
	s_add_i32 s64, 0, 0x10000
	s_cmp_eq_u32 s46, s34
	s_cselect_b32 s35, s1, s35
	s_cselect_b32 s34, s0, s62
	s_cselect_b32 s63, s29, s60
	s_cselect_b32 s62, s28, s59
	s_add_i32 s65, 0, 0x14000
	v_add_u32_e32 v142, s64, v216
	v_add_u32_e32 v158, s65, v216
	ds_read_b128 v[130:133], v142
	ds_read_b128 v[134:137], v142 offset:1024
	ds_read_b128 v[138:141], v142 offset:2048
	ds_read_b128 v[142:145], v142 offset:3072
	ds_read_b128 v[146:149], v158
	ds_read_b128 v[150:153], v158 offset:1024
	ds_read_b128 v[154:157], v158 offset:2048
	ds_read_b128 v[158:161], v158 offset:3072
	v_lshl_add_u64 v[206:207], s[30:31], 0, v[196:197]
	s_add_i32 m0, s38, 0xc000
	ds_read_b128 v[162:165], v218
	ds_read_b128 v[166:169], v218 offset:1024
	ds_read_b128 v[170:173], v218 offset:2048
	ds_read_b128 v[174:177], v218 offset:3072
	ds_read_b128 v[178:181], v218 offset:4096
	ds_read_b128 v[182:185], v218 offset:5120
	ds_read_b128 v[198:201], v218 offset:6144
	ds_read_b128 v[202:205], v218 offset:7168
	global_load_lds_dwordx4 v[206:207], off
	v_lshl_add_u64 v[206:207], s[30:31], 0, v[194:195]
	s_add_i32 m0, s38, 0xe000
	s_nop 0
	global_load_lds_dwordx4 v[206:207], off
	s_waitcnt vmcnt(8)
	s_waitcnt lgkmcnt(0)
	s_barrier
	s_nop 0
	s_waitcnt lgkmcnt(0)
	v_mfma_f32_16x16x32_bf16 v[126:129], v[130:133], v[162:165], v[126:129]
	v_mfma_f32_16x16x32_bf16 v[122:125], v[138:141], v[162:165], v[122:125]
	v_mfma_f32_16x16x32_bf16 v[110:113], v[130:133], v[170:173], v[110:113]
	v_mfma_f32_16x16x32_bf16 v[106:109], v[138:141], v[170:173], v[106:109]
	v_mfma_f32_16x16x32_bf16 v[94:97], v[130:133], v[178:181], v[94:97]
	v_mfma_f32_16x16x32_bf16 v[90:93], v[138:141], v[178:181], v[90:93]
	v_mfma_f32_16x16x32_bf16 v[78:81], v[130:133], v[198:201], v[78:81]
	v_mfma_f32_16x16x32_bf16 v[74:77], v[138:141], v[198:201], v[74:77]
	v_mfma_f32_16x16x32_bf16 v[126:129], v[134:137], v[166:169], v[126:129]
	v_mfma_f32_16x16x32_bf16 v[122:125], v[142:145], v[166:169], v[122:125]
	v_mfma_f32_16x16x32_bf16 v[110:113], v[134:137], v[174:177], v[110:113]
	v_mfma_f32_16x16x32_bf16 v[106:109], v[142:145], v[174:177], v[106:109]
	v_mfma_f32_16x16x32_bf16 v[94:97], v[134:137], v[182:185], v[94:97]
	v_mfma_f32_16x16x32_bf16 v[90:93], v[142:145], v[182:185], v[90:93]
	v_mfma_f32_16x16x32_bf16 v[78:81], v[134:137], v[202:205], v[78:81]
	v_mfma_f32_16x16x32_bf16 v[74:77], v[142:145], v[202:205], v[74:77]
	s_nop 0
	s_nop 0
	v_mfma_f32_16x16x32_bf16 v[118:121], v[146:149], v[162:165], v[118:121]
	v_mfma_f32_16x16x32_bf16 v[114:117], v[154:157], v[162:165], v[114:117]
	v_mfma_f32_16x16x32_bf16 v[102:105], v[146:149], v[170:173], v[102:105]
	v_mfma_f32_16x16x32_bf16 v[98:101], v[154:157], v[170:173], v[98:101]
	v_mfma_f32_16x16x32_bf16 v[86:89], v[146:149], v[178:181], v[86:89]
	v_mfma_f32_16x16x32_bf16 v[82:85], v[154:157], v[178:181], v[82:85]
	v_mfma_f32_16x16x32_bf16 v[70:73], v[146:149], v[198:201], v[70:73]
	v_mfma_f32_16x16x32_bf16 v[66:69], v[154:157], v[198:201], v[66:69]
	v_mfma_f32_16x16x32_bf16 v[118:121], v[150:153], v[166:169], v[118:121]
	v_mfma_f32_16x16x32_bf16 v[114:117], v[158:161], v[166:169], v[114:117]
	v_mfma_f32_16x16x32_bf16 v[102:105], v[150:153], v[174:177], v[102:105]
	v_mfma_f32_16x16x32_bf16 v[98:101], v[158:161], v[174:177], v[98:101]
	v_mfma_f32_16x16x32_bf16 v[86:89], v[150:153], v[182:185], v[86:89]
	v_mfma_f32_16x16x32_bf16 v[82:85], v[158:161], v[182:185], v[82:85]
	v_mfma_f32_16x16x32_bf16 v[70:73], v[150:153], v[202:205], v[70:73]
	v_mfma_f32_16x16x32_bf16 v[66:69], v[158:161], v[202:205], v[66:69]
	s_nop 0
	s_barrier
	s_add_i32 s64, s64, s37
	v_lshl_add_u64 v[206:207], s[62:63], 0, v[188:189]
	s_mov_b32 m0, s64
	ds_read_b128 v[162:165], v218 offset:16384
	ds_read_b128 v[166:169], v218 offset:17408
	ds_read_b128 v[170:173], v218 offset:18432
	ds_read_b128 v[174:177], v218 offset:19456
	ds_read_b128 v[178:181], v218 offset:20480
	ds_read_b128 v[182:185], v218 offset:21504
	ds_read_b128 v[198:201], v218 offset:22528
	ds_read_b128 v[202:205], v218 offset:23552
	global_load_lds_dwordx4 v[206:207], off
	s_add_i32 m0, s64, 0x2000
	v_lshl_add_u64 v[208:209], s[62:63], 0, v[192:193]
	s_add_u32 s62, s62, s16
	s_addc_u32 s63, s63, s17
	s_add_i32 s64, s65, s37
	global_load_lds_dwordx4 v[208:209], off
	v_lshl_add_u64 v[210:211], s[62:63], 0, v[188:189]
	s_mov_b32 m0, s64
	v_lshl_add_u64 v[212:213], s[62:63], 0, v[192:193]
	global_load_lds_dwordx4 v[210:211], off
	s_add_i32 m0, s64, 0x2000
	v_lshl_add_u64 v[214:215], s[34:35], 0, v[186:187]
	global_load_lds_dwordx4 v[212:213], off
	s_mov_b32 m0, s38
	v_lshl_add_u64 v[228:229], s[34:35], 0, v[190:191]
	global_load_lds_dwordx4 v[214:215], off
	s_mov_b32 m0, s39
	s_nop 0
	global_load_lds_dwordx4 v[228:229], off
	s_waitcnt vmcnt(8)
	s_waitcnt lgkmcnt(0)
	s_barrier
; #define PG8_STAGE(bufoff, gbase, voff) do { _Pragma("unroll") for (int _i = 0; _i < 2; ++_i) \
;         __builtin_amdgcn_global_load_lds((const unsigned*)((const char*)(gbase) + (voff)[_i]), (PG8_LAS unsigned*)(lds + (bufoff) + ldsw + _i * 8192), 16, 0, 0); } while (0)
; #define PG8_LDA(dst, b, h) do { _Pragma("unroll") for (int m = 0; m < 4; ++m) _Pragma("unroll") for (int k = 0; k < 2; ++k) dst[m][k] = *(const PG8_LAS bf16x8*)(lds + PG8_SA(b, h) + aoff + m * 2048 + k * 1024); } while (0)
; #define PG8_LDB(dst, b, h) do { _Pragma("unroll") for (int n = 0; n < 2; ++n) _Pragma("unroll") for (int k = 0; k < 2; ++k) dst[n][k] = *(const PG8_LAS bf16x8*)(lds + PG8_SB(b, h) + boff + n * 2048 + k * 1024); } while (0)
; #define PG8_MMA(ai, bj, At, Bt) do { __builtin_amdgcn_s_setprio(1); _Pragma("unroll") for (int m = 0; m < 4; ++m) _Pragma("unroll") for (int n = 0; n < 2; ++n) _Pragma("unroll") for (int k = 0; k < 2; ++k) \
;         acc[ai][bj][m][n] = __builtin_amdgcn_mfma_f32_16x16x32_bf16(Bt[n][k], At[m][k], acc[ai][bj][m][n], 0, 0, 0); __builtin_amdgcn_s_setprio(0); } while (0)
; #define PG8_WAIT_V(n) asm volatile("s_waitcnt vmcnt(" #n ")" ::: "memory")
; #define PG8_WAIT_L(n) asm volatile("s_waitcnt lgkmcnt(" #n ")" ::: "memory")
; #define PG8_BAR __builtin_amdgcn_s_barrier()
; #define PG8_SCHED __builtin_amdgcn_sched_barrier(0)
; template <class Epi, class Sched, bool ALIGN_EPI = false, bool SP2 = false>
; __device__ __forceinline__ void gemm_phase(PG8_LAS unsigned char* lds, const Gemm g, const Sched& S, const Epi& E) {
;     ...
;             PG8_WAIT_V(8); PG8_WAIT_L(0); PG8_BAR; PG8_MMA(1, 0, At, B0); PG8_MMA(1, 1, At, B1); PG8_BAR; PG8_SCHED;
;             PG8_LDB(B0, 1, 0); PG8_LDB(B1, 1, 1); PG8_SCHED; PG8_LDA(At, 1, 0); PG8_STAGE(PG8_SA(0, 1), a2 + hstep, voffA);
;             PG8_WAIT_V(8); PG8_WAIT_L(0); PG8_BAR; PG8_MMA(0, 0, At, B0); PG8_MMA(0, 1, At, B1); PG8_BAR; PG8_SCHED;
	s_nop 0
	s_waitcnt lgkmcnt(0)
	v_mfma_f32_16x16x32_bf16 v[62:65], v[130:133], v[162:165], v[62:65]
	v_mfma_f32_16x16x32_bf16 v[58:61], v[138:141], v[162:165], v[58:61]
	v_mfma_f32_16x16x32_bf16 v[46:49], v[130:133], v[170:173], v[46:49]
	v_mfma_f32_16x16x32_bf16 v[42:45], v[138:141], v[170:173], v[42:45]
	v_mfma_f32_16x16x32_bf16 v[30:33], v[130:133], v[178:181], v[30:33]
	v_mfma_f32_16x16x32_bf16 v[26:29], v[138:141], v[178:181], v[26:29]
	v_mfma_f32_16x16x32_bf16 v[14:17], v[130:133], v[198:201], v[14:17]
	v_mfma_f32_16x16x32_bf16 v[10:13], v[138:141], v[198:201], v[10:13]
	v_mfma_f32_16x16x32_bf16 v[62:65], v[134:137], v[166:169], v[62:65]
	v_mfma_f32_16x16x32_bf16 v[58:61], v[142:145], v[166:169], v[58:61]
	v_mfma_f32_16x16x32_bf16 v[46:49], v[134:137], v[174:177], v[46:49]
	v_mfma_f32_16x16x32_bf16 v[42:45], v[142:145], v[174:177], v[42:45]
	v_mfma_f32_16x16x32_bf16 v[30:33], v[134:137], v[182:185], v[30:33]
	v_mfma_f32_16x16x32_bf16 v[26:29], v[142:145], v[182:185], v[26:29]
	v_mfma_f32_16x16x32_bf16 v[14:17], v[134:137], v[202:205], v[14:17]
	v_mfma_f32_16x16x32_bf16 v[10:13], v[142:145], v[202:205], v[10:13]
	s_nop 0
	s_nop 0
	v_mfma_f32_16x16x32_bf16 v[54:57], v[146:149], v[162:165], v[54:57]
	v_mfma_f32_16x16x32_bf16 v[50:53], v[154:157], v[162:165], v[50:53]
	v_mfma_f32_16x16x32_bf16 v[38:41], v[146:149], v[170:173], v[38:41]
	v_mfma_f32_16x16x32_bf16 v[34:37], v[154:157], v[170:173], v[34:37]
	v_mfma_f32_16x16x32_bf16 v[22:25], v[146:149], v[178:181], v[22:25]
	v_mfma_f32_16x16x32_bf16 v[18:21], v[154:157], v[178:181], v[18:21]
	v_mfma_f32_16x16x32_bf16 v[6:9], v[146:149], v[198:201], v[6:9]
	v_mfma_f32_16x16x32_bf16 v[2:5], v[154:157], v[198:201], v[2:5]
	v_mfma_f32_16x16x32_bf16 v[54:57], v[150:153], v[166:169], v[54:57]
	v_mfma_f32_16x16x32_bf16 v[50:53], v[158:161], v[166:169], v[50:53]
	v_mfma_f32_16x16x32_bf16 v[38:41], v[150:153], v[174:177], v[38:41]
	v_mfma_f32_16x16x32_bf16 v[34:37], v[158:161], v[174:177], v[34:37]
	v_mfma_f32_16x16x32_bf16 v[22:25], v[150:153], v[182:185], v[22:25]
	v_mfma_f32_16x16x32_bf16 v[18:21], v[158:161], v[182:185], v[18:21]
	v_mfma_f32_16x16x32_bf16 v[6:9], v[150:153], v[202:205], v[6:9]
	v_mfma_f32_16x16x32_bf16 v[2:5], v[158:161], v[202:205], v[2:5]
	s_nop 0
	s_barrier
	s_add_i32 s62, 0, 0x18000
	s_add_i32 s63, 0, 0x1c000
	v_add_u32_e32 v142, s62, v216
	v_add_u32_e32 v158, s63, v216
	ds_read_b128 v[130:133], v142
	ds_read_b128 v[134:137], v142 offset:1024
	ds_read_b128 v[138:141], v142 offset:2048
	ds_read_b128 v[142:145], v142 offset:3072
	ds_read_b128 v[146:149], v158
	ds_read_b128 v[150:153], v158 offset:1024
	ds_read_b128 v[154:157], v158 offset:2048
	ds_read_b128 v[158:161], v158 offset:3072
	s_add_u32 s34, s34, s16
	s_addc_u32 s35, s35, s17
	s_mov_b32 m0, s40
	v_lshl_add_u64 v[242:243], s[34:35], 0, v[186:187]
	ds_read_b128 v[162:165], v218 offset:32768
	ds_read_b128 v[166:169], v218 offset:33792
	ds_read_b128 v[170:173], v218 offset:34816
	ds_read_b128 v[174:177], v218 offset:35840
	ds_read_b128 v[178:181], v218 offset:36864
	ds_read_b128 v[182:185], v218 offset:37888
	ds_read_b128 v[198:201], v218 offset:38912
	ds_read_b128 v[202:205], v218 offset:39936
	global_load_lds_dwordx4 v[242:243], off
	v_lshl_add_u64 v[242:243], s[34:35], 0, v[190:191]
	s_mov_b32 m0, s41
	s_nop 0
	global_load_lds_dwordx4 v[242:243], off
	s_waitcnt vmcnt(8)
	s_waitcnt lgkmcnt(0)
	s_barrier
	s_nop 0
	s_waitcnt lgkmcnt(0)
	v_mfma_f32_16x16x32_bf16 v[126:129], v[130:133], v[162:165], v[126:129]
	v_mfma_f32_16x16x32_bf16 v[122:125], v[138:141], v[162:165], v[122:125]
	v_mfma_f32_16x16x32_bf16 v[110:113], v[130:133], v[170:173], v[110:113]
	v_mfma_f32_16x16x32_bf16 v[106:109], v[138:141], v[170:173], v[106:109]
	v_mfma_f32_16x16x32_bf16 v[94:97], v[130:133], v[178:181], v[94:97]
	v_mfma_f32_16x16x32_bf16 v[90:93], v[138:141], v[178:181], v[90:93]
	v_mfma_f32_16x16x32_bf16 v[78:81], v[130:133], v[198:201], v[78:81]
	v_mfma_f32_16x16x32_bf16 v[74:77], v[138:141], v[198:201], v[74:77]
	v_mfma_f32_16x16x32_bf16 v[126:129], v[134:137], v[166:169], v[126:129]
	v_mfma_f32_16x16x32_bf16 v[122:125], v[142:145], v[166:169], v[122:125]
	v_mfma_f32_16x16x32_bf16 v[110:113], v[134:137], v[174:177], v[110:113]
	v_mfma_f32_16x16x32_bf16 v[106:109], v[142:145], v[174:177], v[106:109]
	v_mfma_f32_16x16x32_bf16 v[94:97], v[134:137], v[182:185], v[94:97]
	v_mfma_f32_16x16x32_bf16 v[90:93], v[142:145], v[182:185], v[90:93]
	v_mfma_f32_16x16x32_bf16 v[78:81], v[134:137], v[202:205], v[78:81]
	v_mfma_f32_16x16x32_bf16 v[74:77], v[142:145], v[202:205], v[74:77]
	s_nop 0
	s_nop 0
	v_mfma_f32_16x16x32_bf16 v[118:121], v[146:149], v[162:165], v[118:121]
	v_mfma_f32_16x16x32_bf16 v[114:117], v[154:157], v[162:165], v[114:117]
	v_mfma_f32_16x16x32_bf16 v[102:105], v[146:149], v[170:173], v[102:105]
	v_mfma_f32_16x16x32_bf16 v[98:101], v[154:157], v[170:173], v[98:101]
	v_mfma_f32_16x16x32_bf16 v[86:89], v[146:149], v[178:181], v[86:89]
	v_mfma_f32_16x16x32_bf16 v[82:85], v[154:157], v[178:181], v[82:85]
	v_mfma_f32_16x16x32_bf16 v[70:73], v[146:149], v[198:201], v[70:73]
	v_mfma_f32_16x16x32_bf16 v[66:69], v[154:157], v[198:201], v[66:69]
	v_mfma_f32_16x16x32_bf16 v[118:121], v[150:153], v[166:169], v[118:121]
	v_mfma_f32_16x16x32_bf16 v[114:117], v[158:161], v[166:169], v[114:117]
	v_mfma_f32_16x16x32_bf16 v[102:105], v[150:153], v[174:177], v[102:105]
	v_mfma_f32_16x16x32_bf16 v[98:101], v[158:161], v[174:177], v[98:101]
	v_mfma_f32_16x16x32_bf16 v[86:89], v[150:153], v[182:185], v[86:89]
	v_mfma_f32_16x16x32_bf16 v[82:85], v[158:161], v[182:185], v[82:85]
	v_mfma_f32_16x16x32_bf16 v[70:73], v[150:153], v[202:205], v[70:73]
	v_mfma_f32_16x16x32_bf16 v[66:69], v[158:161], v[202:205], v[66:69]
	s_nop 0
	s_barrier
; #define PG8_STAGE(bufoff, gbase, voff) do { _Pragma("unroll") for (int _i = 0; _i < 2; ++_i) \
;         __builtin_amdgcn_global_load_lds((const unsigned*)((const char*)(gbase) + (voff)[_i]), (PG8_LAS unsigned*)(lds + (bufoff) + ldsw + _i * 8192), 16, 0, 0); } while (0)
; #define PG8_LDA(dst, b, h) do { _Pragma("unroll") for (int m = 0; m < 4; ++m) _Pragma("unroll") for (int k = 0; k < 2; ++k) dst[m][k] = *(const PG8_LAS bf16x8*)(lds + PG8_SA(b, h) + aoff + m * 2048 + k * 1024); } while (0)
; #define PG8_MMA(ai, bj, At, Bt) do { __builtin_amdgcn_s_setprio(1); _Pragma("unroll") for (int m = 0; m < 4; ++m) _Pragma("unroll") for (int n = 0; n < 2; ++n) _Pragma("unroll") for (int k = 0; k < 2; ++k) \
;         acc[ai][bj][m][n] = __builtin_amdgcn_mfma_f32_16x16x32_bf16(Bt[n][k], At[m][k], acc[ai][bj][m][n], 0, 0, 0); __builtin_amdgcn_s_setprio(0); } while (0)
; #define PG8_WAIT_V(n) asm volatile("s_waitcnt vmcnt(" #n ")" ::: "memory")
; #define PG8_WAIT_L(n) asm volatile("s_waitcnt lgkmcnt(" #n ")" ::: "memory")
; #define PG8_BAR __builtin_amdgcn_s_barrier()
; #define PG8_SCHED __builtin_amdgcn_sched_barrier(0)
; template <class Epi, class Sched, bool ALIGN_EPI = false, bool SP2 = false>
; __device__ __forceinline__ void gemm_phase(PG8_LAS unsigned char* lds, const Gemm g, const Sched& S, const Epi& E) {
;     ...
;         for (int t = 0; t < nt; t += 2) {
;             const bool last = (t == nt - 2);
;             const char* a1 = cA + (size_t)(t + 1) * kstep;
;             const char* a2 = last ? nA : cA + (size_t)(t + 2) * kstep; const char* b2 = last ? nB : cB + (size_t)(t + 2) * kstep;
;             const char* a3 = a2 + kstep; const char* b3 = b2 + kstep;
;     ...
;             PG8_LDA(At, 1, 1); PG8_STAGE(PG8_SB(1, 0), b3, voffB); PG8_STAGE(PG8_SB(1, 1), b3 + hstep, voffB); PG8_STAGE(PG8_SA(1, 0), a3, voffA);
;             PG8_WAIT_V(8); PG8_WAIT_L(0); PG8_BAR; PG8_MMA(1, 0, At, B0); PG8_MMA(1, 1, At, B1); PG8_BAR; PG8_SCHED;
	s_add_i32 s34, s62, s37
	v_lshl_add_u64 v[206:207], v[206:207], 0, s[92:93]
	s_mov_b32 m0, s34
	ds_read_b128 v[162:165], v218 offset:49152
	ds_read_b128 v[166:169], v218 offset:50176
	ds_read_b128 v[170:173], v218 offset:51200
	ds_read_b128 v[174:177], v218 offset:52224
	ds_read_b128 v[178:181], v218 offset:53248
	ds_read_b128 v[182:185], v218 offset:54272
	ds_read_b128 v[198:201], v218 offset:55296
	ds_read_b128 v[202:205], v218 offset:56320
	global_load_lds_dwordx4 v[206:207], off
	v_lshl_add_u64 v[206:207], v[208:209], 0, s[92:93]
	s_add_i32 m0, s34, 0x2000
	s_add_i32 s34, s63, s37
	global_load_lds_dwordx4 v[206:207], off
	v_lshl_add_u64 v[206:207], v[210:211], 0, s[92:93]
	s_mov_b32 m0, s34
	s_nop 0
	global_load_lds_dwordx4 v[206:207], off
	v_lshl_add_u64 v[206:207], v[212:213], 0, s[92:93]
	s_add_i32 m0, s34, 0x2000
	s_nop 0
	global_load_lds_dwordx4 v[206:207], off
	v_lshl_add_u64 v[206:207], v[214:215], 0, s[92:93]
	s_mov_b32 m0, s42
	s_nop 0
	global_load_lds_dwordx4 v[206:207], off
	v_lshl_add_u64 v[206:207], v[228:229], 0, s[92:93]
	s_mov_b32 m0, s43
	s_nop 0
	global_load_lds_dwordx4 v[206:207], off
	s_waitcnt vmcnt(8)
	s_waitcnt lgkmcnt(0)
	s_barrier
	s_nop 0
	s_waitcnt lgkmcnt(0)
	v_mfma_f32_16x16x32_bf16 v[62:65], v[130:133], v[162:165], v[62:65]
	v_mfma_f32_16x16x32_bf16 v[58:61], v[138:141], v[162:165], v[58:61]
	v_mfma_f32_16x16x32_bf16 v[46:49], v[130:133], v[170:173], v[46:49]
	v_mfma_f32_16x16x32_bf16 v[42:45], v[138:141], v[170:173], v[42:45]
	v_mfma_f32_16x16x32_bf16 v[30:33], v[130:133], v[178:181], v[30:33]
	v_mfma_f32_16x16x32_bf16 v[26:29], v[138:141], v[178:181], v[26:29]
	v_mfma_f32_16x16x32_bf16 v[14:17], v[130:133], v[198:201], v[14:17]
	v_mfma_f32_16x16x32_bf16 v[10:13], v[138:141], v[198:201], v[10:13]
	v_mfma_f32_16x16x32_bf16 v[62:65], v[134:137], v[166:169], v[62:65]
	v_mfma_f32_16x16x32_bf16 v[58:61], v[142:145], v[166:169], v[58:61]
	v_mfma_f32_16x16x32_bf16 v[46:49], v[134:137], v[174:177], v[46:49]
	v_mfma_f32_16x16x32_bf16 v[42:45], v[142:145], v[174:177], v[42:45]
	v_mfma_f32_16x16x32_bf16 v[30:33], v[134:137], v[182:185], v[30:33]
	v_mfma_f32_16x16x32_bf16 v[26:29], v[142:145], v[182:185], v[26:29]
	v_mfma_f32_16x16x32_bf16 v[14:17], v[134:137], v[202:205], v[14:17]
	v_mfma_f32_16x16x32_bf16 v[10:13], v[142:145], v[202:205], v[10:13]
	s_nop 0
	s_nop 0
	v_mfma_f32_16x16x32_bf16 v[54:57], v[146:149], v[162:165], v[54:57]
	v_mfma_f32_16x16x32_bf16 v[50:53], v[154:157], v[162:165], v[50:53]
	v_mfma_f32_16x16x32_bf16 v[38:41], v[146:149], v[170:173], v[38:41]
	v_mfma_f32_16x16x32_bf16 v[34:37], v[154:157], v[170:173], v[34:37]
	v_mfma_f32_16x16x32_bf16 v[22:25], v[146:149], v[178:181], v[22:25]
	v_mfma_f32_16x16x32_bf16 v[18:21], v[154:157], v[178:181], v[18:21]
	v_mfma_f32_16x16x32_bf16 v[6:9], v[146:149], v[198:201], v[6:9]
	v_mfma_f32_16x16x32_bf16 v[2:5], v[154:157], v[198:201], v[2:5]
	v_mfma_f32_16x16x32_bf16 v[54:57], v[150:153], v[166:169], v[54:57]
	v_mfma_f32_16x16x32_bf16 v[50:53], v[158:161], v[166:169], v[50:53]
	v_mfma_f32_16x16x32_bf16 v[38:41], v[150:153], v[174:177], v[38:41]
	v_mfma_f32_16x16x32_bf16 v[34:37], v[158:161], v[174:177], v[34:37]
	v_mfma_f32_16x16x32_bf16 v[22:25], v[150:153], v[182:185], v[22:25]
	v_mfma_f32_16x16x32_bf16 v[18:21], v[158:161], v[182:185], v[18:21]
	v_mfma_f32_16x16x32_bf16 v[6:9], v[150:153], v[202:205], v[6:9]
	v_mfma_f32_16x16x32_bf16 v[2:5], v[158:161], v[202:205], v[2:5]
	s_nop 0
	s_barrier
	s_add_u32 s59, s59, 0x100
	s_addc_u32 s60, s60, 0
	s_add_u32 s30, s30, 0x100
	s_addc_u32 s31, s31, 0
	s_cmp_ge_i32 s61, s45
	s_mov_b32 s34, s61
	s_cbranch_scc0 .LBB0_3989

; #define PG8_WAIT_V(n) asm volatile("s_waitcnt vmcnt(" #n ")" ::: "memory")
; #define PG8_BAR __builtin_amdgcn_s_barrier()
; __device__ __forceinline__ unsigned xb_add(unsigned* p, unsigned v) { return __hip_atomic_fetch_add(p, v, __ATOMIC_RELAXED, __HIP_MEMORY_SCOPE_AGENT); }
; template <class Epi, class Sched, bool ALIGN_EPI = false, bool SP2 = false>
; __device__ __forceinline__ void gemm_phase(PG8_LAS unsigned char* lds, const Gemm g, const Sched& S, const Epi& E) {
;     ...
;     PG8_WAIT_V(0);
;     if constexpr (!ALIGN_EPI) { if (wr == 0) PG8_BAR; }
;     PG8_BAR;
; __device__ __forceinline__ void xcd_barrier(const XcdBarrier& b) {
;     asm volatile("s_waitcnt vmcnt(0)" ::: "memory");
;     __syncthreads();
;     if (b.tid == 0u) {
;         unsigned* bar = b.bar;
;         __builtin_amdgcn_s_waitcnt(0);
;         unsigned nloc = b.st[0], nx = b.st[1];
;         if (nloc == 0u) { xcd_barrier_complete(bar, b.x, nloc, nx); b.st[0] = nloc; b.st[1] = nx; }
;         const unsigned old = xb_add(&bar[XB_XSUB(b.x)], 1u);
.LBB0_4012:
	s_mov_b64 s[2:3], s[88:89]
	s_getreg_b32 s4, hwreg(HW_REG_XCC_ID, 0, 4)
	s_waitcnt vmcnt(0)
	s_waitcnt lgkmcnt(0)
	s_setprio 0
	s_barrier
	s_mov_b64 s[0:1], exec
	v_readlane_b32 s6, v252, 2
	v_readlane_b32 s7, v252, 3
	s_and_b64 s[6:7], s[0:1], s[6:7]
	s_movk_i32 s29, 0x600
	s_mov_b32 s34, 0x5ffff
	s_movk_i32 s35, 0xffe8
	s_mov_b64 s[36:37], 0x8c00340
	s_mov_b64 exec, s[6:7]
	s_cbranch_execz .LBB0_4064
	v_readlane_b32 s5, v252, 13
	s_load_dwordx2 s[2:3], s[2:3], 0x100
	s_waitcnt vmcnt(0) expcnt(0) lgkmcnt(0)
	v_mov_b32_e32 v1, s5
	ds_read_b32 v3, v1
	v_readlane_b32 s5, v252, 14
	s_and_b32 s46, s4, 15
	s_waitcnt lgkmcnt(0)
	v_cmp_ne_u32_e32 vcc, 0, v3
	v_mov_b32_e32 v1, s5
	ds_read_b32 v2, v1
	s_cbranch_vccnz .LBB0_4028
	s_add_u32 s4, s2, 0x17900200
	s_addc_u32 s5, s3, 0
	s_add_u32 s6, s2, 0x17900400
	s_addc_u32 s7, s3, 0
	s_add_u32 s8, s2, 0x17900500
	s_addc_u32 s9, s3, 0
	s_add_u32 s10, s2, 0x17900600
	s_addc_u32 s11, s3, 0
	s_add_u32 s12, s2, 0x17900700
	s_addc_u32 s13, s3, 0
	s_add_u32 s14, s2, 0x17900800
	s_addc_u32 s15, s3, 0
	s_add_u32 s16, s2, 0x17900900
	s_addc_u32 s17, s3, 0
	s_add_u32 s18, s2, 0x17900a00
	s_addc_u32 s19, s3, 0
	s_add_u32 s20, s2, 0x17900b00
	s_addc_u32 s21, s3, 0
	s_add_u32 s22, s2, 0x17900c00
	s_addc_u32 s23, s3, 0
	s_add_u32 s24, s2, 0x17900d00
	s_addc_u32 s25, s3, 0
	s_add_u32 s26, s2, 0x17900e00
	s_addc_u32 s27, s3, 0
	s_add_u32 s28, s2, 0x17900f00
	s_addc_u32 s29, s3, 0
	s_add_u32 s30, s2, 0x17901000
	s_addc_u32 s31, s3, 0
	s_add_u32 s34, s2, 0x17901100
	s_addc_u32 s35, s3, 0
	s_add_u32 s36, s2, 0x17901200
	s_addc_u32 s37, s3, 0
	s_add_u32 s38, s2, 0x17901300
	s_addc_u32 s39, s3, 0
	s_mov_b32 s47, 1
	s_branch .LBB0_4016

; #define KA_DEF const __attribute__((address_space(4))) KArgs* ka_ = (const __attribute__((address_space(4))) KArgs*)__builtin_amdgcn_kernarg_segment_ptr(); asm volatile("" : "+s"(ka_));
;     __host__ __device__ bool next(int i, Unit& u) const {
;         const long L = (long)i * G + c; if (L >= nwg) return false;
;         int wgid = (int)L; { const int q = nwg / NXCD, r = nwg % NXCD, xcd = wgid % NXCD, off = wgid / NXCD; wgid = (xcd < r ? xcd * (q + 1) : r * (q + 1) + (xcd - r) * q) + off; }
;         const int nig = WGM * nN, gid = wgid / nig, fm = gid * WGM, gsz = (nM - fm) < WGM ? (nM - fm) : WGM;
;         u.pm = fm + ((wgid % nig) % gsz); u.pn = (wgid % nig) / gsz; return true;
; __global__ void __launch_bounds__(512, 2) mega_fwd(KArgs a) {
;     ...
;             { KA_DEF pg8::EpiBf16S E{RA, 1792, nullptr}; run_gemm(TIDX, lds, CQKV, Wl + WO_BD, T_, 1792, 384, E); }
.Lmy_prio_skip_12:
	s_load_dwordx2 s[4:5], s[0:1], 0x100
	s_movk_i32 s0, 0x180
	s_movk_i32 s1, 0x700
	s_movk_i32 s10, 0x4000
	s_waitcnt lgkmcnt(0)
	s_add_u32 s6, s4, 0x16c00000
	s_addc_u32 s7, s5, 0
	s_add_u32 s8, s4, 0x2a80000
	s_addc_u32 s9, s5, 0
	s_ashr_i32 s11, s10, 31
	s_lshr_b32 s11, s11, 24
	s_add_i32 s10, s10, s11
	s_ashr_i32 s30, s10, 8
	s_ashr_i32 s10, s1, 31
	s_lshr_b32 s10, s10, 24
	s_add_i32 s1, s1, s10
	s_ashr_i32 s16, s1, 8
	s_mul_i32 s10, s16, s30
	v_mov_b32_e32 v14, v220
	s_cmp_ge_i32 s86, s10
	v_readfirstlane_b32 s22, v14
	s_cbranch_scc1 .LBB0_4171
	s_ashr_i32 s11, s10, 31
	s_lshr_b32 s1, s11, 29
	s_add_i32 s1, s10, s1
	s_ashr_i32 s31, s1, 3
	s_and_b32 s1, s1, -8
	s_sub_i32 s34, s10, s1
	s_add_i32 s35, s31, 1
	v_readlane_b32 s1, v252, 5
	s_cmp_ge_i32 s1, s34
	s_mov_b64 s[12:13], -1
	s_mul_i32 s36, s35, s34
	s_cbranch_scc0 .LBB0_4145
	v_readlane_b32 s1, v252, 5
	s_sub_i32 s1, s1, s34
	s_mul_i32 s1, s1, s31
	s_add_i32 s17, s1, s36
	s_mov_b64 s[12:13], 0

; #define PG8_STAGE(bufoff, gbase, voff) do { _Pragma("unroll") for (int _i = 0; _i < 2; ++_i) \
;         __builtin_amdgcn_global_load_lds((const unsigned*)((const char*)(gbase) + (voff)[_i]), (PG8_LAS unsigned*)(lds + (bufoff) + ldsw + _i * 8192), 16, 0, 0); } while (0)
; #define PG8_LDA(dst, b, h) do { _Pragma("unroll") for (int m = 0; m < 4; ++m) _Pragma("unroll") for (int k = 0; k < 2; ++k) dst[m][k] = *(const PG8_LAS bf16x8*)(lds + PG8_SA(b, h) + aoff + m * 2048 + k * 1024); } while (0)
; #define PG8_LDB(dst, b, h) do { _Pragma("unroll") for (int n = 0; n < 2; ++n) _Pragma("unroll") for (int k = 0; k < 2; ++k) dst[n][k] = *(const PG8_LAS bf16x8*)(lds + PG8_SB(b, h) + boff + n * 2048 + k * 1024); } while (0)
; #define PG8_MMA(ai, bj, At, Bt) do { __builtin_amdgcn_s_setprio(1); _Pragma("unroll") for (int m = 0; m < 4; ++m) _Pragma("unroll") for (int n = 0; n < 2; ++n) _Pragma("unroll") for (int k = 0; k < 2; ++k) \
;         acc[ai][bj][m][n] = __builtin_amdgcn_mfma_f32_16x16x32_bf16(Bt[n][k], At[m][k], acc[ai][bj][m][n], 0, 0, 0); __builtin_amdgcn_s_setprio(0); } while (0)
; #define PG8_WAIT_V(n) asm volatile("s_waitcnt vmcnt(" #n ")" ::: "memory")
; #define PG8_WAIT_L(n) asm volatile("s_waitcnt lgkmcnt(" #n ")" ::: "memory")
; #define PG8_BAR __builtin_amdgcn_s_barrier()
; #define PG8_SCHED __builtin_amdgcn_sched_barrier(0)
; template <class Epi, class Sched, bool ALIGN_EPI = false, bool SP2 = false>
; __device__ __forceinline__ void gemm_phase(PG8_LAS unsigned char* lds, const Gemm g, const Sched& S, const Epi& E) {
;     ...
;             const bool last = (t == nt - 2);
;             const char* a1 = cA + (size_t)(t + 1) * kstep;
;             const char* a2 = last ? nA : cA + (size_t)(t + 2) * kstep; const char* b2 = last ? nB : cB + (size_t)(t + 2) * kstep;
;             const char* a3 = a2 + kstep; const char* b3 = b2 + kstep;
;             if (last && has_next) S.a_ready(nxt);
;             if constexpr (SP2) {
;             PG8_LDB(B0, 0, 0); PG8_LDB(B1, 0, 1); PG8_SCHED; PG8_LDA(At, 0, 0); PG8_STAGE(PG8_SA(1, 1), a1 + hstep, voffA);
;             PG8_WAIT_V(8); PG8_WAIT_L(0); PG8_BAR; PG8_MMA(0, 0, At, B0); PG8_MMA(0, 1, At, B1); PG8_BAR; PG8_SCHED;
;             PG8_LDA(At, 0, 1); PG8_STAGE(PG8_SB(0, 0), b2, voffB); PG8_STAGE(PG8_SB(0, 1), b2 + hstep, voffB); PG8_STAGE(PG8_SA(0, 0), a2, voffA);
.LBB0_4164:
	s_add_i32 s57, s28, 2
	s_add_u32 s58, s26, 0x80
	s_addc_u32 s29, s27, 0
	s_add_i32 s60, 0, 0x10000
	s_cmp_eq_u32 s51, s28
	s_cselect_b32 s29, s1, s29
	s_cselect_b32 s28, s0, s58
	v_add_u32_e32 v145, s60, v142
	s_cselect_b32 s59, s25, s56
	s_cselect_b32 s58, s24, s55
	s_add_i32 s61, 0, 0x14000
	ds_read_b128 v[146:149], v145
	ds_read_b128 v[150:153], v145 offset:1024
	ds_read_b128 v[154:157], v145 offset:2048
	ds_read_b128 v[158:161], v145 offset:3072
	v_add_u32_e32 v145, s61, v142
	ds_read_b128 v[162:165], v145
	ds_read_b128 v[166:169], v145 offset:1024
	ds_read_b128 v[170:173], v145 offset:2048
	ds_read_b128 v[174:177], v145 offset:3072
	v_lshl_add_u64 v[210:211], s[26:27], 0, v[140:141]
	s_add_i32 m0, s42, 0xc000
	ds_read_b128 v[178:181], v144
	ds_read_b128 v[182:185], v144 offset:1024
	ds_read_b128 v[186:189], v144 offset:2048
	ds_read_b128 v[190:193], v144 offset:3072
	ds_read_b128 v[194:197], v144 offset:4096
	ds_read_b128 v[198:201], v144 offset:5120
	ds_read_b128 v[202:205], v144 offset:6144
	ds_read_b128 v[206:209], v144 offset:7168
	global_load_lds_dwordx4 v[210:211], off
	v_lshl_add_u64 v[210:211], s[26:27], 0, v[138:139]
	s_add_i32 m0, s42, 0xe000
	s_nop 0
	global_load_lds_dwordx4 v[210:211], off
	s_waitcnt vmcnt(8)
	s_waitcnt lgkmcnt(0)
	s_barrier
	s_nop 0
	s_waitcnt lgkmcnt(0)
	v_mfma_f32_16x16x32_bf16 v[122:125], v[146:149], v[178:181], v[122:125]
	v_mfma_f32_16x16x32_bf16 v[126:129], v[154:157], v[178:181], v[126:129]
	v_mfma_f32_16x16x32_bf16 v[110:113], v[146:149], v[186:189], v[110:113]
	v_mfma_f32_16x16x32_bf16 v[106:109], v[154:157], v[186:189], v[106:109]
	v_mfma_f32_16x16x32_bf16 v[94:97], v[146:149], v[194:197], v[94:97]
	v_mfma_f32_16x16x32_bf16 v[90:93], v[154:157], v[194:197], v[90:93]
	v_mfma_f32_16x16x32_bf16 v[78:81], v[146:149], v[202:205], v[78:81]
	v_mfma_f32_16x16x32_bf16 v[74:77], v[154:157], v[202:205], v[74:77]
	v_mfma_f32_16x16x32_bf16 v[122:125], v[150:153], v[182:185], v[122:125]
	v_mfma_f32_16x16x32_bf16 v[126:129], v[158:161], v[182:185], v[126:129]
	v_mfma_f32_16x16x32_bf16 v[110:113], v[150:153], v[190:193], v[110:113]
	v_mfma_f32_16x16x32_bf16 v[106:109], v[158:161], v[190:193], v[106:109]
	v_mfma_f32_16x16x32_bf16 v[94:97], v[150:153], v[198:201], v[94:97]
	v_mfma_f32_16x16x32_bf16 v[90:93], v[158:161], v[198:201], v[90:93]
	v_mfma_f32_16x16x32_bf16 v[78:81], v[150:153], v[206:209], v[78:81]
	v_mfma_f32_16x16x32_bf16 v[74:77], v[158:161], v[206:209], v[74:77]
	s_nop 0
	s_nop 0
	v_mfma_f32_16x16x32_bf16 v[118:121], v[162:165], v[178:181], v[118:121]
	v_mfma_f32_16x16x32_bf16 v[114:117], v[170:173], v[178:181], v[114:117]
	v_mfma_f32_16x16x32_bf16 v[102:105], v[162:165], v[186:189], v[102:105]
	v_mfma_f32_16x16x32_bf16 v[98:101], v[170:173], v[186:189], v[98:101]
	v_mfma_f32_16x16x32_bf16 v[86:89], v[162:165], v[194:197], v[86:89]
	v_mfma_f32_16x16x32_bf16 v[82:85], v[170:173], v[194:197], v[82:85]
	v_mfma_f32_16x16x32_bf16 v[70:73], v[162:165], v[202:205], v[70:73]
	v_mfma_f32_16x16x32_bf16 v[66:69], v[170:173], v[202:205], v[66:69]
	v_mfma_f32_16x16x32_bf16 v[118:121], v[166:169], v[182:185], v[118:121]
	v_mfma_f32_16x16x32_bf16 v[114:117], v[174:177], v[182:185], v[114:117]
	v_mfma_f32_16x16x32_bf16 v[102:105], v[166:169], v[190:193], v[102:105]
	v_mfma_f32_16x16x32_bf16 v[98:101], v[174:177], v[190:193], v[98:101]
	v_mfma_f32_16x16x32_bf16 v[86:89], v[166:169], v[198:201], v[86:89]
	v_mfma_f32_16x16x32_bf16 v[82:85], v[174:177], v[198:201], v[82:85]
	v_mfma_f32_16x16x32_bf16 v[70:73], v[166:169], v[206:209], v[70:73]
	v_mfma_f32_16x16x32_bf16 v[66:69], v[174:177], v[206:209], v[66:69]
	s_nop 0
	s_barrier
	s_add_i32 s60, s60, s37
	v_lshl_add_u64 v[210:211], s[58:59], 0, v[132:133]
	s_mov_b32 m0, s60
	ds_read_b128 v[178:181], v144 offset:16384
	ds_read_b128 v[182:185], v144 offset:17408
	ds_read_b128 v[186:189], v144 offset:18432
	ds_read_b128 v[190:193], v144 offset:19456
	ds_read_b128 v[194:197], v144 offset:20480
	ds_read_b128 v[198:201], v144 offset:21504
	ds_read_b128 v[202:205], v144 offset:22528
	ds_read_b128 v[206:209], v144 offset:23552
	global_load_lds_dwordx4 v[210:211], off
	s_add_i32 m0, s60, 0x2000
	v_lshl_add_u64 v[212:213], s[58:59], 0, v[136:137]
	s_add_u32 s58, s58, s12
	s_addc_u32 s59, s59, s13
	s_add_i32 s60, s61, s37
	global_load_lds_dwordx4 v[212:213], off
	v_lshl_add_u64 v[214:215], s[58:59], 0, v[132:133]
	s_mov_b32 m0, s60
	v_lshl_add_u64 v[216:217], s[58:59], 0, v[136:137]
	global_load_lds_dwordx4 v[214:215], off
	s_add_i32 m0, s60, 0x2000
	v_lshl_add_u64 v[218:219], s[28:29], 0, v[130:131]
	global_load_lds_dwordx4 v[216:217], off
	s_mov_b32 m0, s42
	v_lshl_add_u64 v[228:229], s[28:29], 0, v[134:135]
	global_load_lds_dwordx4 v[218:219], off
	s_mov_b32 m0, s43
	s_nop 0
	global_load_lds_dwordx4 v[228:229], off
	s_waitcnt vmcnt(8)
	s_waitcnt lgkmcnt(0)
	s_barrier
; #define PG8_STAGE(bufoff, gbase, voff) do { _Pragma("unroll") for (int _i = 0; _i < 2; ++_i) \
;         __builtin_amdgcn_global_load_lds((const unsigned*)((const char*)(gbase) + (voff)[_i]), (PG8_LAS unsigned*)(lds + (bufoff) + ldsw + _i * 8192), 16, 0, 0); } while (0)
; #define PG8_LDA(dst, b, h) do { _Pragma("unroll") for (int m = 0; m < 4; ++m) _Pragma("unroll") for (int k = 0; k < 2; ++k) dst[m][k] = *(const PG8_LAS bf16x8*)(lds + PG8_SA(b, h) + aoff + m * 2048 + k * 1024); } while (0)
; #define PG8_LDB(dst, b, h) do { _Pragma("unroll") for (int n = 0; n < 2; ++n) _Pragma("unroll") for (int k = 0; k < 2; ++k) dst[n][k] = *(const PG8_LAS bf16x8*)(lds + PG8_SB(b, h) + boff + n * 2048 + k * 1024); } while (0)
; #define PG8_MMA(ai, bj, At, Bt) do { __builtin_amdgcn_s_setprio(1); _Pragma("unroll") for (int m = 0; m < 4; ++m) _Pragma("unroll") for (int n = 0; n < 2; ++n) _Pragma("unroll") for (int k = 0; k < 2; ++k) \
;         acc[ai][bj][m][n] = __builtin_amdgcn_mfma_f32_16x16x32_bf16(Bt[n][k], At[m][k], acc[ai][bj][m][n], 0, 0, 0); __builtin_amdgcn_s_setprio(0); } while (0)
; #define PG8_WAIT_V(n) asm volatile("s_waitcnt vmcnt(" #n ")" ::: "memory")
; #define PG8_WAIT_L(n) asm volatile("s_waitcnt lgkmcnt(" #n ")" ::: "memory")
; #define PG8_BAR __builtin_amdgcn_s_barrier()
; #define PG8_SCHED __builtin_amdgcn_sched_barrier(0)
; template <class Epi, class Sched, bool ALIGN_EPI = false, bool SP2 = false>
; __device__ __forceinline__ void gemm_phase(PG8_LAS unsigned char* lds, const Gemm g, const Sched& S, const Epi& E) {
;     ...
;             PG8_WAIT_V(8); PG8_WAIT_L(0); PG8_BAR; PG8_MMA(1, 0, At, B0); PG8_MMA(1, 1, At, B1); PG8_BAR; PG8_SCHED;
;             PG8_LDB(B0, 1, 0); PG8_LDB(B1, 1, 1); PG8_SCHED; PG8_LDA(At, 1, 0); PG8_STAGE(PG8_SA(0, 1), a2 + hstep, voffA);
;             PG8_WAIT_V(8); PG8_WAIT_L(0); PG8_BAR; PG8_MMA(0, 0, At, B0); PG8_MMA(0, 1, At, B1); PG8_BAR; PG8_SCHED;
	s_nop 0
	s_waitcnt lgkmcnt(0)
	v_mfma_f32_16x16x32_bf16 v[62:65], v[146:149], v[178:181], v[62:65]
	v_mfma_f32_16x16x32_bf16 v[58:61], v[154:157], v[178:181], v[58:61]
	v_mfma_f32_16x16x32_bf16 v[46:49], v[146:149], v[186:189], v[46:49]
	v_mfma_f32_16x16x32_bf16 v[42:45], v[154:157], v[186:189], v[42:45]
	v_mfma_f32_16x16x32_bf16 v[30:33], v[146:149], v[194:197], v[30:33]
	v_mfma_f32_16x16x32_bf16 v[26:29], v[154:157], v[194:197], v[26:29]
	v_mfma_f32_16x16x32_bf16 v[14:17], v[146:149], v[202:205], v[14:17]
	v_mfma_f32_16x16x32_bf16 v[10:13], v[154:157], v[202:205], v[10:13]
	v_mfma_f32_16x16x32_bf16 v[62:65], v[150:153], v[182:185], v[62:65]
	v_mfma_f32_16x16x32_bf16 v[58:61], v[158:161], v[182:185], v[58:61]
	v_mfma_f32_16x16x32_bf16 v[46:49], v[150:153], v[190:193], v[46:49]
	v_mfma_f32_16x16x32_bf16 v[42:45], v[158:161], v[190:193], v[42:45]
	v_mfma_f32_16x16x32_bf16 v[30:33], v[150:153], v[198:201], v[30:33]
	v_mfma_f32_16x16x32_bf16 v[26:29], v[158:161], v[198:201], v[26:29]
	v_mfma_f32_16x16x32_bf16 v[14:17], v[150:153], v[206:209], v[14:17]
	v_mfma_f32_16x16x32_bf16 v[10:13], v[158:161], v[206:209], v[10:13]
	s_nop 0
	s_nop 0
	v_mfma_f32_16x16x32_bf16 v[54:57], v[162:165], v[178:181], v[54:57]
	v_mfma_f32_16x16x32_bf16 v[50:53], v[170:173], v[178:181], v[50:53]
	v_mfma_f32_16x16x32_bf16 v[38:41], v[162:165], v[186:189], v[38:41]
	v_mfma_f32_16x16x32_bf16 v[34:37], v[170:173], v[186:189], v[34:37]
	v_mfma_f32_16x16x32_bf16 v[22:25], v[162:165], v[194:197], v[22:25]
	v_mfma_f32_16x16x32_bf16 v[18:21], v[170:173], v[194:197], v[18:21]
	v_mfma_f32_16x16x32_bf16 v[6:9], v[162:165], v[202:205], v[6:9]
	v_mfma_f32_16x16x32_bf16 v[2:5], v[170:173], v[202:205], v[2:5]
	v_mfma_f32_16x16x32_bf16 v[54:57], v[166:169], v[182:185], v[54:57]
	v_mfma_f32_16x16x32_bf16 v[50:53], v[174:177], v[182:185], v[50:53]
	v_mfma_f32_16x16x32_bf16 v[38:41], v[166:169], v[190:193], v[38:41]
	v_mfma_f32_16x16x32_bf16 v[34:37], v[174:177], v[190:193], v[34:37]
	v_mfma_f32_16x16x32_bf16 v[22:25], v[166:169], v[198:201], v[22:25]
	v_mfma_f32_16x16x32_bf16 v[18:21], v[174:177], v[198:201], v[18:21]
	v_mfma_f32_16x16x32_bf16 v[6:9], v[166:169], v[206:209], v[6:9]
	v_mfma_f32_16x16x32_bf16 v[2:5], v[174:177], v[206:209], v[2:5]
	s_nop 0
	s_barrier
	s_add_i32 s58, 0, 0x18000
	v_add_u32_e32 v145, s58, v142
	s_add_i32 s59, 0, 0x1c000
	ds_read_b128 v[146:149], v145
	ds_read_b128 v[150:153], v145 offset:1024
	ds_read_b128 v[154:157], v145 offset:2048
	ds_read_b128 v[158:161], v145 offset:3072
	v_add_u32_e32 v145, s59, v142
	ds_read_b128 v[162:165], v145
	ds_read_b128 v[166:169], v145 offset:1024
	ds_read_b128 v[170:173], v145 offset:2048
	ds_read_b128 v[174:177], v145 offset:3072
	s_add_u32 s28, s28, s12
	s_addc_u32 s29, s29, s13
	s_mov_b32 m0, s44
	v_lshl_add_u64 v[242:243], s[28:29], 0, v[130:131]
	ds_read_b128 v[178:181], v144 offset:32768
	ds_read_b128 v[182:185], v144 offset:33792
	ds_read_b128 v[186:189], v144 offset:34816
	ds_read_b128 v[190:193], v144 offset:35840
	ds_read_b128 v[194:197], v144 offset:36864
	ds_read_b128 v[198:201], v144 offset:37888
	ds_read_b128 v[202:205], v144 offset:38912
	ds_read_b128 v[206:209], v144 offset:39936
	global_load_lds_dwordx4 v[242:243], off
	v_lshl_add_u64 v[242:243], s[28:29], 0, v[134:135]
	s_mov_b32 m0, s45
	s_nop 0
	global_load_lds_dwordx4 v[242:243], off
	s_waitcnt vmcnt(8)
	s_waitcnt lgkmcnt(0)
	s_barrier
	s_nop 0
	s_waitcnt lgkmcnt(0)
	v_mfma_f32_16x16x32_bf16 v[122:125], v[146:149], v[178:181], v[122:125]
	v_mfma_f32_16x16x32_bf16 v[126:129], v[154:157], v[178:181], v[126:129]
	v_mfma_f32_16x16x32_bf16 v[110:113], v[146:149], v[186:189], v[110:113]
	v_mfma_f32_16x16x32_bf16 v[106:109], v[154:157], v[186:189], v[106:109]
	v_mfma_f32_16x16x32_bf16 v[94:97], v[146:149], v[194:197], v[94:97]
	v_mfma_f32_16x16x32_bf16 v[90:93], v[154:157], v[194:197], v[90:93]
	v_mfma_f32_16x16x32_bf16 v[78:81], v[146:149], v[202:205], v[78:81]
	v_mfma_f32_16x16x32_bf16 v[74:77], v[154:157], v[202:205], v[74:77]
	v_mfma_f32_16x16x32_bf16 v[122:125], v[150:153], v[182:185], v[122:125]
	v_mfma_f32_16x16x32_bf16 v[126:129], v[158:161], v[182:185], v[126:129]
	v_mfma_f32_16x16x32_bf16 v[110:113], v[150:153], v[190:193], v[110:113]
	v_mfma_f32_16x16x32_bf16 v[106:109], v[158:161], v[190:193], v[106:109]
	v_mfma_f32_16x16x32_bf16 v[94:97], v[150:153], v[198:201], v[94:97]
	v_mfma_f32_16x16x32_bf16 v[90:93], v[158:161], v[198:201], v[90:93]
	v_mfma_f32_16x16x32_bf16 v[78:81], v[150:153], v[206:209], v[78:81]
	v_mfma_f32_16x16x32_bf16 v[74:77], v[158:161], v[206:209], v[74:77]
	s_nop 0
	s_nop 0
	v_mfma_f32_16x16x32_bf16 v[118:121], v[162:165], v[178:181], v[118:121]
	v_mfma_f32_16x16x32_bf16 v[114:117], v[170:173], v[178:181], v[114:117]
	v_mfma_f32_16x16x32_bf16 v[102:105], v[162:165], v[186:189], v[102:105]
	v_mfma_f32_16x16x32_bf16 v[98:101], v[170:173], v[186:189], v[98:101]
	v_mfma_f32_16x16x32_bf16 v[86:89], v[162:165], v[194:197], v[86:89]
	v_mfma_f32_16x16x32_bf16 v[82:85], v[170:173], v[194:197], v[82:85]
	v_mfma_f32_16x16x32_bf16 v[70:73], v[162:165], v[202:205], v[70:73]
	v_mfma_f32_16x16x32_bf16 v[66:69], v[170:173], v[202:205], v[66:69]
	v_mfma_f32_16x16x32_bf16 v[118:121], v[166:169], v[182:185], v[118:121]
	v_mfma_f32_16x16x32_bf16 v[114:117], v[174:177], v[182:185], v[114:117]
	v_mfma_f32_16x16x32_bf16 v[102:105], v[166:169], v[190:193], v[102:105]
	v_mfma_f32_16x16x32_bf16 v[98:101], v[174:177], v[190:193], v[98:101]
	v_mfma_f32_16x16x32_bf16 v[86:89], v[166:169], v[198:201], v[86:89]
	v_mfma_f32_16x16x32_bf16 v[82:85], v[174:177], v[198:201], v[82:85]
	v_mfma_f32_16x16x32_bf16 v[70:73], v[166:169], v[206:209], v[70:73]
	v_mfma_f32_16x16x32_bf16 v[66:69], v[174:177], v[206:209], v[66:69]
	s_nop 0
	s_barrier
; #define PG8_STAGE(bufoff, gbase, voff) do { _Pragma("unroll") for (int _i = 0; _i < 2; ++_i) \
;         __builtin_amdgcn_global_load_lds((const unsigned*)((const char*)(gbase) + (voff)[_i]), (PG8_LAS unsigned*)(lds + (bufoff) + ldsw + _i * 8192), 16, 0, 0); } while (0)
; #define PG8_LDA(dst, b, h) do { _Pragma("unroll") for (int m = 0; m < 4; ++m) _Pragma("unroll") for (int k = 0; k < 2; ++k) dst[m][k] = *(const PG8_LAS bf16x8*)(lds + PG8_SA(b, h) + aoff + m * 2048 + k * 1024); } while (0)
; #define PG8_MMA(ai, bj, At, Bt) do { __builtin_amdgcn_s_setprio(1); _Pragma("unroll") for (int m = 0; m < 4; ++m) _Pragma("unroll") for (int n = 0; n < 2; ++n) _Pragma("unroll") for (int k = 0; k < 2; ++k) \
;         acc[ai][bj][m][n] = __builtin_amdgcn_mfma_f32_16x16x32_bf16(Bt[n][k], At[m][k], acc[ai][bj][m][n], 0, 0, 0); __builtin_amdgcn_s_setprio(0); } while (0)
; #define PG8_WAIT_V(n) asm volatile("s_waitcnt vmcnt(" #n ")" ::: "memory")
; #define PG8_WAIT_L(n) asm volatile("s_waitcnt lgkmcnt(" #n ")" ::: "memory")
; #define PG8_BAR __builtin_amdgcn_s_barrier()
; #define PG8_SCHED __builtin_amdgcn_sched_barrier(0)
; template <class Epi, class Sched, bool ALIGN_EPI = false, bool SP2 = false>
; __device__ __forceinline__ void gemm_phase(PG8_LAS unsigned char* lds, const Gemm g, const Sched& S, const Epi& E) {
;     ...
;         for (int t = 0; t < nt; t += 2) {
;     ...
;             PG8_LDA(At, 1, 1); PG8_STAGE(PG8_SB(1, 0), b3, voffB); PG8_STAGE(PG8_SB(1, 1), b3 + hstep, voffB); PG8_STAGE(PG8_SA(1, 0), a3, voffA);
;             PG8_WAIT_V(8); PG8_WAIT_L(0); PG8_BAR; PG8_MMA(1, 0, At, B0); PG8_MMA(1, 1, At, B1); PG8_BAR; PG8_SCHED;
	s_add_i32 s28, s58, s37
	v_lshl_add_u64 v[210:211], v[210:211], 0, s[92:93]
	s_mov_b32 m0, s28
	ds_read_b128 v[178:181], v144 offset:49152
	ds_read_b128 v[182:185], v144 offset:50176
	ds_read_b128 v[186:189], v144 offset:51200
	ds_read_b128 v[190:193], v144 offset:52224
	ds_read_b128 v[194:197], v144 offset:53248
	ds_read_b128 v[198:201], v144 offset:54272
	ds_read_b128 v[202:205], v144 offset:55296
	ds_read_b128 v[206:209], v144 offset:56320
	global_load_lds_dwordx4 v[210:211], off
	v_lshl_add_u64 v[210:211], v[212:213], 0, s[92:93]
	s_add_i32 m0, s28, 0x2000
	s_add_i32 s28, s59, s37
	global_load_lds_dwordx4 v[210:211], off
	v_lshl_add_u64 v[210:211], v[214:215], 0, s[92:93]
	s_mov_b32 m0, s28
	s_nop 0
	global_load_lds_dwordx4 v[210:211], off
	v_lshl_add_u64 v[210:211], v[216:217], 0, s[92:93]
	s_add_i32 m0, s28, 0x2000
	s_nop 0
	global_load_lds_dwordx4 v[210:211], off
	v_lshl_add_u64 v[210:211], v[218:219], 0, s[92:93]
	s_mov_b32 m0, s46
	s_nop 0
	global_load_lds_dwordx4 v[210:211], off
	v_lshl_add_u64 v[210:211], v[228:229], 0, s[92:93]
	s_mov_b32 m0, s48
	s_nop 0
	global_load_lds_dwordx4 v[210:211], off
	s_waitcnt vmcnt(8)
	s_waitcnt lgkmcnt(0)
	s_barrier
	s_nop 0
	s_waitcnt lgkmcnt(0)
	v_mfma_f32_16x16x32_bf16 v[62:65], v[146:149], v[178:181], v[62:65]
	v_mfma_f32_16x16x32_bf16 v[58:61], v[154:157], v[178:181], v[58:61]
	v_mfma_f32_16x16x32_bf16 v[46:49], v[146:149], v[186:189], v[46:49]
	v_mfma_f32_16x16x32_bf16 v[42:45], v[154:157], v[186:189], v[42:45]
	v_mfma_f32_16x16x32_bf16 v[30:33], v[146:149], v[194:197], v[30:33]
	v_mfma_f32_16x16x32_bf16 v[26:29], v[154:157], v[194:197], v[26:29]
	v_mfma_f32_16x16x32_bf16 v[14:17], v[146:149], v[202:205], v[14:17]
	v_mfma_f32_16x16x32_bf16 v[10:13], v[154:157], v[202:205], v[10:13]
	v_mfma_f32_16x16x32_bf16 v[62:65], v[150:153], v[182:185], v[62:65]
	v_mfma_f32_16x16x32_bf16 v[58:61], v[158:161], v[182:185], v[58:61]
	v_mfma_f32_16x16x32_bf16 v[46:49], v[150:153], v[190:193], v[46:49]
	v_mfma_f32_16x16x32_bf16 v[42:45], v[158:161], v[190:193], v[42:45]
	v_mfma_f32_16x16x32_bf16 v[30:33], v[150:153], v[198:201], v[30:33]
	v_mfma_f32_16x16x32_bf16 v[26:29], v[158:161], v[198:201], v[26:29]
	v_mfma_f32_16x16x32_bf16 v[14:17], v[150:153], v[206:209], v[14:17]
	v_mfma_f32_16x16x32_bf16 v[10:13], v[158:161], v[206:209], v[10:13]
	s_nop 0
	s_nop 0
	v_mfma_f32_16x16x32_bf16 v[54:57], v[162:165], v[178:181], v[54:57]
	v_mfma_f32_16x16x32_bf16 v[50:53], v[170:173], v[178:181], v[50:53]
	v_mfma_f32_16x16x32_bf16 v[38:41], v[162:165], v[186:189], v[38:41]
	v_mfma_f32_16x16x32_bf16 v[34:37], v[170:173], v[186:189], v[34:37]
	v_mfma_f32_16x16x32_bf16 v[22:25], v[162:165], v[194:197], v[22:25]
	v_mfma_f32_16x16x32_bf16 v[18:21], v[170:173], v[194:197], v[18:21]
	v_mfma_f32_16x16x32_bf16 v[6:9], v[162:165], v[202:205], v[6:9]
	v_mfma_f32_16x16x32_bf16 v[2:5], v[170:173], v[202:205], v[2:5]
	v_mfma_f32_16x16x32_bf16 v[54:57], v[166:169], v[182:185], v[54:57]
	v_mfma_f32_16x16x32_bf16 v[50:53], v[174:177], v[182:185], v[50:53]
	v_mfma_f32_16x16x32_bf16 v[38:41], v[166:169], v[190:193], v[38:41]
	v_mfma_f32_16x16x32_bf16 v[34:37], v[174:177], v[190:193], v[34:37]
	v_mfma_f32_16x16x32_bf16 v[22:25], v[166:169], v[198:201], v[22:25]
	v_mfma_f32_16x16x32_bf16 v[18:21], v[174:177], v[198:201], v[18:21]
	v_mfma_f32_16x16x32_bf16 v[6:9], v[166:169], v[206:209], v[6:9]
	v_mfma_f32_16x16x32_bf16 v[2:5], v[174:177], v[206:209], v[2:5]
	s_nop 0
	s_barrier
	s_add_u32 s55, s55, 0x100
	s_addc_u32 s56, s56, 0
	s_add_u32 s26, s26, 0x100
	s_addc_u32 s27, s27, 0
	s_cmp_ge_i32 s57, s50
	s_mov_b32 s28, s57
	s_cbranch_scc0 .LBB0_4164

; __device__ __forceinline__ void xcd_barrier(const XcdBarrier& b) {
;     asm volatile("s_waitcnt vmcnt(0)" ::: "memory");
;     __syncthreads();
;     if (b.tid == 0u) {
;         unsigned* bar = b.bar;
;         __builtin_amdgcn_s_waitcnt(0);
;         unsigned nloc = b.st[0], nx = b.st[1];
;         if (nloc == 0u) { xcd_barrier_complete(bar, b.x, nloc, nx); b.st[0] = nloc; b.st[1] = nx; }
.LBB0_4171:
	s_mov_b64 s[4:5], s[88:89]
	s_getreg_b32 s6, hwreg(HW_REG_XCC_ID, 0, 4)
	s_waitcnt vmcnt(0)
	s_waitcnt vmcnt(0) lgkmcnt(0)
	s_setprio 0
	s_barrier
	s_mov_b64 s[0:1], exec
	v_readlane_b32 s8, v252, 2
	v_readlane_b32 s9, v252, 3
	s_and_b64 s[8:9], s[0:1], s[8:9]
	s_mov_b64 exec, s[8:9]
	s_cbranch_execz .LBB0_4223
	v_readlane_b32 s7, v252, 13
	s_load_dwordx2 s[4:5], s[4:5], 0x100
	s_waitcnt vmcnt(0) expcnt(0) lgkmcnt(0)
	v_mov_b32_e32 v1, s7
	ds_read_b32 v3, v1
	v_readlane_b32 s7, v252, 14
	s_and_b32 s48, s6, 15
	s_waitcnt lgkmcnt(0)
	v_cmp_ne_u32_e32 vcc, 0, v3
	v_mov_b32_e32 v1, s7
	ds_read_b32 v2, v1
	s_cbranch_vccnz .LBB0_4187
	s_add_u32 s6, s4, 0x17900200
	s_addc_u32 s7, s5, 0
	s_add_u32 s8, s4, 0x17900400
	s_addc_u32 s9, s5, 0
	s_add_u32 s10, s4, 0x17900500
	s_addc_u32 s11, s5, 0
	s_add_u32 s12, s4, 0x17900600
	s_addc_u32 s13, s5, 0
	s_add_u32 s14, s4, 0x17900700
	s_addc_u32 s15, s5, 0
	s_add_u32 s16, s4, 0x17900800
	s_addc_u32 s17, s5, 0
	s_add_u32 s18, s4, 0x17900900
	s_addc_u32 s19, s5, 0
	s_add_u32 s20, s4, 0x17900a00
	s_addc_u32 s21, s5, 0
	s_add_u32 s22, s4, 0x17900b00
	s_addc_u32 s23, s5, 0
	s_add_u32 s24, s4, 0x17900c00
	s_addc_u32 s25, s5, 0
	s_add_u32 s26, s4, 0x17900d00
	s_addc_u32 s27, s5, 0
	s_add_u32 s28, s4, 0x17900e00
	s_addc_u32 s29, s5, 0
	s_add_u32 s30, s4, 0x17900f00
	s_addc_u32 s31, s5, 0
	s_add_u32 s34, s4, 0x17901000
	s_addc_u32 s35, s5, 0
	s_add_u32 s36, s4, 0x17901100
	s_addc_u32 s37, s5, 0
	s_add_u32 s38, s4, 0x17901200
	s_addc_u32 s39, s5, 0
	s_add_u32 s40, s4, 0x17901300
	s_addc_u32 s41, s5, 0
	s_mov_b32 s49, 1
	s_branch .LBB0_4175

;     __host__ __device__ bool next(int i, Unit& u) const {
;         const long L = (long)i * G + c; if (L >= nwg) return false;
;         int wgid = (int)L; { const int q = nwg / NXCD, r = nwg % NXCD, xcd = wgid % NXCD, off = wgid / NXCD; wgid = (xcd < r ? xcd * (q + 1) : r * (q + 1) + (xcd - r) * q) + off; }
;         const int nig = WGM * nN, gid = wgid / nig, fm = gid * WGM, gsz = (nM - fm) < WGM ? (nM - fm) : WGM;
; template <class Epi> __device__ __forceinline__ void run_gemm(const int tid, LAS unsigned char* lds, const bf16_t* A, const bf16_t* Bt, int M, int N, int K, const Epi& E) {
;     ...
;     pg8::Gemm g{A, Bt, M, N, K, tid}; pg8::StaticOrder S; S.init(M, N, (int)gridDim.x, (int)blockIdx.x);
.Lmy_prio_skip_16:
	s_load_dwordx4 s[8:11], s[0:1], 0xf8
	s_movk_i32 s1, 0x400
	s_movk_i32 s0, 0x300
	s_movk_i32 s4, 0x4000
	s_waitcnt lgkmcnt(0)
	s_add_u32 s2, s10, 0x8c00000
	s_addc_u32 s3, s11, 0
	s_add_u32 s12, s10, 0x2bd0000
	s_addc_u32 s13, s11, 0
	s_ashr_i32 s5, s4, 31
	s_lshr_b32 s5, s5, 24
	s_add_i32 s4, s4, s5
	s_ashr_i32 s36, s4, 8
	s_ashr_i32 s4, s1, 31
	s_lshr_b32 s4, s4, 24
	s_add_i32 s1, s1, s4
	s_ashr_i32 s28, s1, 8
	s_mul_i32 s14, s28, s36
	v_mov_b32_e32 v14, v220
	s_cmp_lt_i32 s86, s14
	s_cselect_b64 s[4:5], -1, 0
	s_cmp_ge_i32 s86, s14
	v_readfirstlane_b32 s15, v14
	s_cbranch_scc1 .LBB0_4464
	s_ashr_i32 s1, s14, 31
	s_lshr_b32 s1, s1, 29
	s_add_i32 s1, s14, s1
	s_ashr_i32 s17, s1, 3
	s_and_b32 s1, s1, -8
	s_sub_i32 s18, s14, s1
	s_add_i32 s16, s17, 1
	v_readlane_b32 s1, v252, 5
	s_cmp_ge_i32 s1, s18
	s_mov_b64 s[6:7], -1
	s_cbranch_scc0 .LBB0_4461
	v_readlane_b32 s6, v252, 5
	s_sub_i32 s6, s6, s18
	s_mul_i32 s1, s16, s18
	s_mul_i32 s6, s6, s17
	s_add_i32 s1, s6, s1
	s_mov_b64 s[6:7], 0

; __device__ __forceinline__ void xcd_barrier(const XcdBarrier& b) {
;     asm volatile("s_waitcnt vmcnt(0)" ::: "memory");
;     __syncthreads();
;     if (b.tid == 0u) {
;         unsigned* bar = b.bar;
;         __builtin_amdgcn_s_waitcnt(0);
;         unsigned nloc = b.st[0], nx = b.st[1];
;         if (nloc == 0u) { xcd_barrier_complete(bar, b.x, nloc, nx); b.st[0] = nloc; b.st[1] = nx; }
.LBB0_4505:
	s_mov_b64 s[2:3], s[88:89]
	s_getreg_b32 s4, hwreg(HW_REG_XCC_ID, 0, 4)
	s_waitcnt vmcnt(0)
	s_waitcnt lgkmcnt(0)
	s_setprio 0
	s_barrier
	s_mov_b64 s[0:1], exec
	v_readlane_b32 s6, v252, 2
	v_readlane_b32 s7, v252, 3
	s_and_b64 s[6:7], s[0:1], s[6:7]
	s_movk_i32 s29, 0x600
	s_mov_b64 exec, s[6:7]
	s_cbranch_execz .LBB0_4557
	v_readlane_b32 s5, v252, 13
	s_load_dwordx2 s[2:3], s[2:3], 0x100
	s_waitcnt vmcnt(0) expcnt(0) lgkmcnt(0)
	v_mov_b32_e32 v1, s5
	ds_read_b32 v3, v1
	v_readlane_b32 s5, v252, 14
	s_and_b32 s46, s4, 15
	s_waitcnt lgkmcnt(0)
	v_cmp_ne_u32_e32 vcc, 0, v3
	v_mov_b32_e32 v1, s5
	ds_read_b32 v2, v1
	s_cbranch_vccnz .LBB0_4521
	s_add_u32 s4, s2, 0x17900200
	s_addc_u32 s5, s3, 0
	s_add_u32 s6, s2, 0x17900400
	s_addc_u32 s7, s3, 0
	s_add_u32 s8, s2, 0x17900500
	s_addc_u32 s9, s3, 0
	s_add_u32 s10, s2, 0x17900600
	s_addc_u32 s11, s3, 0
	s_add_u32 s12, s2, 0x17900700
	s_addc_u32 s13, s3, 0
	s_add_u32 s14, s2, 0x17900800
	s_addc_u32 s15, s3, 0
	s_add_u32 s16, s2, 0x17900900
	s_addc_u32 s17, s3, 0
	s_add_u32 s18, s2, 0x17900a00
	s_addc_u32 s19, s3, 0
	s_add_u32 s20, s2, 0x17900b00
	s_addc_u32 s21, s3, 0
	s_add_u32 s22, s2, 0x17900c00
	s_addc_u32 s23, s3, 0
	s_add_u32 s24, s2, 0x17900d00
	s_addc_u32 s25, s3, 0
	s_add_u32 s26, s2, 0x17900e00
	s_addc_u32 s27, s3, 0
	s_add_u32 s28, s2, 0x17900f00
	s_addc_u32 s29, s3, 0
	s_add_u32 s30, s2, 0x17901000
	s_addc_u32 s31, s3, 0
	s_add_u32 s34, s2, 0x17901100
	s_addc_u32 s35, s3, 0
	s_add_u32 s36, s2, 0x17901200
	s_addc_u32 s37, s3, 0
	s_add_u32 s38, s2, 0x17901300
	s_addc_u32 s39, s3, 0
	s_mov_b32 s47, 1
	s_branch .LBB0_4509

; #define KA_DEF const __attribute__((address_space(4))) KArgs* ka_ = (const __attribute__((address_space(4))) KArgs*)__builtin_amdgcn_kernarg_segment_ptr(); asm volatile("" : "+s"(ka_));
; #define SSQ ((float*)WSP(WS_SSQ))
;     __host__ __device__ bool next(int i, Unit& u) const {
;         const long L = (long)i * G + c; if (L >= nwg) return false;
;         int wgid = (int)L; { const int q = nwg / NXCD, r = nwg % NXCD, xcd = wgid % NXCD, off = wgid / NXCD; wgid = (xcd < r ? xcd * (q + 1) : r * (q + 1) + (xcd - r) * q) + off; }
;         const int nig = WGM * nN, gid = wgid / nig, fm = gid * WGM, gsz = (nM - fm) < WGM ? (nM - fm) : WGM;
; __global__ void __launch_bounds__(512, 2) mega_fwd(KArgs a) {
;     ...
;         { KA_DEF pg8::EpiBf16S E{RA, 1024, SSQ}; run_gemm(TIDX, lds, XB, Wl + WO_XQ, T_, 1024, 1024, E); }
.Lmy_prio_skip_17:
.LBB0_4558:
	s_mov_b64 s[0:1], s[88:89]
	s_load_dwordx2 s[0:1], s[0:1], 0x100
	s_movk_i32 s5, 0x400
	s_movk_i32 s4, 0x400
	s_movk_i32 s8, 0x4000
	s_waitcnt lgkmcnt(0)
	s_add_u32 s2, s0, 0x6000000
	s_addc_u32 s3, s1, 0
	s_add_u32 s6, s0, 0x2100000
	s_addc_u32 s7, s1, 0
	s_ashr_i32 s9, s8, 31
	s_lshr_b32 s9, s9, 24
	s_add_i32 s8, s8, s9
	s_ashr_i32 s28, s8, 8
	s_ashr_i32 s8, s5, 31
	s_lshr_b32 s8, s8, 24
	s_add_i32 s5, s5, s8
	s_ashr_i32 s14, s5, 8
	s_mul_i32 s8, s14, s28
	v_mov_b32_e32 v14, v220
	s_cmp_ge_i32 s86, s8
	v_readfirstlane_b32 s20, v14
	s_cbranch_scc1 .LBB0_4587
	s_ashr_i32 s9, s8, 31
	s_lshr_b32 s5, s9, 29
	s_add_i32 s5, s8, s5
	s_ashr_i32 s29, s5, 3
	s_and_b32 s5, s5, -8
	s_sub_i32 s30, s8, s5
	s_add_i32 s31, s29, 1
	v_readlane_b32 s5, v252, 5
	s_cmp_ge_i32 s5, s30
	s_mov_b64 s[10:11], -1
	s_mul_i32 s34, s31, s30
	s_cbranch_scc0 .LBB0_4561
	v_readlane_b32 s5, v252, 5
	s_sub_i32 s5, s5, s30
	s_mul_i32 s5, s5, s29
	s_add_i32 s15, s5, s34
	s_mov_b64 s[10:11], 0

; #define PG8_STAGE(bufoff, gbase, voff) do { _Pragma("unroll") for (int _i = 0; _i < 2; ++_i) \
;         __builtin_amdgcn_global_load_lds((const unsigned*)((const char*)(gbase) + (voff)[_i]), (PG8_LAS unsigned*)(lds + (bufoff) + ldsw + _i * 8192), 16, 0, 0); } while (0)
; #define PG8_LDA(dst, b, h) do { _Pragma("unroll") for (int m = 0; m < 4; ++m) _Pragma("unroll") for (int k = 0; k < 2; ++k) dst[m][k] = *(const PG8_LAS bf16x8*)(lds + PG8_SA(b, h) + aoff + m * 2048 + k * 1024); } while (0)
; #define PG8_LDB(dst, b, h) do { _Pragma("unroll") for (int n = 0; n < 2; ++n) _Pragma("unroll") for (int k = 0; k < 2; ++k) dst[n][k] = *(const PG8_LAS bf16x8*)(lds + PG8_SB(b, h) + boff + n * 2048 + k * 1024); } while (0)
; #define PG8_MMA(ai, bj, At, Bt) do { __builtin_amdgcn_s_setprio(1); _Pragma("unroll") for (int m = 0; m < 4; ++m) _Pragma("unroll") for (int n = 0; n < 2; ++n) _Pragma("unroll") for (int k = 0; k < 2; ++k) \
;         acc[ai][bj][m][n] = __builtin_amdgcn_mfma_f32_16x16x32_bf16(Bt[n][k], At[m][k], acc[ai][bj][m][n], 0, 0, 0); __builtin_amdgcn_s_setprio(0); } while (0)
; #define PG8_WAIT_V(n) asm volatile("s_waitcnt vmcnt(" #n ")" ::: "memory")
; #define PG8_WAIT_L(n) asm volatile("s_waitcnt lgkmcnt(" #n ")" ::: "memory")
; #define PG8_BAR __builtin_amdgcn_s_barrier()
; #define PG8_SCHED __builtin_amdgcn_sched_barrier(0)
; template <class Epi, class Sched, bool ALIGN_EPI = false, bool SP2 = false>
; __device__ __forceinline__ void gemm_phase(PG8_LAS unsigned char* lds, const Gemm g, const Sched& S, const Epi& E) {
;     ...
;             const bool last = (t == nt - 2);
;             const char* a1 = cA + (size_t)(t + 1) * kstep;
;             const char* a2 = last ? nA : cA + (size_t)(t + 2) * kstep; const char* b2 = last ? nB : cB + (size_t)(t + 2) * kstep;
;             const char* a3 = a2 + kstep; const char* b3 = b2 + kstep;
;             if (last && has_next) S.a_ready(nxt);
;             if constexpr (SP2) {
;             PG8_LDB(B0, 0, 0); PG8_LDB(B1, 0, 1); PG8_SCHED; PG8_LDA(At, 0, 0); PG8_STAGE(PG8_SA(1, 1), a1 + hstep, voffA);
;             PG8_WAIT_V(8); PG8_WAIT_L(0); PG8_BAR; PG8_MMA(0, 0, At, B0); PG8_MMA(0, 1, At, B1); PG8_BAR; PG8_SCHED;
;             PG8_LDA(At, 0, 1); PG8_STAGE(PG8_SB(0, 0), b2, voffB); PG8_STAGE(PG8_SB(0, 1), b2 + hstep, voffB); PG8_STAGE(PG8_SA(0, 0), a2, voffA);
.LBB0_4580:
	s_add_i32 s55, s26, 2
	s_add_u32 s56, s24, 0x80
	s_addc_u32 s27, s25, 0
	s_add_i32 s58, 0, 0x10000
	s_cmp_eq_u32 s47, s26
	s_cselect_b32 s27, s1, s27
	s_cselect_b32 s26, s0, s56
	v_add_u32_e32 v148, s58, v149
	s_cselect_b32 s57, s23, s54
	s_cselect_b32 s56, s22, s53
	s_add_i32 s59, 0, 0x14000
	ds_read_b128 v[130:133], v148
	ds_read_b128 v[154:157], v148 offset:1024
	ds_read_b128 v[158:161], v148 offset:2048
	ds_read_b128 v[162:165], v148 offset:3072
	v_add_u32_e32 v148, s59, v149
	ds_read_b128 v[166:169], v148
	ds_read_b128 v[170:173], v148 offset:1024
	ds_read_b128 v[174:177], v148 offset:2048
	ds_read_b128 v[178:181], v148 offset:3072
	v_lshl_add_u64 v[214:215], s[24:25], 0, v[146:147]
	s_add_i32 m0, s40, 0xc000
	ds_read_b128 v[182:185], v153
	ds_read_b128 v[186:189], v153 offset:1024
	ds_read_b128 v[190:193], v153 offset:2048
	ds_read_b128 v[194:197], v153 offset:3072
	ds_read_b128 v[198:201], v153 offset:4096
	ds_read_b128 v[202:205], v153 offset:5120
	ds_read_b128 v[206:209], v153 offset:6144
	ds_read_b128 v[210:213], v153 offset:7168
	global_load_lds_dwordx4 v[214:215], off
	v_lshl_add_u64 v[214:215], s[24:25], 0, v[144:145]
	s_add_i32 m0, s40, 0xe000
	s_nop 0
	global_load_lds_dwordx4 v[214:215], off
	s_waitcnt vmcnt(8)
	s_waitcnt lgkmcnt(0)
	s_barrier
	s_nop 0
	s_waitcnt lgkmcnt(0)
	v_mfma_f32_16x16x32_bf16 v[126:129], v[130:133], v[182:185], v[126:129]
	v_mfma_f32_16x16x32_bf16 v[122:125], v[158:161], v[182:185], v[122:125]
	v_mfma_f32_16x16x32_bf16 v[110:113], v[130:133], v[190:193], v[110:113]
	v_mfma_f32_16x16x32_bf16 v[106:109], v[158:161], v[190:193], v[106:109]
	v_mfma_f32_16x16x32_bf16 v[94:97], v[130:133], v[198:201], v[94:97]
	v_mfma_f32_16x16x32_bf16 v[90:93], v[158:161], v[198:201], v[90:93]
	v_mfma_f32_16x16x32_bf16 v[78:81], v[130:133], v[206:209], v[78:81]
	v_mfma_f32_16x16x32_bf16 v[74:77], v[158:161], v[206:209], v[74:77]
	v_mfma_f32_16x16x32_bf16 v[126:129], v[154:157], v[186:189], v[126:129]
	v_mfma_f32_16x16x32_bf16 v[122:125], v[162:165], v[186:189], v[122:125]
	v_mfma_f32_16x16x32_bf16 v[110:113], v[154:157], v[194:197], v[110:113]
	v_mfma_f32_16x16x32_bf16 v[106:109], v[162:165], v[194:197], v[106:109]
	v_mfma_f32_16x16x32_bf16 v[94:97], v[154:157], v[202:205], v[94:97]
	v_mfma_f32_16x16x32_bf16 v[90:93], v[162:165], v[202:205], v[90:93]
	v_mfma_f32_16x16x32_bf16 v[78:81], v[154:157], v[210:213], v[78:81]
	v_mfma_f32_16x16x32_bf16 v[74:77], v[162:165], v[210:213], v[74:77]
	s_nop 0
	s_nop 0
	v_mfma_f32_16x16x32_bf16 v[118:121], v[166:169], v[182:185], v[118:121]
	v_mfma_f32_16x16x32_bf16 v[114:117], v[174:177], v[182:185], v[114:117]
	v_mfma_f32_16x16x32_bf16 v[102:105], v[166:169], v[190:193], v[102:105]
	v_mfma_f32_16x16x32_bf16 v[98:101], v[174:177], v[190:193], v[98:101]
	v_mfma_f32_16x16x32_bf16 v[86:89], v[166:169], v[198:201], v[86:89]
	v_mfma_f32_16x16x32_bf16 v[82:85], v[174:177], v[198:201], v[82:85]
	v_mfma_f32_16x16x32_bf16 v[70:73], v[166:169], v[206:209], v[70:73]
	v_mfma_f32_16x16x32_bf16 v[66:69], v[174:177], v[206:209], v[66:69]
	v_mfma_f32_16x16x32_bf16 v[118:121], v[170:173], v[186:189], v[118:121]
	v_mfma_f32_16x16x32_bf16 v[114:117], v[178:181], v[186:189], v[114:117]
	v_mfma_f32_16x16x32_bf16 v[102:105], v[170:173], v[194:197], v[102:105]
	v_mfma_f32_16x16x32_bf16 v[98:101], v[178:181], v[194:197], v[98:101]
	v_mfma_f32_16x16x32_bf16 v[86:89], v[170:173], v[202:205], v[86:89]
	v_mfma_f32_16x16x32_bf16 v[82:85], v[178:181], v[202:205], v[82:85]
	v_mfma_f32_16x16x32_bf16 v[70:73], v[170:173], v[210:213], v[70:73]
	v_mfma_f32_16x16x32_bf16 v[66:69], v[178:181], v[210:213], v[66:69]
	s_nop 0
	s_barrier
	s_add_i32 s58, s58, s35
	v_lshl_add_u64 v[214:215], s[56:57], 0, v[136:137]
	s_mov_b32 m0, s58
	ds_read_b128 v[182:185], v153 offset:16384
	ds_read_b128 v[186:189], v153 offset:17408
	ds_read_b128 v[190:193], v153 offset:18432
	ds_read_b128 v[194:197], v153 offset:19456
	ds_read_b128 v[198:201], v153 offset:20480
	ds_read_b128 v[202:205], v153 offset:21504
	ds_read_b128 v[206:209], v153 offset:22528
	ds_read_b128 v[210:213], v153 offset:23552
	global_load_lds_dwordx4 v[214:215], off
	s_add_i32 m0, s58, 0x2000
	v_lshl_add_u64 v[216:217], s[56:57], 0, v[140:141]
	s_add_u32 s56, s56, s10
	s_addc_u32 s57, s57, s11
	s_add_i32 s58, s59, s35
	global_load_lds_dwordx4 v[216:217], off
	v_lshl_add_u64 v[218:219], s[56:57], 0, v[136:137]
	s_mov_b32 m0, s58
	v_lshl_add_u64 v[228:229], s[56:57], 0, v[140:141]
	global_load_lds_dwordx4 v[218:219], off
	s_add_i32 m0, s58, 0x2000
	v_lshl_add_u64 v[242:243], s[26:27], 0, v[134:135]
	global_load_lds_dwordx4 v[228:229], off
	s_mov_b32 m0, s40
	v_lshl_add_u64 v[244:245], s[26:27], 0, v[138:139]
	global_load_lds_dwordx4 v[242:243], off
	s_mov_b32 m0, s41
	s_nop 0
	global_load_lds_dwordx4 v[244:245], off
	s_waitcnt vmcnt(8)
	s_waitcnt lgkmcnt(0)
	s_barrier
; #define PG8_STAGE(bufoff, gbase, voff) do { _Pragma("unroll") for (int _i = 0; _i < 2; ++_i) \
;         __builtin_amdgcn_global_load_lds((const unsigned*)((const char*)(gbase) + (voff)[_i]), (PG8_LAS unsigned*)(lds + (bufoff) + ldsw + _i * 8192), 16, 0, 0); } while (0)
; #define PG8_LDA(dst, b, h) do { _Pragma("unroll") for (int m = 0; m < 4; ++m) _Pragma("unroll") for (int k = 0; k < 2; ++k) dst[m][k] = *(const PG8_LAS bf16x8*)(lds + PG8_SA(b, h) + aoff + m * 2048 + k * 1024); } while (0)
; #define PG8_LDB(dst, b, h) do { _Pragma("unroll") for (int n = 0; n < 2; ++n) _Pragma("unroll") for (int k = 0; k < 2; ++k) dst[n][k] = *(const PG8_LAS bf16x8*)(lds + PG8_SB(b, h) + boff + n * 2048 + k * 1024); } while (0)
; #define PG8_MMA(ai, bj, At, Bt) do { __builtin_amdgcn_s_setprio(1); _Pragma("unroll") for (int m = 0; m < 4; ++m) _Pragma("unroll") for (int n = 0; n < 2; ++n) _Pragma("unroll") for (int k = 0; k < 2; ++k) \
;         acc[ai][bj][m][n] = __builtin_amdgcn_mfma_f32_16x16x32_bf16(Bt[n][k], At[m][k], acc[ai][bj][m][n], 0, 0, 0); __builtin_amdgcn_s_setprio(0); } while (0)
; #define PG8_WAIT_V(n) asm volatile("s_waitcnt vmcnt(" #n ")" ::: "memory")
; #define PG8_WAIT_L(n) asm volatile("s_waitcnt lgkmcnt(" #n ")" ::: "memory")
; #define PG8_BAR __builtin_amdgcn_s_barrier()
; #define PG8_SCHED __builtin_amdgcn_sched_barrier(0)
; template <class Epi, class Sched, bool ALIGN_EPI = false, bool SP2 = false>
; __device__ __forceinline__ void gemm_phase(PG8_LAS unsigned char* lds, const Gemm g, const Sched& S, const Epi& E) {
;     ...
;             PG8_WAIT_V(8); PG8_WAIT_L(0); PG8_BAR; PG8_MMA(1, 0, At, B0); PG8_MMA(1, 1, At, B1); PG8_BAR; PG8_SCHED;
;             PG8_LDB(B0, 1, 0); PG8_LDB(B1, 1, 1); PG8_SCHED; PG8_LDA(At, 1, 0); PG8_STAGE(PG8_SA(0, 1), a2 + hstep, voffA);
;             PG8_WAIT_V(8); PG8_WAIT_L(0); PG8_BAR; PG8_MMA(0, 0, At, B0); PG8_MMA(0, 1, At, B1); PG8_BAR; PG8_SCHED;
	s_nop 0
	s_waitcnt lgkmcnt(0)
	v_mfma_f32_16x16x32_bf16 v[62:65], v[130:133], v[182:185], v[62:65]
	v_mfma_f32_16x16x32_bf16 v[58:61], v[158:161], v[182:185], v[58:61]
	v_mfma_f32_16x16x32_bf16 v[46:49], v[130:133], v[190:193], v[46:49]
	v_mfma_f32_16x16x32_bf16 v[42:45], v[158:161], v[190:193], v[42:45]
	v_mfma_f32_16x16x32_bf16 v[30:33], v[130:133], v[198:201], v[30:33]
	v_mfma_f32_16x16x32_bf16 v[26:29], v[158:161], v[198:201], v[26:29]
	v_mfma_f32_16x16x32_bf16 v[14:17], v[130:133], v[206:209], v[14:17]
	v_mfma_f32_16x16x32_bf16 v[10:13], v[158:161], v[206:209], v[10:13]
	v_mfma_f32_16x16x32_bf16 v[62:65], v[154:157], v[186:189], v[62:65]
	v_mfma_f32_16x16x32_bf16 v[58:61], v[162:165], v[186:189], v[58:61]
	v_mfma_f32_16x16x32_bf16 v[46:49], v[154:157], v[194:197], v[46:49]
	v_mfma_f32_16x16x32_bf16 v[42:45], v[162:165], v[194:197], v[42:45]
	v_mfma_f32_16x16x32_bf16 v[30:33], v[154:157], v[202:205], v[30:33]
	v_mfma_f32_16x16x32_bf16 v[26:29], v[162:165], v[202:205], v[26:29]
	v_mfma_f32_16x16x32_bf16 v[14:17], v[154:157], v[210:213], v[14:17]
	v_mfma_f32_16x16x32_bf16 v[10:13], v[162:165], v[210:213], v[10:13]
	s_nop 0
	s_nop 0
	v_mfma_f32_16x16x32_bf16 v[54:57], v[166:169], v[182:185], v[54:57]
	v_mfma_f32_16x16x32_bf16 v[50:53], v[174:177], v[182:185], v[50:53]
	v_mfma_f32_16x16x32_bf16 v[38:41], v[166:169], v[190:193], v[38:41]
	v_mfma_f32_16x16x32_bf16 v[34:37], v[174:177], v[190:193], v[34:37]
	v_mfma_f32_16x16x32_bf16 v[22:25], v[166:169], v[198:201], v[22:25]
	v_mfma_f32_16x16x32_bf16 v[18:21], v[174:177], v[198:201], v[18:21]
	v_mfma_f32_16x16x32_bf16 v[6:9], v[166:169], v[206:209], v[6:9]
	v_mfma_f32_16x16x32_bf16 v[2:5], v[174:177], v[206:209], v[2:5]
	v_mfma_f32_16x16x32_bf16 v[54:57], v[170:173], v[186:189], v[54:57]
	v_mfma_f32_16x16x32_bf16 v[50:53], v[178:181], v[186:189], v[50:53]
	v_mfma_f32_16x16x32_bf16 v[38:41], v[170:173], v[194:197], v[38:41]
	v_mfma_f32_16x16x32_bf16 v[34:37], v[178:181], v[194:197], v[34:37]
	v_mfma_f32_16x16x32_bf16 v[22:25], v[170:173], v[202:205], v[22:25]
	v_mfma_f32_16x16x32_bf16 v[18:21], v[178:181], v[202:205], v[18:21]
	v_mfma_f32_16x16x32_bf16 v[6:9], v[170:173], v[210:213], v[6:9]
	v_mfma_f32_16x16x32_bf16 v[2:5], v[178:181], v[210:213], v[2:5]
	s_nop 0
	s_barrier
	s_add_i32 s56, 0, 0x18000
	v_add_u32_e32 v148, s56, v149
	s_add_i32 s57, 0, 0x1c000
	ds_read_b128 v[130:133], v148
	ds_read_b128 v[154:157], v148 offset:1024
	ds_read_b128 v[158:161], v148 offset:2048
	ds_read_b128 v[162:165], v148 offset:3072
	v_add_u32_e32 v148, s57, v149
	ds_read_b128 v[166:169], v148
	ds_read_b128 v[170:173], v148 offset:1024
	ds_read_b128 v[174:177], v148 offset:2048
	ds_read_b128 v[178:181], v148 offset:3072
	s_add_u32 s26, s26, s10
	s_addc_u32 s27, s27, s11
	s_mov_b32 m0, s42
	v_lshl_add_u64 v[246:247], s[26:27], 0, v[134:135]
	ds_read_b128 v[182:185], v153 offset:32768
	ds_read_b128 v[186:189], v153 offset:33792
	ds_read_b128 v[190:193], v153 offset:34816
	ds_read_b128 v[194:197], v153 offset:35840
	ds_read_b128 v[198:201], v153 offset:36864
	ds_read_b128 v[202:205], v153 offset:37888
	ds_read_b128 v[206:209], v153 offset:38912
	ds_read_b128 v[210:213], v153 offset:39936
	global_load_lds_dwordx4 v[246:247], off
	v_lshl_add_u64 v[246:247], s[26:27], 0, v[138:139]
	s_mov_b32 m0, s43
	s_nop 0
	global_load_lds_dwordx4 v[246:247], off
	s_waitcnt vmcnt(8)
	s_waitcnt lgkmcnt(0)
	s_barrier
	s_nop 0
	s_waitcnt lgkmcnt(0)
	v_mfma_f32_16x16x32_bf16 v[126:129], v[130:133], v[182:185], v[126:129]
	v_mfma_f32_16x16x32_bf16 v[122:125], v[158:161], v[182:185], v[122:125]
	v_mfma_f32_16x16x32_bf16 v[110:113], v[130:133], v[190:193], v[110:113]
	v_mfma_f32_16x16x32_bf16 v[106:109], v[158:161], v[190:193], v[106:109]
	v_mfma_f32_16x16x32_bf16 v[94:97], v[130:133], v[198:201], v[94:97]
	v_mfma_f32_16x16x32_bf16 v[90:93], v[158:161], v[198:201], v[90:93]
	v_mfma_f32_16x16x32_bf16 v[78:81], v[130:133], v[206:209], v[78:81]
	v_mfma_f32_16x16x32_bf16 v[74:77], v[158:161], v[206:209], v[74:77]
	v_mfma_f32_16x16x32_bf16 v[126:129], v[154:157], v[186:189], v[126:129]
	v_mfma_f32_16x16x32_bf16 v[122:125], v[162:165], v[186:189], v[122:125]
	v_mfma_f32_16x16x32_bf16 v[110:113], v[154:157], v[194:197], v[110:113]
	v_mfma_f32_16x16x32_bf16 v[106:109], v[162:165], v[194:197], v[106:109]
	v_mfma_f32_16x16x32_bf16 v[94:97], v[154:157], v[202:205], v[94:97]
	v_mfma_f32_16x16x32_bf16 v[90:93], v[162:165], v[202:205], v[90:93]
	v_mfma_f32_16x16x32_bf16 v[78:81], v[154:157], v[210:213], v[78:81]
	v_mfma_f32_16x16x32_bf16 v[74:77], v[162:165], v[210:213], v[74:77]
	s_nop 0
	s_nop 0
	v_mfma_f32_16x16x32_bf16 v[118:121], v[166:169], v[182:185], v[118:121]
	v_mfma_f32_16x16x32_bf16 v[114:117], v[174:177], v[182:185], v[114:117]
	v_mfma_f32_16x16x32_bf16 v[102:105], v[166:169], v[190:193], v[102:105]
	v_mfma_f32_16x16x32_bf16 v[98:101], v[174:177], v[190:193], v[98:101]
	v_mfma_f32_16x16x32_bf16 v[86:89], v[166:169], v[198:201], v[86:89]
	v_mfma_f32_16x16x32_bf16 v[82:85], v[174:177], v[198:201], v[82:85]
	v_mfma_f32_16x16x32_bf16 v[70:73], v[166:169], v[206:209], v[70:73]
	v_mfma_f32_16x16x32_bf16 v[66:69], v[174:177], v[206:209], v[66:69]
	v_mfma_f32_16x16x32_bf16 v[118:121], v[170:173], v[186:189], v[118:121]
	v_mfma_f32_16x16x32_bf16 v[114:117], v[178:181], v[186:189], v[114:117]
	v_mfma_f32_16x16x32_bf16 v[102:105], v[170:173], v[194:197], v[102:105]
	v_mfma_f32_16x16x32_bf16 v[98:101], v[178:181], v[194:197], v[98:101]
	v_mfma_f32_16x16x32_bf16 v[86:89], v[170:173], v[202:205], v[86:89]
	v_mfma_f32_16x16x32_bf16 v[82:85], v[178:181], v[202:205], v[82:85]
	v_mfma_f32_16x16x32_bf16 v[70:73], v[170:173], v[210:213], v[70:73]
	v_mfma_f32_16x16x32_bf16 v[66:69], v[178:181], v[210:213], v[66:69]
	s_nop 0
	s_barrier
; #define PG8_STAGE(bufoff, gbase, voff) do { _Pragma("unroll") for (int _i = 0; _i < 2; ++_i) \
;         __builtin_amdgcn_global_load_lds((const unsigned*)((const char*)(gbase) + (voff)[_i]), (PG8_LAS unsigned*)(lds + (bufoff) + ldsw + _i * 8192), 16, 0, 0); } while (0)
; #define PG8_LDA(dst, b, h) do { _Pragma("unroll") for (int m = 0; m < 4; ++m) _Pragma("unroll") for (int k = 0; k < 2; ++k) dst[m][k] = *(const PG8_LAS bf16x8*)(lds + PG8_SA(b, h) + aoff + m * 2048 + k * 1024); } while (0)
; #define PG8_MMA(ai, bj, At, Bt) do { __builtin_amdgcn_s_setprio(1); _Pragma("unroll") for (int m = 0; m < 4; ++m) _Pragma("unroll") for (int n = 0; n < 2; ++n) _Pragma("unroll") for (int k = 0; k < 2; ++k) \
;         acc[ai][bj][m][n] = __builtin_amdgcn_mfma_f32_16x16x32_bf16(Bt[n][k], At[m][k], acc[ai][bj][m][n], 0, 0, 0); __builtin_amdgcn_s_setprio(0); } while (0)
; #define PG8_WAIT_V(n) asm volatile("s_waitcnt vmcnt(" #n ")" ::: "memory")
; #define PG8_WAIT_L(n) asm volatile("s_waitcnt lgkmcnt(" #n ")" ::: "memory")
; #define PG8_BAR __builtin_amdgcn_s_barrier()
; #define PG8_SCHED __builtin_amdgcn_sched_barrier(0)
; template <class Epi, class Sched, bool ALIGN_EPI = false, bool SP2 = false>
; __device__ __forceinline__ void gemm_phase(PG8_LAS unsigned char* lds, const Gemm g, const Sched& S, const Epi& E) {
;     ...
;         for (int t = 0; t < nt; t += 2) {
;     ...
;             PG8_LDA(At, 1, 1); PG8_STAGE(PG8_SB(1, 0), b3, voffB); PG8_STAGE(PG8_SB(1, 1), b3 + hstep, voffB); PG8_STAGE(PG8_SA(1, 0), a3, voffA);
;             PG8_WAIT_V(8); PG8_WAIT_L(0); PG8_BAR; PG8_MMA(1, 0, At, B0); PG8_MMA(1, 1, At, B1); PG8_BAR; PG8_SCHED;
	s_add_i32 s26, s56, s35
	v_lshl_add_u64 v[214:215], v[214:215], 0, s[92:93]
	s_mov_b32 m0, s26
	ds_read_b128 v[182:185], v153 offset:49152
	ds_read_b128 v[186:189], v153 offset:50176
	ds_read_b128 v[190:193], v153 offset:51200
	ds_read_b128 v[194:197], v153 offset:52224
	ds_read_b128 v[198:201], v153 offset:53248
	ds_read_b128 v[202:205], v153 offset:54272
	ds_read_b128 v[206:209], v153 offset:55296
	ds_read_b128 v[210:213], v153 offset:56320
	global_load_lds_dwordx4 v[214:215], off
	v_lshl_add_u64 v[214:215], v[216:217], 0, s[92:93]
	s_add_i32 m0, s26, 0x2000
	s_add_i32 s26, s57, s35
	global_load_lds_dwordx4 v[214:215], off
	v_lshl_add_u64 v[214:215], v[218:219], 0, s[92:93]
	s_mov_b32 m0, s26
	s_nop 0
	global_load_lds_dwordx4 v[214:215], off
	v_lshl_add_u64 v[214:215], v[228:229], 0, s[92:93]
	s_add_i32 m0, s26, 0x2000
	s_nop 0
	global_load_lds_dwordx4 v[214:215], off
	v_lshl_add_u64 v[214:215], v[242:243], 0, s[92:93]
	s_mov_b32 m0, s44
	s_nop 0
	global_load_lds_dwordx4 v[214:215], off
	v_lshl_add_u64 v[214:215], v[244:245], 0, s[92:93]
	s_mov_b32 m0, s45
	s_nop 0
	global_load_lds_dwordx4 v[214:215], off
	s_waitcnt vmcnt(8)
	s_waitcnt lgkmcnt(0)
	s_barrier
	s_nop 0
	s_waitcnt lgkmcnt(0)
	v_mfma_f32_16x16x32_bf16 v[62:65], v[130:133], v[182:185], v[62:65]
	v_mfma_f32_16x16x32_bf16 v[58:61], v[158:161], v[182:185], v[58:61]
	v_mfma_f32_16x16x32_bf16 v[46:49], v[130:133], v[190:193], v[46:49]
	v_mfma_f32_16x16x32_bf16 v[42:45], v[158:161], v[190:193], v[42:45]
	v_mfma_f32_16x16x32_bf16 v[30:33], v[130:133], v[198:201], v[30:33]
	v_mfma_f32_16x16x32_bf16 v[26:29], v[158:161], v[198:201], v[26:29]
	v_mfma_f32_16x16x32_bf16 v[14:17], v[130:133], v[206:209], v[14:17]
	v_mfma_f32_16x16x32_bf16 v[10:13], v[158:161], v[206:209], v[10:13]
	v_mfma_f32_16x16x32_bf16 v[62:65], v[154:157], v[186:189], v[62:65]
	v_mfma_f32_16x16x32_bf16 v[58:61], v[162:165], v[186:189], v[58:61]
	v_mfma_f32_16x16x32_bf16 v[46:49], v[154:157], v[194:197], v[46:49]
	v_mfma_f32_16x16x32_bf16 v[42:45], v[162:165], v[194:197], v[42:45]
	v_mfma_f32_16x16x32_bf16 v[30:33], v[154:157], v[202:205], v[30:33]
	v_mfma_f32_16x16x32_bf16 v[26:29], v[162:165], v[202:205], v[26:29]
	v_mfma_f32_16x16x32_bf16 v[14:17], v[154:157], v[210:213], v[14:17]
	v_mfma_f32_16x16x32_bf16 v[10:13], v[162:165], v[210:213], v[10:13]
	s_nop 0
	s_nop 0
	v_mfma_f32_16x16x32_bf16 v[54:57], v[166:169], v[182:185], v[54:57]
	v_mfma_f32_16x16x32_bf16 v[50:53], v[174:177], v[182:185], v[50:53]
	v_mfma_f32_16x16x32_bf16 v[38:41], v[166:169], v[190:193], v[38:41]
	v_mfma_f32_16x16x32_bf16 v[34:37], v[174:177], v[190:193], v[34:37]
	v_mfma_f32_16x16x32_bf16 v[22:25], v[166:169], v[198:201], v[22:25]
	v_mfma_f32_16x16x32_bf16 v[18:21], v[174:177], v[198:201], v[18:21]
	v_mfma_f32_16x16x32_bf16 v[6:9], v[166:169], v[206:209], v[6:9]
	v_mfma_f32_16x16x32_bf16 v[2:5], v[174:177], v[206:209], v[2:5]
	v_mfma_f32_16x16x32_bf16 v[54:57], v[170:173], v[186:189], v[54:57]
	v_mfma_f32_16x16x32_bf16 v[50:53], v[178:181], v[186:189], v[50:53]
	v_mfma_f32_16x16x32_bf16 v[38:41], v[170:173], v[194:197], v[38:41]
	v_mfma_f32_16x16x32_bf16 v[34:37], v[178:181], v[194:197], v[34:37]
	v_mfma_f32_16x16x32_bf16 v[22:25], v[170:173], v[202:205], v[22:25]
	v_mfma_f32_16x16x32_bf16 v[18:21], v[178:181], v[202:205], v[18:21]
	v_mfma_f32_16x16x32_bf16 v[6:9], v[170:173], v[210:213], v[6:9]
	v_mfma_f32_16x16x32_bf16 v[2:5], v[178:181], v[210:213], v[2:5]
	s_nop 0
	s_barrier
	s_add_u32 s53, s53, 0x100
	s_addc_u32 s54, s54, 0
	s_add_u32 s24, s24, 0x100
	s_addc_u32 s25, s25, 0
	s_cmp_ge_i32 s55, s46
	s_mov_b32 s26, s55
	s_cbranch_scc0 .LBB0_4580

; __device__ __forceinline__ void xcd_barrier(const XcdBarrier& b) {
;     asm volatile("s_waitcnt vmcnt(0)" ::: "memory");
;     __syncthreads();
;     if (b.tid == 0u) {
;         unsigned* bar = b.bar;
;         __builtin_amdgcn_s_waitcnt(0);
;         unsigned nloc = b.st[0], nx = b.st[1];
;         if (nloc == 0u) { xcd_barrier_complete(bar, b.x, nloc, nx); b.st[0] = nloc; b.st[1] = nx; }
.LBB0_4587:
	s_mov_b64 s[2:3], s[88:89]
	s_getreg_b32 s4, hwreg(HW_REG_XCC_ID, 0, 4)
	s_waitcnt vmcnt(0)
	s_setprio 0
	s_barrier
	s_mov_b64 s[0:1], exec
	v_readlane_b32 s6, v252, 2
	v_readlane_b32 s7, v252, 3
	s_and_b64 s[6:7], s[0:1], s[6:7]
	s_mov_b64 exec, s[6:7]
	s_cbranch_execz .LBB0_4639
	v_readlane_b32 s5, v252, 13
	s_load_dwordx2 s[2:3], s[2:3], 0x100
	s_waitcnt vmcnt(0) expcnt(0) lgkmcnt(0)
	v_mov_b32_e32 v1, s5
	ds_read_b32 v3, v1
	v_readlane_b32 s5, v252, 14
	s_and_b32 s46, s4, 15
	s_waitcnt lgkmcnt(0)
	v_cmp_ne_u32_e32 vcc, 0, v3
	v_mov_b32_e32 v1, s5
	ds_read_b32 v2, v1
	s_cbranch_vccnz .LBB0_4603
	s_add_u32 s4, s2, 0x17900200
	s_addc_u32 s5, s3, 0
	s_add_u32 s6, s2, 0x17900400
	s_addc_u32 s7, s3, 0
	s_add_u32 s8, s2, 0x17900500
	s_addc_u32 s9, s3, 0
	s_add_u32 s10, s2, 0x17900600
	s_addc_u32 s11, s3, 0
	s_add_u32 s12, s2, 0x17900700
	s_addc_u32 s13, s3, 0
	s_add_u32 s14, s2, 0x17900800
	s_addc_u32 s15, s3, 0
	s_add_u32 s16, s2, 0x17900900
	s_addc_u32 s17, s3, 0
	s_add_u32 s18, s2, 0x17900a00
	s_addc_u32 s19, s3, 0
	s_add_u32 s20, s2, 0x17900b00
	s_addc_u32 s21, s3, 0
	s_add_u32 s22, s2, 0x17900c00
	s_addc_u32 s23, s3, 0
	s_add_u32 s24, s2, 0x17900d00
	s_addc_u32 s25, s3, 0
	s_add_u32 s26, s2, 0x17900e00
	s_addc_u32 s27, s3, 0
	s_add_u32 s28, s2, 0x17900f00
	s_addc_u32 s29, s3, 0
	s_add_u32 s30, s2, 0x17901000
	s_addc_u32 s31, s3, 0
	s_add_u32 s34, s2, 0x17901100
	s_addc_u32 s35, s3, 0
	s_add_u32 s36, s2, 0x17901200
	s_addc_u32 s37, s3, 0
	s_add_u32 s38, s2, 0x17901300
	s_addc_u32 s39, s3, 0
	s_mov_b32 s47, 1
	s_branch .LBB0_4591

; #define KA_DEF const __attribute__((address_space(4))) KArgs* ka_ = (const __attribute__((address_space(4))) KArgs*)__builtin_amdgcn_kernarg_segment_ptr(); asm volatile("" : "+s"(ka_));
; #define SSQ ((float*)WSP(WS_SSQ))
;     __host__ __device__ bool next(int i, Unit& u) const {
;         const long L = (long)i * G + c; if (L >= nwg) return false;
;         int wgid = (int)L; { const int q = nwg / NXCD, r = nwg % NXCD, xcd = wgid % NXCD, off = wgid / NXCD; wgid = (xcd < r ? xcd * (q + 1) : r * (q + 1) + (xcd - r) * q) + off; }
;         const int nig = WGM * nN, gid = wgid / nig, fm = gid * WGM, gsz = (nM - fm) < WGM ? (nM - fm) : WGM;
; __global__ void __launch_bounds__(512, 2) mega_fwd(KArgs a) {
;     ...
;         { KA_DEF pg8::EpiResid E{X, X, XB, SSQ, 1.0f}; run_gemm(TIDX, lds, OX, Wl + WO_XO, T_, 1024, 1024, E); }
.Lmy_prio_skip_19:
	s_load_dwordx4 s[8:11], s[0:1], 0xf8
	s_movk_i32 s1, 0x400
	s_movk_i32 s0, 0x400
	s_movk_i32 s4, 0x4000
	s_waitcnt lgkmcnt(0)
	s_add_u32 s2, s10, 0xac00000
	s_addc_u32 s3, s11, 0
	s_add_u32 s12, s10, 0x2300000
	s_addc_u32 s13, s11, 0
	s_ashr_i32 s5, s4, 31
	s_lshr_b32 s5, s5, 24
	s_add_i32 s4, s4, s5
	s_ashr_i32 s36, s4, 8
	s_ashr_i32 s4, s1, 31
	s_lshr_b32 s4, s4, 24
	s_add_i32 s1, s1, s4
	s_ashr_i32 s28, s1, 8
	s_mul_i32 s14, s28, s36
	v_mov_b32_e32 v14, v220
	s_cmp_lt_i32 s86, s14
	s_cselect_b64 s[4:5], -1, 0
	s_cmp_ge_i32 s86, s14
	v_readfirstlane_b32 s15, v14
	s_cbranch_scc1 .LBB0_4730
	s_ashr_i32 s1, s14, 31
	s_lshr_b32 s1, s1, 29
	s_add_i32 s1, s14, s1
	s_ashr_i32 s17, s1, 3
	s_and_b32 s1, s1, -8
	s_sub_i32 s18, s14, s1
	s_add_i32 s16, s17, 1
	v_readlane_b32 s1, v252, 5
	s_cmp_ge_i32 s1, s18
	s_mov_b64 s[6:7], -1
	s_cbranch_scc0 .LBB0_4727
	v_readlane_b32 s6, v252, 5
	s_sub_i32 s6, s6, s18
	s_mul_i32 s1, s16, s18
	s_mul_i32 s6, s6, s17
	s_add_i32 s1, s6, s1
	s_mov_b64 s[6:7], 0

; __device__ __forceinline__ void xcd_barrier(const XcdBarrier& b) {
;     asm volatile("s_waitcnt vmcnt(0)" ::: "memory");
;     __syncthreads();
;     if (b.tid == 0u) {
;         unsigned* bar = b.bar;
;         __builtin_amdgcn_s_waitcnt(0);
;         unsigned nloc = b.st[0], nx = b.st[1];
;         if (nloc == 0u) { xcd_barrier_complete(bar, b.x, nloc, nx); b.st[0] = nloc; b.st[1] = nx; }
.LBB0_4771:
	s_mov_b64 s[2:3], s[88:89]
	s_getreg_b32 s4, hwreg(HW_REG_XCC_ID, 0, 4)
	s_waitcnt vmcnt(0)
	s_waitcnt lgkmcnt(0)
	s_setprio 0
	s_barrier
	s_mov_b64 s[0:1], exec
	v_readlane_b32 s6, v252, 2
	v_readlane_b32 s7, v252, 3
	s_and_b64 s[6:7], s[0:1], s[6:7]
	s_mov_b64 exec, s[6:7]
	s_cbranch_execz .LBB0_4823
	v_readlane_b32 s5, v252, 13
	s_load_dwordx2 s[2:3], s[2:3], 0x100
	s_waitcnt vmcnt(0) expcnt(0) lgkmcnt(0)
	v_mov_b32_e32 v1, s5
	ds_read_b32 v3, v1
	v_readlane_b32 s5, v252, 14
	s_and_b32 s46, s4, 15
	s_waitcnt lgkmcnt(0)
	v_cmp_ne_u32_e32 vcc, 0, v3
	v_mov_b32_e32 v1, s5
	ds_read_b32 v2, v1
	s_cbranch_vccnz .LBB0_4787
	s_add_u32 s4, s2, 0x17900200
	s_addc_u32 s5, s3, 0
	s_add_u32 s6, s2, 0x17900400
	s_addc_u32 s7, s3, 0
	s_add_u32 s8, s2, 0x17900500
	s_addc_u32 s9, s3, 0
	s_add_u32 s10, s2, 0x17900600
	s_addc_u32 s11, s3, 0
	s_add_u32 s12, s2, 0x17900700
	s_addc_u32 s13, s3, 0
	s_add_u32 s14, s2, 0x17900800
	s_addc_u32 s15, s3, 0
	s_add_u32 s16, s2, 0x17900900
	s_addc_u32 s17, s3, 0
	s_add_u32 s18, s2, 0x17900a00
	s_addc_u32 s19, s3, 0
	s_add_u32 s20, s2, 0x17900b00
	s_addc_u32 s21, s3, 0
	s_add_u32 s22, s2, 0x17900c00
	s_addc_u32 s23, s3, 0
	s_add_u32 s24, s2, 0x17900d00
	s_addc_u32 s25, s3, 0
	s_add_u32 s26, s2, 0x17900e00
	s_addc_u32 s27, s3, 0
	s_add_u32 s28, s2, 0x17900f00
	s_addc_u32 s29, s3, 0
	s_add_u32 s30, s2, 0x17901000
	s_addc_u32 s31, s3, 0
	s_add_u32 s34, s2, 0x17901100
	s_addc_u32 s35, s3, 0
	s_add_u32 s36, s2, 0x17901200
	s_addc_u32 s37, s3, 0
	s_add_u32 s38, s2, 0x17901300
	s_addc_u32 s39, s3, 0
	s_mov_b32 s47, 1
	s_branch .LBB0_4775

; #define KA_DEF const __attribute__((address_space(4))) KArgs* ka_ = (const __attribute__((address_space(4))) KArgs*)__builtin_amdgcn_kernarg_segment_ptr(); asm volatile("" : "+s"(ka_));
; #define SSQ ((float*)WSP(WS_SSQ))
;     __host__ __device__ bool next(int i, Unit& u) const {
;         const long L = (long)i * G + c; if (L >= nwg) return false;
;         int wgid = (int)L; { const int q = nwg / NXCD, r = nwg % NXCD, xcd = wgid % NXCD, off = wgid / NXCD; wgid = (xcd < r ? xcd * (q + 1) : r * (q + 1) + (xcd - r) * q) + off; }
;         const int nig = WGM * nN, gid = wgid / nig, fm = gid * WGM, gsz = (nM - fm) < WGM ? (nM - fm) : WGM;
; __global__ void __launch_bounds__(512, 2) mega_fwd(KArgs a) {
;     ...
;         { KA_DEF pg8::EpiSwiGLU E{RA, FF, SSQ}; run_gemm(TIDX, lds, XB, Wl + WO_13B, T_, 2 * FF, 1024, E); }
.Lmy_prio_skip_20:
	s_load_dwordx2 s[0:1], s[0:1], 0x100
	s_movk_i32 s4, 0x400
	s_movk_i32 s5, 0x1600
	s_movk_i32 s8, 0x4000
	s_waitcnt lgkmcnt(0)
	s_add_u32 s2, s0, 0x6000000
	s_addc_u32 s3, s1, 0
	s_add_u32 s6, s0, 0x1080000
	s_addc_u32 s7, s1, 0
	s_ashr_i32 s9, s8, 31
	s_lshr_b32 s9, s9, 24
	s_add_i32 s8, s8, s9
	s_ashr_i32 s28, s8, 8
	s_ashr_i32 s8, s5, 31
	s_lshr_b32 s8, s8, 24
	s_add_i32 s5, s5, s8
	s_ashr_i32 s14, s5, 8
	s_mul_i32 s8, s14, s28
	v_mov_b32_e32 v14, v220
	s_cmp_ge_i32 s86, s8
	v_readfirstlane_b32 s20, v14
	s_cbranch_scc1 .LBB0_4852
	s_ashr_i32 s9, s8, 31
	s_lshr_b32 s5, s9, 29
	s_add_i32 s5, s8, s5
	s_ashr_i32 s29, s5, 3
	s_and_b32 s5, s5, -8
	s_sub_i32 s30, s8, s5
	s_add_i32 s31, s29, 1
	v_readlane_b32 s5, v252, 5
	s_cmp_ge_i32 s5, s30
	s_mov_b64 s[10:11], -1
	s_mul_i32 s34, s31, s30
	s_cbranch_scc0 .LBB0_4826
	v_readlane_b32 s5, v252, 5
	s_sub_i32 s5, s5, s30
	s_mul_i32 s5, s5, s29
	s_add_i32 s15, s5, s34
	s_mov_b64 s[10:11], 0

; #define PG8_STAGE(bufoff, gbase, voff) do { _Pragma("unroll") for (int _i = 0; _i < 2; ++_i) \
;         __builtin_amdgcn_global_load_lds((const unsigned*)((const char*)(gbase) + (voff)[_i]), (PG8_LAS unsigned*)(lds + (bufoff) + ldsw + _i * 8192), 16, 0, 0); } while (0)
; #define PG8_LDA(dst, b, h) do { _Pragma("unroll") for (int m = 0; m < 4; ++m) _Pragma("unroll") for (int k = 0; k < 2; ++k) dst[m][k] = *(const PG8_LAS bf16x8*)(lds + PG8_SA(b, h) + aoff + m * 2048 + k * 1024); } while (0)
; #define PG8_LDB(dst, b, h) do { _Pragma("unroll") for (int n = 0; n < 2; ++n) _Pragma("unroll") for (int k = 0; k < 2; ++k) dst[n][k] = *(const PG8_LAS bf16x8*)(lds + PG8_SB(b, h) + boff + n * 2048 + k * 1024); } while (0)
; #define PG8_MMA(ai, bj, At, Bt) do { __builtin_amdgcn_s_setprio(1); _Pragma("unroll") for (int m = 0; m < 4; ++m) _Pragma("unroll") for (int n = 0; n < 2; ++n) _Pragma("unroll") for (int k = 0; k < 2; ++k) \
;         acc[ai][bj][m][n] = __builtin_amdgcn_mfma_f32_16x16x32_bf16(Bt[n][k], At[m][k], acc[ai][bj][m][n], 0, 0, 0); __builtin_amdgcn_s_setprio(0); } while (0)
; #define PG8_WAIT_V(n) asm volatile("s_waitcnt vmcnt(" #n ")" ::: "memory")
; #define PG8_WAIT_L(n) asm volatile("s_waitcnt lgkmcnt(" #n ")" ::: "memory")
; #define PG8_BAR __builtin_amdgcn_s_barrier()
; #define PG8_SCHED __builtin_amdgcn_sched_barrier(0)
; template <class Epi, class Sched, bool ALIGN_EPI = false, bool SP2 = false>
; __device__ __forceinline__ void gemm_phase(PG8_LAS unsigned char* lds, const Gemm g, const Sched& S, const Epi& E) {
;     ...
;             const bool last = (t == nt - 2);
;             const char* a1 = cA + (size_t)(t + 1) * kstep;
;             const char* a2 = last ? nA : cA + (size_t)(t + 2) * kstep; const char* b2 = last ? nB : cB + (size_t)(t + 2) * kstep;
;             const char* a3 = a2 + kstep; const char* b3 = b2 + kstep;
;             if (last && has_next) S.a_ready(nxt);
;             if constexpr (SP2) {
;             PG8_LDB(B0, 0, 0); PG8_LDB(B1, 0, 1); PG8_SCHED; PG8_LDA(At, 0, 0); PG8_STAGE(PG8_SA(1, 1), a1 + hstep, voffA);
;             PG8_WAIT_V(8); PG8_WAIT_L(0); PG8_BAR; PG8_MMA(0, 0, At, B0); PG8_MMA(0, 1, At, B1); PG8_BAR; PG8_SCHED;
;             PG8_LDA(At, 0, 1); PG8_STAGE(PG8_SB(0, 0), b2, voffB); PG8_STAGE(PG8_SB(0, 1), b2 + hstep, voffB); PG8_STAGE(PG8_SA(0, 0), a2, voffA);
.LBB0_4845:
	s_add_i32 s55, s26, 2
	s_add_u32 s56, s24, 0x80
	s_addc_u32 s27, s25, 0
	s_add_i32 s58, 0, 0x10000
	s_cmp_eq_u32 s47, s26
	s_cselect_b32 s27, s1, s27
	s_cselect_b32 s26, s0, s56
	v_add_u32_e32 v148, s58, v151
	s_cselect_b32 s57, s23, s54
	s_cselect_b32 s56, s22, s53
	s_add_i32 s59, 0, 0x14000
	ds_read_b128 v[130:133], v148
	ds_read_b128 v[156:159], v148 offset:1024
	ds_read_b128 v[162:165], v148 offset:2048
	ds_read_b128 v[166:169], v148 offset:3072
	v_add_u32_e32 v148, s59, v151
	ds_read_b128 v[170:173], v148
	ds_read_b128 v[174:177], v148 offset:1024
	ds_read_b128 v[178:181], v148 offset:2048
	ds_read_b128 v[182:185], v148 offset:3072
	v_lshl_add_u64 v[148:149], s[24:25], 0, v[146:147]
	s_add_i32 m0, s40, 0xc000
	ds_read_b128 v[186:189], v161
	ds_read_b128 v[190:193], v161 offset:1024
	ds_read_b128 v[194:197], v161 offset:2048
	ds_read_b128 v[198:201], v161 offset:3072
	ds_read_b128 v[202:205], v161 offset:4096
	ds_read_b128 v[206:209], v161 offset:5120
	ds_read_b128 v[210:213], v161 offset:6144
	ds_read_b128 v[214:217], v161 offset:7168
	global_load_lds_dwordx4 v[148:149], off
	v_lshl_add_u64 v[148:149], s[24:25], 0, v[144:145]
	s_add_i32 m0, s40, 0xe000
	s_nop 0
	global_load_lds_dwordx4 v[148:149], off
	s_waitcnt vmcnt(8)
	s_waitcnt lgkmcnt(0)
	s_barrier
	s_nop 0
	s_waitcnt lgkmcnt(0)
	v_mfma_f32_16x16x32_bf16 v[122:125], v[130:133], v[186:189], v[122:125]
	v_mfma_f32_16x16x32_bf16 v[126:129], v[162:165], v[186:189], v[126:129]
	v_mfma_f32_16x16x32_bf16 v[110:113], v[130:133], v[194:197], v[110:113]
	v_mfma_f32_16x16x32_bf16 v[106:109], v[162:165], v[194:197], v[106:109]
	v_mfma_f32_16x16x32_bf16 v[94:97], v[130:133], v[202:205], v[94:97]
	v_mfma_f32_16x16x32_bf16 v[90:93], v[162:165], v[202:205], v[90:93]
	v_mfma_f32_16x16x32_bf16 v[78:81], v[130:133], v[210:213], v[78:81]
	v_mfma_f32_16x16x32_bf16 v[74:77], v[162:165], v[210:213], v[74:77]
	v_mfma_f32_16x16x32_bf16 v[122:125], v[156:159], v[190:193], v[122:125]
	v_mfma_f32_16x16x32_bf16 v[126:129], v[166:169], v[190:193], v[126:129]
	v_mfma_f32_16x16x32_bf16 v[110:113], v[156:159], v[198:201], v[110:113]
	v_mfma_f32_16x16x32_bf16 v[106:109], v[166:169], v[198:201], v[106:109]
	v_mfma_f32_16x16x32_bf16 v[94:97], v[156:159], v[206:209], v[94:97]
	v_mfma_f32_16x16x32_bf16 v[90:93], v[166:169], v[206:209], v[90:93]
	v_mfma_f32_16x16x32_bf16 v[78:81], v[156:159], v[214:217], v[78:81]
	v_mfma_f32_16x16x32_bf16 v[74:77], v[166:169], v[214:217], v[74:77]
	s_nop 0
	s_nop 0
	v_mfma_f32_16x16x32_bf16 v[118:121], v[170:173], v[186:189], v[118:121]
	v_mfma_f32_16x16x32_bf16 v[114:117], v[178:181], v[186:189], v[114:117]
	v_mfma_f32_16x16x32_bf16 v[102:105], v[170:173], v[194:197], v[102:105]
	v_mfma_f32_16x16x32_bf16 v[98:101], v[178:181], v[194:197], v[98:101]
	v_mfma_f32_16x16x32_bf16 v[86:89], v[170:173], v[202:205], v[86:89]
	v_mfma_f32_16x16x32_bf16 v[82:85], v[178:181], v[202:205], v[82:85]
	v_mfma_f32_16x16x32_bf16 v[70:73], v[170:173], v[210:213], v[70:73]
	v_mfma_f32_16x16x32_bf16 v[66:69], v[178:181], v[210:213], v[66:69]
	v_mfma_f32_16x16x32_bf16 v[118:121], v[174:177], v[190:193], v[118:121]
	v_mfma_f32_16x16x32_bf16 v[114:117], v[182:185], v[190:193], v[114:117]
	v_mfma_f32_16x16x32_bf16 v[102:105], v[174:177], v[198:201], v[102:105]
	v_mfma_f32_16x16x32_bf16 v[98:101], v[182:185], v[198:201], v[98:101]
	v_mfma_f32_16x16x32_bf16 v[86:89], v[174:177], v[206:209], v[86:89]
	v_mfma_f32_16x16x32_bf16 v[82:85], v[182:185], v[206:209], v[82:85]
	v_mfma_f32_16x16x32_bf16 v[70:73], v[174:177], v[214:217], v[70:73]
	v_mfma_f32_16x16x32_bf16 v[66:69], v[182:185], v[214:217], v[66:69]
	s_nop 0
	s_barrier
	s_add_i32 s58, s58, s35
	v_lshl_add_u64 v[148:149], s[56:57], 0, v[136:137]
	s_mov_b32 m0, s58
	ds_read_b128 v[186:189], v161 offset:16384
	ds_read_b128 v[190:193], v161 offset:17408
	ds_read_b128 v[194:197], v161 offset:18432
	ds_read_b128 v[198:201], v161 offset:19456
	ds_read_b128 v[202:205], v161 offset:20480
	ds_read_b128 v[206:209], v161 offset:21504
	ds_read_b128 v[210:213], v161 offset:22528
	ds_read_b128 v[214:217], v161 offset:23552
	global_load_lds_dwordx4 v[148:149], off
	s_add_i32 m0, s58, 0x2000
	v_lshl_add_u64 v[152:153], s[56:57], 0, v[140:141]
	s_add_u32 s56, s56, s10
	s_addc_u32 s57, s57, s11
	s_add_i32 s58, s59, s35
	global_load_lds_dwordx4 v[152:153], off
	v_lshl_add_u64 v[218:219], s[56:57], 0, v[136:137]
	s_mov_b32 m0, s58
	v_lshl_add_u64 v[228:229], s[56:57], 0, v[140:141]
	global_load_lds_dwordx4 v[218:219], off
	s_add_i32 m0, s58, 0x2000
	v_lshl_add_u64 v[242:243], s[26:27], 0, v[134:135]
	global_load_lds_dwordx4 v[228:229], off
	s_mov_b32 m0, s40
	v_lshl_add_u64 v[244:245], s[26:27], 0, v[138:139]
	global_load_lds_dwordx4 v[242:243], off
	s_mov_b32 m0, s41
	s_nop 0
	global_load_lds_dwordx4 v[244:245], off
	s_waitcnt vmcnt(8)
	s_waitcnt lgkmcnt(0)
	s_barrier
; #define PG8_STAGE(bufoff, gbase, voff) do { _Pragma("unroll") for (int _i = 0; _i < 2; ++_i) \
;         __builtin_amdgcn_global_load_lds((const unsigned*)((const char*)(gbase) + (voff)[_i]), (PG8_LAS unsigned*)(lds + (bufoff) + ldsw + _i * 8192), 16, 0, 0); } while (0)
; #define PG8_LDA(dst, b, h) do { _Pragma("unroll") for (int m = 0; m < 4; ++m) _Pragma("unroll") for (int k = 0; k < 2; ++k) dst[m][k] = *(const PG8_LAS bf16x8*)(lds + PG8_SA(b, h) + aoff + m * 2048 + k * 1024); } while (0)
; #define PG8_LDB(dst, b, h) do { _Pragma("unroll") for (int n = 0; n < 2; ++n) _Pragma("unroll") for (int k = 0; k < 2; ++k) dst[n][k] = *(const PG8_LAS bf16x8*)(lds + PG8_SB(b, h) + boff + n * 2048 + k * 1024); } while (0)
; #define PG8_MMA(ai, bj, At, Bt) do { __builtin_amdgcn_s_setprio(1); _Pragma("unroll") for (int m = 0; m < 4; ++m) _Pragma("unroll") for (int n = 0; n < 2; ++n) _Pragma("unroll") for (int k = 0; k < 2; ++k) \
;         acc[ai][bj][m][n] = __builtin_amdgcn_mfma_f32_16x16x32_bf16(Bt[n][k], At[m][k], acc[ai][bj][m][n], 0, 0, 0); __builtin_amdgcn_s_setprio(0); } while (0)
; #define PG8_WAIT_V(n) asm volatile("s_waitcnt vmcnt(" #n ")" ::: "memory")
; #define PG8_WAIT_L(n) asm volatile("s_waitcnt lgkmcnt(" #n ")" ::: "memory")
; #define PG8_BAR __builtin_amdgcn_s_barrier()
; #define PG8_SCHED __builtin_amdgcn_sched_barrier(0)
; template <class Epi, class Sched, bool ALIGN_EPI = false, bool SP2 = false>
; __device__ __forceinline__ void gemm_phase(PG8_LAS unsigned char* lds, const Gemm g, const Sched& S, const Epi& E) {
;     ...
;             PG8_WAIT_V(8); PG8_WAIT_L(0); PG8_BAR; PG8_MMA(1, 0, At, B0); PG8_MMA(1, 1, At, B1); PG8_BAR; PG8_SCHED;
;             PG8_LDB(B0, 1, 0); PG8_LDB(B1, 1, 1); PG8_SCHED; PG8_LDA(At, 1, 0); PG8_STAGE(PG8_SA(0, 1), a2 + hstep, voffA);
;             PG8_WAIT_V(8); PG8_WAIT_L(0); PG8_BAR; PG8_MMA(0, 0, At, B0); PG8_MMA(0, 1, At, B1); PG8_BAR; PG8_SCHED;
	s_nop 0
	s_waitcnt lgkmcnt(0)
	v_mfma_f32_16x16x32_bf16 v[62:65], v[130:133], v[186:189], v[62:65]
	v_mfma_f32_16x16x32_bf16 v[58:61], v[162:165], v[186:189], v[58:61]
	v_mfma_f32_16x16x32_bf16 v[46:49], v[130:133], v[194:197], v[46:49]
	v_mfma_f32_16x16x32_bf16 v[42:45], v[162:165], v[194:197], v[42:45]
	v_mfma_f32_16x16x32_bf16 v[30:33], v[130:133], v[202:205], v[30:33]
	v_mfma_f32_16x16x32_bf16 v[26:29], v[162:165], v[202:205], v[26:29]
	v_mfma_f32_16x16x32_bf16 v[14:17], v[130:133], v[210:213], v[14:17]
	v_mfma_f32_16x16x32_bf16 v[10:13], v[162:165], v[210:213], v[10:13]
	v_mfma_f32_16x16x32_bf16 v[62:65], v[156:159], v[190:193], v[62:65]
	v_mfma_f32_16x16x32_bf16 v[58:61], v[166:169], v[190:193], v[58:61]
	v_mfma_f32_16x16x32_bf16 v[46:49], v[156:159], v[198:201], v[46:49]
	v_mfma_f32_16x16x32_bf16 v[42:45], v[166:169], v[198:201], v[42:45]
	v_mfma_f32_16x16x32_bf16 v[30:33], v[156:159], v[206:209], v[30:33]
	v_mfma_f32_16x16x32_bf16 v[26:29], v[166:169], v[206:209], v[26:29]
	v_mfma_f32_16x16x32_bf16 v[14:17], v[156:159], v[214:217], v[14:17]
	v_mfma_f32_16x16x32_bf16 v[10:13], v[166:169], v[214:217], v[10:13]
	s_nop 0
	s_nop 0
	v_mfma_f32_16x16x32_bf16 v[54:57], v[170:173], v[186:189], v[54:57]
	v_mfma_f32_16x16x32_bf16 v[50:53], v[178:181], v[186:189], v[50:53]
	v_mfma_f32_16x16x32_bf16 v[38:41], v[170:173], v[194:197], v[38:41]
	v_mfma_f32_16x16x32_bf16 v[34:37], v[178:181], v[194:197], v[34:37]
	v_mfma_f32_16x16x32_bf16 v[22:25], v[170:173], v[202:205], v[22:25]
	v_mfma_f32_16x16x32_bf16 v[18:21], v[178:181], v[202:205], v[18:21]
	v_mfma_f32_16x16x32_bf16 v[6:9], v[170:173], v[210:213], v[6:9]
	v_mfma_f32_16x16x32_bf16 v[2:5], v[178:181], v[210:213], v[2:5]
	v_mfma_f32_16x16x32_bf16 v[54:57], v[174:177], v[190:193], v[54:57]
	v_mfma_f32_16x16x32_bf16 v[50:53], v[182:185], v[190:193], v[50:53]
	v_mfma_f32_16x16x32_bf16 v[38:41], v[174:177], v[198:201], v[38:41]
	v_mfma_f32_16x16x32_bf16 v[34:37], v[182:185], v[198:201], v[34:37]
	v_mfma_f32_16x16x32_bf16 v[22:25], v[174:177], v[206:209], v[22:25]
	v_mfma_f32_16x16x32_bf16 v[18:21], v[182:185], v[206:209], v[18:21]
	v_mfma_f32_16x16x32_bf16 v[6:9], v[174:177], v[214:217], v[6:9]
	v_mfma_f32_16x16x32_bf16 v[2:5], v[182:185], v[214:217], v[2:5]
	s_nop 0
	s_barrier
	s_add_i32 s56, 0, 0x18000
	v_add_u32_e32 v150, s56, v151
	s_add_i32 s57, 0, 0x1c000
	ds_read_b128 v[130:133], v150
	ds_read_b128 v[156:159], v150 offset:1024
	ds_read_b128 v[162:165], v150 offset:2048
	ds_read_b128 v[166:169], v150 offset:3072
	v_add_u32_e32 v150, s57, v151
	ds_read_b128 v[170:173], v150
	ds_read_b128 v[174:177], v150 offset:1024
	ds_read_b128 v[178:181], v150 offset:2048
	ds_read_b128 v[182:185], v150 offset:3072
	s_add_u32 s26, s26, s10
	s_addc_u32 s27, s27, s11
	s_mov_b32 m0, s42
	v_lshl_add_u64 v[246:247], s[26:27], 0, v[134:135]
	ds_read_b128 v[186:189], v161 offset:32768
	ds_read_b128 v[190:193], v161 offset:33792
	ds_read_b128 v[194:197], v161 offset:34816
	ds_read_b128 v[198:201], v161 offset:35840
	ds_read_b128 v[202:205], v161 offset:36864
	ds_read_b128 v[206:209], v161 offset:37888
	ds_read_b128 v[210:213], v161 offset:38912
	ds_read_b128 v[214:217], v161 offset:39936
	global_load_lds_dwordx4 v[246:247], off
	v_lshl_add_u64 v[246:247], s[26:27], 0, v[138:139]
	s_mov_b32 m0, s43
	s_nop 0
	global_load_lds_dwordx4 v[246:247], off
	s_waitcnt vmcnt(8)
	s_waitcnt lgkmcnt(0)
	s_barrier
	s_nop 0
	s_waitcnt lgkmcnt(0)
	v_mfma_f32_16x16x32_bf16 v[122:125], v[130:133], v[186:189], v[122:125]
	v_mfma_f32_16x16x32_bf16 v[126:129], v[162:165], v[186:189], v[126:129]
	v_mfma_f32_16x16x32_bf16 v[110:113], v[130:133], v[194:197], v[110:113]
	v_mfma_f32_16x16x32_bf16 v[106:109], v[162:165], v[194:197], v[106:109]
	v_mfma_f32_16x16x32_bf16 v[94:97], v[130:133], v[202:205], v[94:97]
	v_mfma_f32_16x16x32_bf16 v[90:93], v[162:165], v[202:205], v[90:93]
	v_mfma_f32_16x16x32_bf16 v[78:81], v[130:133], v[210:213], v[78:81]
	v_mfma_f32_16x16x32_bf16 v[74:77], v[162:165], v[210:213], v[74:77]
	v_mfma_f32_16x16x32_bf16 v[122:125], v[156:159], v[190:193], v[122:125]
	v_mfma_f32_16x16x32_bf16 v[126:129], v[166:169], v[190:193], v[126:129]
	v_mfma_f32_16x16x32_bf16 v[110:113], v[156:159], v[198:201], v[110:113]
	v_mfma_f32_16x16x32_bf16 v[106:109], v[166:169], v[198:201], v[106:109]
	v_mfma_f32_16x16x32_bf16 v[94:97], v[156:159], v[206:209], v[94:97]
	v_mfma_f32_16x16x32_bf16 v[90:93], v[166:169], v[206:209], v[90:93]
	v_mfma_f32_16x16x32_bf16 v[78:81], v[156:159], v[214:217], v[78:81]
	v_mfma_f32_16x16x32_bf16 v[74:77], v[166:169], v[214:217], v[74:77]
	s_nop 0
	s_nop 0
	v_mfma_f32_16x16x32_bf16 v[118:121], v[170:173], v[186:189], v[118:121]
	v_mfma_f32_16x16x32_bf16 v[114:117], v[178:181], v[186:189], v[114:117]
	v_mfma_f32_16x16x32_bf16 v[102:105], v[170:173], v[194:197], v[102:105]
	v_mfma_f32_16x16x32_bf16 v[98:101], v[178:181], v[194:197], v[98:101]
	v_mfma_f32_16x16x32_bf16 v[86:89], v[170:173], v[202:205], v[86:89]
	v_mfma_f32_16x16x32_bf16 v[82:85], v[178:181], v[202:205], v[82:85]
	v_mfma_f32_16x16x32_bf16 v[70:73], v[170:173], v[210:213], v[70:73]
	v_mfma_f32_16x16x32_bf16 v[66:69], v[178:181], v[210:213], v[66:69]
	v_mfma_f32_16x16x32_bf16 v[118:121], v[174:177], v[190:193], v[118:121]
	v_mfma_f32_16x16x32_bf16 v[114:117], v[182:185], v[190:193], v[114:117]
	v_mfma_f32_16x16x32_bf16 v[102:105], v[174:177], v[198:201], v[102:105]
	v_mfma_f32_16x16x32_bf16 v[98:101], v[182:185], v[198:201], v[98:101]
	v_mfma_f32_16x16x32_bf16 v[86:89], v[174:177], v[206:209], v[86:89]
	v_mfma_f32_16x16x32_bf16 v[82:85], v[182:185], v[206:209], v[82:85]
	v_mfma_f32_16x16x32_bf16 v[70:73], v[174:177], v[214:217], v[70:73]
	v_mfma_f32_16x16x32_bf16 v[66:69], v[182:185], v[214:217], v[66:69]
	s_nop 0
	s_barrier
; #define PG8_STAGE(bufoff, gbase, voff) do { _Pragma("unroll") for (int _i = 0; _i < 2; ++_i) \
;         __builtin_amdgcn_global_load_lds((const unsigned*)((const char*)(gbase) + (voff)[_i]), (PG8_LAS unsigned*)(lds + (bufoff) + ldsw + _i * 8192), 16, 0, 0); } while (0)
; #define PG8_LDA(dst, b, h) do { _Pragma("unroll") for (int m = 0; m < 4; ++m) _Pragma("unroll") for (int k = 0; k < 2; ++k) dst[m][k] = *(const PG8_LAS bf16x8*)(lds + PG8_SA(b, h) + aoff + m * 2048 + k * 1024); } while (0)
; #define PG8_MMA(ai, bj, At, Bt) do { __builtin_amdgcn_s_setprio(1); _Pragma("unroll") for (int m = 0; m < 4; ++m) _Pragma("unroll") for (int n = 0; n < 2; ++n) _Pragma("unroll") for (int k = 0; k < 2; ++k) \
;         acc[ai][bj][m][n] = __builtin_amdgcn_mfma_f32_16x16x32_bf16(Bt[n][k], At[m][k], acc[ai][bj][m][n], 0, 0, 0); __builtin_amdgcn_s_setprio(0); } while (0)
; #define PG8_WAIT_V(n) asm volatile("s_waitcnt vmcnt(" #n ")" ::: "memory")
; #define PG8_WAIT_L(n) asm volatile("s_waitcnt lgkmcnt(" #n ")" ::: "memory")
; #define PG8_BAR __builtin_amdgcn_s_barrier()
; #define PG8_SCHED __builtin_amdgcn_sched_barrier(0)
; template <class Epi, class Sched, bool ALIGN_EPI = false, bool SP2 = false>
; __device__ __forceinline__ void gemm_phase(PG8_LAS unsigned char* lds, const Gemm g, const Sched& S, const Epi& E) {
;     ...
;         for (int t = 0; t < nt; t += 2) {
;     ...
;             PG8_LDA(At, 1, 1); PG8_STAGE(PG8_SB(1, 0), b3, voffB); PG8_STAGE(PG8_SB(1, 1), b3 + hstep, voffB); PG8_STAGE(PG8_SA(1, 0), a3, voffA);
;             PG8_WAIT_V(8); PG8_WAIT_L(0); PG8_BAR; PG8_MMA(1, 0, At, B0); PG8_MMA(1, 1, At, B1); PG8_BAR; PG8_SCHED;
	s_add_i32 s26, s56, s35
	v_lshl_add_u64 v[148:149], v[148:149], 0, s[92:93]
	s_mov_b32 m0, s26
	ds_read_b128 v[186:189], v161 offset:49152
	ds_read_b128 v[190:193], v161 offset:50176
	ds_read_b128 v[194:197], v161 offset:51200
	ds_read_b128 v[198:201], v161 offset:52224
	ds_read_b128 v[202:205], v161 offset:53248
	ds_read_b128 v[206:209], v161 offset:54272
	ds_read_b128 v[210:213], v161 offset:55296
	ds_read_b128 v[214:217], v161 offset:56320
	global_load_lds_dwordx4 v[148:149], off
	v_lshl_add_u64 v[148:149], v[152:153], 0, s[92:93]
	s_add_i32 m0, s26, 0x2000
	s_add_i32 s26, s57, s35
	global_load_lds_dwordx4 v[148:149], off
	v_lshl_add_u64 v[148:149], v[218:219], 0, s[92:93]
	s_mov_b32 m0, s26
	s_nop 0
	global_load_lds_dwordx4 v[148:149], off
	v_lshl_add_u64 v[148:149], v[228:229], 0, s[92:93]
	s_add_i32 m0, s26, 0x2000
	s_nop 0
	global_load_lds_dwordx4 v[148:149], off
	v_lshl_add_u64 v[148:149], v[242:243], 0, s[92:93]
	s_mov_b32 m0, s44
	s_nop 0
	global_load_lds_dwordx4 v[148:149], off
	v_lshl_add_u64 v[148:149], v[244:245], 0, s[92:93]
	s_mov_b32 m0, s45
	s_nop 0
	global_load_lds_dwordx4 v[148:149], off
	s_waitcnt vmcnt(8)
	s_waitcnt lgkmcnt(0)
	s_barrier
	s_nop 0
	s_waitcnt lgkmcnt(0)
	v_mfma_f32_16x16x32_bf16 v[62:65], v[130:133], v[186:189], v[62:65]
	v_mfma_f32_16x16x32_bf16 v[58:61], v[162:165], v[186:189], v[58:61]
	v_mfma_f32_16x16x32_bf16 v[46:49], v[130:133], v[194:197], v[46:49]
	v_mfma_f32_16x16x32_bf16 v[42:45], v[162:165], v[194:197], v[42:45]
	v_mfma_f32_16x16x32_bf16 v[30:33], v[130:133], v[202:205], v[30:33]
	v_mfma_f32_16x16x32_bf16 v[26:29], v[162:165], v[202:205], v[26:29]
	v_mfma_f32_16x16x32_bf16 v[14:17], v[130:133], v[210:213], v[14:17]
	v_mfma_f32_16x16x32_bf16 v[10:13], v[162:165], v[210:213], v[10:13]
	v_mfma_f32_16x16x32_bf16 v[62:65], v[156:159], v[190:193], v[62:65]
	v_mfma_f32_16x16x32_bf16 v[58:61], v[166:169], v[190:193], v[58:61]
	v_mfma_f32_16x16x32_bf16 v[46:49], v[156:159], v[198:201], v[46:49]
	v_mfma_f32_16x16x32_bf16 v[42:45], v[166:169], v[198:201], v[42:45]
	v_mfma_f32_16x16x32_bf16 v[30:33], v[156:159], v[206:209], v[30:33]
	v_mfma_f32_16x16x32_bf16 v[26:29], v[166:169], v[206:209], v[26:29]
	v_mfma_f32_16x16x32_bf16 v[14:17], v[156:159], v[214:217], v[14:17]
	v_mfma_f32_16x16x32_bf16 v[10:13], v[166:169], v[214:217], v[10:13]
	s_nop 0
	s_nop 0
	v_mfma_f32_16x16x32_bf16 v[54:57], v[170:173], v[186:189], v[54:57]
	v_mfma_f32_16x16x32_bf16 v[50:53], v[178:181], v[186:189], v[50:53]
	v_mfma_f32_16x16x32_bf16 v[38:41], v[170:173], v[194:197], v[38:41]
	v_mfma_f32_16x16x32_bf16 v[34:37], v[178:181], v[194:197], v[34:37]
	v_mfma_f32_16x16x32_bf16 v[22:25], v[170:173], v[202:205], v[22:25]
	v_mfma_f32_16x16x32_bf16 v[18:21], v[178:181], v[202:205], v[18:21]
	v_mfma_f32_16x16x32_bf16 v[6:9], v[170:173], v[210:213], v[6:9]
	v_mfma_f32_16x16x32_bf16 v[2:5], v[178:181], v[210:213], v[2:5]
	v_mfma_f32_16x16x32_bf16 v[54:57], v[174:177], v[190:193], v[54:57]
	v_mfma_f32_16x16x32_bf16 v[50:53], v[182:185], v[190:193], v[50:53]
	v_mfma_f32_16x16x32_bf16 v[38:41], v[174:177], v[198:201], v[38:41]
	v_mfma_f32_16x16x32_bf16 v[34:37], v[182:185], v[198:201], v[34:37]
	v_mfma_f32_16x16x32_bf16 v[22:25], v[174:177], v[206:209], v[22:25]
	v_mfma_f32_16x16x32_bf16 v[18:21], v[182:185], v[206:209], v[18:21]
	v_mfma_f32_16x16x32_bf16 v[6:9], v[174:177], v[214:217], v[6:9]
	v_mfma_f32_16x16x32_bf16 v[2:5], v[182:185], v[214:217], v[2:5]
	s_nop 0
	s_barrier
	s_add_u32 s53, s53, 0x100
	s_addc_u32 s54, s54, 0
	s_add_u32 s24, s24, 0x100
	s_addc_u32 s25, s25, 0
	s_cmp_ge_i32 s55, s46
	s_mov_b32 s26, s55
	s_cbranch_scc0 .LBB0_4845

; #define KA_DEF const __attribute__((address_space(4))) KArgs* ka_ = (const __attribute__((address_space(4))) KArgs*)__builtin_amdgcn_kernarg_segment_ptr(); asm volatile("" : "+s"(ka_));
; #define SSQ ((float*)WSP(WS_SSQ))
;     __host__ __device__ bool next(int i, Unit& u) const {
;         const long L = (long)i * G + c; if (L >= nwg) return false;
;         int wgid = (int)L; { const int q = nwg / NXCD, r = nwg % NXCD, xcd = wgid % NXCD, off = wgid / NXCD; wgid = (xcd < r ? xcd * (q + 1) : r * (q + 1) + (xcd - r) * q) + off; }
;         const int nig = WGM * nN, gid = wgid / nig, fm = gid * WGM, gsz = (nM - fm) < WGM ? (nM - fm) : WGM;
; __global__ void __launch_bounds__(512, 2) mega_fwd(KArgs a) {
;     ...
;         { KA_DEF pg8::EpiResid E{X, X, XB, SSQ, 0.5f}; run_gemm(TIDX, lds, RA, Wl + WO_2B, T_, 1024, FF, E); }
.Lmy_prio_skip_21:
	s_load_dwordx4 s[8:11], s[0:1], 0xf8
	s_movk_i32 s1, 0x400
	s_movk_i32 s0, 0xb00
	s_movk_i32 s4, 0x4000
	s_waitcnt lgkmcnt(0)
	s_add_u32 s2, s10, 0x8c00000
	s_addc_u32 s3, s11, 0
	s_add_u32 s12, s10, 0x1b80000
	s_addc_u32 s13, s11, 0
	s_ashr_i32 s5, s4, 31
	s_lshr_b32 s5, s5, 24
	s_add_i32 s4, s4, s5
	s_ashr_i32 s36, s4, 8
	s_ashr_i32 s4, s1, 31
	s_lshr_b32 s4, s4, 24
	s_add_i32 s1, s1, s4
	s_ashr_i32 s28, s1, 8
	s_mul_i32 s14, s28, s36
	v_mov_b32_e32 v14, v220
	s_cmp_lt_i32 s86, s14
	s_cselect_b64 s[4:5], -1, 0
	s_cmp_ge_i32 s86, s14
	v_readfirstlane_b32 s15, v14
	s_cbranch_scc1 .LBB0_4910
	s_ashr_i32 s1, s14, 31
	s_lshr_b32 s1, s1, 29
	s_add_i32 s1, s14, s1
	s_ashr_i32 s17, s1, 3
	s_and_b32 s1, s1, -8
	s_sub_i32 s18, s14, s1
	s_add_i32 s16, s17, 1
	v_readlane_b32 s1, v252, 5
	s_cmp_ge_i32 s1, s18
	s_mov_b64 s[6:7], -1
	s_cbranch_scc0 .LBB0_4907
	v_readlane_b32 s6, v252, 5
	s_sub_i32 s6, s6, s18
	s_mul_i32 s1, s16, s18
	s_mul_i32 s6, s6, s17
	s_add_i32 s1, s6, s1
	s_mov_b64 s[6:7], 0

; #define PG8_STAGE(bufoff, gbase, voff) do { _Pragma("unroll") for (int _i = 0; _i < 2; ++_i) \
;         __builtin_amdgcn_global_load_lds((const unsigned*)((const char*)(gbase) + (voff)[_i]), (PG8_LAS unsigned*)(lds + (bufoff) + ldsw + _i * 8192), 16, 0, 0); } while (0)
; #define PG8_LDA(dst, b, h) do { _Pragma("unroll") for (int m = 0; m < 4; ++m) _Pragma("unroll") for (int k = 0; k < 2; ++k) dst[m][k] = *(const PG8_LAS bf16x8*)(lds + PG8_SA(b, h) + aoff + m * 2048 + k * 1024); } while (0)
; #define PG8_LDB(dst, b, h) do { _Pragma("unroll") for (int n = 0; n < 2; ++n) _Pragma("unroll") for (int k = 0; k < 2; ++k) dst[n][k] = *(const PG8_LAS bf16x8*)(lds + PG8_SB(b, h) + boff + n * 2048 + k * 1024); } while (0)
; #define PG8_MMA(ai, bj, At, Bt) do { __builtin_amdgcn_s_setprio(1); _Pragma("unroll") for (int m = 0; m < 4; ++m) _Pragma("unroll") for (int n = 0; n < 2; ++n) _Pragma("unroll") for (int k = 0; k < 2; ++k) \
;         acc[ai][bj][m][n] = __builtin_amdgcn_mfma_f32_16x16x32_bf16(Bt[n][k], At[m][k], acc[ai][bj][m][n], 0, 0, 0); __builtin_amdgcn_s_setprio(0); } while (0)
; #define PG8_WAIT_V(n) asm volatile("s_waitcnt vmcnt(" #n ")" ::: "memory")
; #define PG8_WAIT_L(n) asm volatile("s_waitcnt lgkmcnt(" #n ")" ::: "memory")
; #define PG8_BAR __builtin_amdgcn_s_barrier()
; #define PG8_SCHED __builtin_amdgcn_sched_barrier(0)
; template <class Epi, class Sched, bool ALIGN_EPI = false, bool SP2 = false>
; __device__ __forceinline__ void gemm_phase(PG8_LAS unsigned char* lds, const Gemm g, const Sched& S, const Epi& E) {
;     ...
;             const bool last = (t == nt - 2);
;             const char* a1 = cA + (size_t)(t + 1) * kstep;
;             const char* a2 = last ? nA : cA + (size_t)(t + 2) * kstep; const char* b2 = last ? nB : cB + (size_t)(t + 2) * kstep;
;             const char* a3 = a2 + kstep; const char* b3 = b2 + kstep;
;             if (last && has_next) S.a_ready(nxt);
;             if constexpr (SP2) {
;             PG8_LDB(B0, 0, 0); PG8_LDB(B1, 0, 1); PG8_SCHED; PG8_LDA(At, 0, 0); PG8_STAGE(PG8_SA(1, 1), a1 + hstep, voffA);
;             PG8_WAIT_V(8); PG8_WAIT_L(0); PG8_BAR; PG8_MMA(0, 0, At, B0); PG8_MMA(0, 1, At, B1); PG8_BAR; PG8_SCHED;
;             PG8_LDA(At, 0, 1); PG8_STAGE(PG8_SB(0, 0), b2, voffB); PG8_STAGE(PG8_SB(0, 1), b2 + hstep, voffB); PG8_STAGE(PG8_SA(0, 0), a2, voffA);
.LBB0_4928:
	s_add_i32 s61, s34, 2
	s_add_u32 s62, s30, 0x80
	s_addc_u32 s35, s31, 0
	s_add_i32 s64, 0, 0x10000
	s_cmp_eq_u32 s46, s34
	s_cselect_b32 s35, s1, s35
	s_cselect_b32 s34, s0, s62
	s_cselect_b32 s63, s29, s60
	s_cselect_b32 s62, s28, s59
	s_add_i32 s65, 0, 0x14000
	v_add_u32_e32 v154, s64, v242
	v_add_u32_e32 v170, s65, v242
	ds_read_b128 v[142:145], v154
	ds_read_b128 v[146:149], v154 offset:1024
	ds_read_b128 v[150:153], v154 offset:2048
	ds_read_b128 v[154:157], v154 offset:3072
	ds_read_b128 v[158:161], v170
	ds_read_b128 v[162:165], v170 offset:1024
	ds_read_b128 v[166:169], v170 offset:2048
	ds_read_b128 v[170:173], v170 offset:3072
	v_lshl_add_u64 v[206:207], s[30:31], 0, v[140:141]
	s_add_i32 m0, s38, 0xc000
	ds_read_b128 v[174:177], v244
	ds_read_b128 v[178:181], v244 offset:1024
	ds_read_b128 v[182:185], v244 offset:2048
	ds_read_b128 v[186:189], v244 offset:3072
	ds_read_b128 v[190:193], v244 offset:4096
	ds_read_b128 v[194:197], v244 offset:5120
	ds_read_b128 v[198:201], v244 offset:6144
	ds_read_b128 v[202:205], v244 offset:7168
	global_load_lds_dwordx4 v[206:207], off
	v_lshl_add_u64 v[206:207], s[30:31], 0, v[138:139]
	s_add_i32 m0, s38, 0xe000
	s_nop 0
	global_load_lds_dwordx4 v[206:207], off
	s_waitcnt vmcnt(8)
	s_waitcnt lgkmcnt(0)
	s_barrier
	s_nop 0
	s_waitcnt lgkmcnt(0)
	v_mfma_f32_16x16x32_bf16 v[126:129], v[142:145], v[174:177], v[126:129]
	v_mfma_f32_16x16x32_bf16 v[122:125], v[150:153], v[174:177], v[122:125]
	v_mfma_f32_16x16x32_bf16 v[118:121], v[142:145], v[182:185], v[118:121]
	v_mfma_f32_16x16x32_bf16 v[114:117], v[150:153], v[182:185], v[114:117]
	v_mfma_f32_16x16x32_bf16 v[106:109], v[142:145], v[190:193], v[106:109]
	v_mfma_f32_16x16x32_bf16 v[98:101], v[150:153], v[190:193], v[98:101]
	v_mfma_f32_16x16x32_bf16 v[90:93], v[142:145], v[198:201], v[90:93]
	v_mfma_f32_16x16x32_bf16 v[82:85], v[150:153], v[198:201], v[82:85]
	v_mfma_f32_16x16x32_bf16 v[126:129], v[146:149], v[178:181], v[126:129]
	v_mfma_f32_16x16x32_bf16 v[122:125], v[154:157], v[178:181], v[122:125]
	v_mfma_f32_16x16x32_bf16 v[118:121], v[146:149], v[186:189], v[118:121]
	v_mfma_f32_16x16x32_bf16 v[114:117], v[154:157], v[186:189], v[114:117]
	v_mfma_f32_16x16x32_bf16 v[106:109], v[146:149], v[194:197], v[106:109]
	v_mfma_f32_16x16x32_bf16 v[98:101], v[154:157], v[194:197], v[98:101]
	v_mfma_f32_16x16x32_bf16 v[90:93], v[146:149], v[202:205], v[90:93]
	v_mfma_f32_16x16x32_bf16 v[82:85], v[154:157], v[202:205], v[82:85]
	s_nop 0
	s_nop 0
	v_mfma_f32_16x16x32_bf16 v[110:113], v[158:161], v[174:177], v[110:113]
	v_mfma_f32_16x16x32_bf16 v[102:105], v[166:169], v[174:177], v[102:105]
	v_mfma_f32_16x16x32_bf16 v[94:97], v[158:161], v[182:185], v[94:97]
	v_mfma_f32_16x16x32_bf16 v[86:89], v[166:169], v[182:185], v[86:89]
	v_mfma_f32_16x16x32_bf16 v[78:81], v[158:161], v[190:193], v[78:81]
	v_mfma_f32_16x16x32_bf16 v[74:77], v[166:169], v[190:193], v[74:77]
	v_mfma_f32_16x16x32_bf16 v[70:73], v[158:161], v[198:201], v[70:73]
	v_mfma_f32_16x16x32_bf16 v[66:69], v[166:169], v[198:201], v[66:69]
	v_mfma_f32_16x16x32_bf16 v[110:113], v[162:165], v[178:181], v[110:113]
	v_mfma_f32_16x16x32_bf16 v[102:105], v[170:173], v[178:181], v[102:105]
	v_mfma_f32_16x16x32_bf16 v[94:97], v[162:165], v[186:189], v[94:97]
	v_mfma_f32_16x16x32_bf16 v[86:89], v[170:173], v[186:189], v[86:89]
	v_mfma_f32_16x16x32_bf16 v[78:81], v[162:165], v[194:197], v[78:81]
	v_mfma_f32_16x16x32_bf16 v[74:77], v[170:173], v[194:197], v[74:77]
	v_mfma_f32_16x16x32_bf16 v[70:73], v[162:165], v[202:205], v[70:73]
	v_mfma_f32_16x16x32_bf16 v[66:69], v[170:173], v[202:205], v[66:69]
	s_nop 0
	s_barrier
	s_add_i32 s64, s64, s37
	v_lshl_add_u64 v[206:207], s[62:63], 0, v[132:133]
	s_mov_b32 m0, s64
	ds_read_b128 v[174:177], v244 offset:16384
	ds_read_b128 v[178:181], v244 offset:17408
	ds_read_b128 v[182:185], v244 offset:18432
	ds_read_b128 v[186:189], v244 offset:19456
	ds_read_b128 v[190:193], v244 offset:20480
	ds_read_b128 v[194:197], v244 offset:21504
	ds_read_b128 v[198:201], v244 offset:22528
	ds_read_b128 v[202:205], v244 offset:23552
	global_load_lds_dwordx4 v[206:207], off
	s_add_i32 m0, s64, 0x2000
	v_lshl_add_u64 v[208:209], s[62:63], 0, v[136:137]
	s_add_u32 s62, s62, s16
	s_addc_u32 s63, s63, s17
	s_add_i32 s64, s65, s37
	global_load_lds_dwordx4 v[208:209], off
	v_lshl_add_u64 v[210:211], s[62:63], 0, v[132:133]
	s_mov_b32 m0, s64
	v_lshl_add_u64 v[212:213], s[62:63], 0, v[136:137]
	global_load_lds_dwordx4 v[210:211], off
	s_add_i32 m0, s64, 0x2000
	v_lshl_add_u64 v[214:215], s[34:35], 0, v[130:131]
	global_load_lds_dwordx4 v[212:213], off
	s_mov_b32 m0, s38
	v_lshl_add_u64 v[216:217], s[34:35], 0, v[134:135]
	global_load_lds_dwordx4 v[214:215], off
	s_mov_b32 m0, s39
	s_nop 0
	global_load_lds_dwordx4 v[216:217], off
	s_waitcnt vmcnt(8)
	s_waitcnt lgkmcnt(0)
	s_barrier
; #define PG8_STAGE(bufoff, gbase, voff) do { _Pragma("unroll") for (int _i = 0; _i < 2; ++_i) \
;         __builtin_amdgcn_global_load_lds((const unsigned*)((const char*)(gbase) + (voff)[_i]), (PG8_LAS unsigned*)(lds + (bufoff) + ldsw + _i * 8192), 16, 0, 0); } while (0)
; #define PG8_LDA(dst, b, h) do { _Pragma("unroll") for (int m = 0; m < 4; ++m) _Pragma("unroll") for (int k = 0; k < 2; ++k) dst[m][k] = *(const PG8_LAS bf16x8*)(lds + PG8_SA(b, h) + aoff + m * 2048 + k * 1024); } while (0)
; #define PG8_LDB(dst, b, h) do { _Pragma("unroll") for (int n = 0; n < 2; ++n) _Pragma("unroll") for (int k = 0; k < 2; ++k) dst[n][k] = *(const PG8_LAS bf16x8*)(lds + PG8_SB(b, h) + boff + n * 2048 + k * 1024); } while (0)
; #define PG8_MMA(ai, bj, At, Bt) do { __builtin_amdgcn_s_setprio(1); _Pragma("unroll") for (int m = 0; m < 4; ++m) _Pragma("unroll") for (int n = 0; n < 2; ++n) _Pragma("unroll") for (int k = 0; k < 2; ++k) \
;         acc[ai][bj][m][n] = __builtin_amdgcn_mfma_f32_16x16x32_bf16(Bt[n][k], At[m][k], acc[ai][bj][m][n], 0, 0, 0); __builtin_amdgcn_s_setprio(0); } while (0)
; #define PG8_WAIT_V(n) asm volatile("s_waitcnt vmcnt(" #n ")" ::: "memory")
; #define PG8_WAIT_L(n) asm volatile("s_waitcnt lgkmcnt(" #n ")" ::: "memory")
; #define PG8_BAR __builtin_amdgcn_s_barrier()
; #define PG8_SCHED __builtin_amdgcn_sched_barrier(0)
; template <class Epi, class Sched, bool ALIGN_EPI = false, bool SP2 = false>
; __device__ __forceinline__ void gemm_phase(PG8_LAS unsigned char* lds, const Gemm g, const Sched& S, const Epi& E) {
;     ...
;             PG8_WAIT_V(8); PG8_WAIT_L(0); PG8_BAR; PG8_MMA(1, 0, At, B0); PG8_MMA(1, 1, At, B1); PG8_BAR; PG8_SCHED;
;             PG8_LDB(B0, 1, 0); PG8_LDB(B1, 1, 1); PG8_SCHED; PG8_LDA(At, 1, 0); PG8_STAGE(PG8_SA(0, 1), a2 + hstep, voffA);
;             PG8_WAIT_V(8); PG8_WAIT_L(0); PG8_BAR; PG8_MMA(0, 0, At, B0); PG8_MMA(0, 1, At, B1); PG8_BAR; PG8_SCHED;
	s_nop 0
	s_waitcnt lgkmcnt(0)
	v_mfma_f32_16x16x32_bf16 v[62:65], v[142:145], v[174:177], v[62:65]
	v_mfma_f32_16x16x32_bf16 v[58:61], v[150:153], v[174:177], v[58:61]
	v_mfma_f32_16x16x32_bf16 v[54:57], v[142:145], v[182:185], v[54:57]
	v_mfma_f32_16x16x32_bf16 v[50:53], v[150:153], v[182:185], v[50:53]
	v_mfma_f32_16x16x32_bf16 v[42:45], v[142:145], v[190:193], v[42:45]
	v_mfma_f32_16x16x32_bf16 v[34:37], v[150:153], v[190:193], v[34:37]
	v_mfma_f32_16x16x32_bf16 v[26:29], v[142:145], v[198:201], v[26:29]
	v_mfma_f32_16x16x32_bf16 v[18:21], v[150:153], v[198:201], v[18:21]
	v_mfma_f32_16x16x32_bf16 v[62:65], v[146:149], v[178:181], v[62:65]
	v_mfma_f32_16x16x32_bf16 v[58:61], v[154:157], v[178:181], v[58:61]
	v_mfma_f32_16x16x32_bf16 v[54:57], v[146:149], v[186:189], v[54:57]
	v_mfma_f32_16x16x32_bf16 v[50:53], v[154:157], v[186:189], v[50:53]
	v_mfma_f32_16x16x32_bf16 v[42:45], v[146:149], v[194:197], v[42:45]
	v_mfma_f32_16x16x32_bf16 v[34:37], v[154:157], v[194:197], v[34:37]
	v_mfma_f32_16x16x32_bf16 v[26:29], v[146:149], v[202:205], v[26:29]
	v_mfma_f32_16x16x32_bf16 v[18:21], v[154:157], v[202:205], v[18:21]
	s_nop 0
	s_nop 0
	v_mfma_f32_16x16x32_bf16 v[46:49], v[158:161], v[174:177], v[46:49]
	v_mfma_f32_16x16x32_bf16 v[38:41], v[166:169], v[174:177], v[38:41]
	v_mfma_f32_16x16x32_bf16 v[30:33], v[158:161], v[182:185], v[30:33]
	v_mfma_f32_16x16x32_bf16 v[22:25], v[166:169], v[182:185], v[22:25]
	v_mfma_f32_16x16x32_bf16 v[14:17], v[158:161], v[190:193], v[14:17]
	v_mfma_f32_16x16x32_bf16 v[10:13], v[166:169], v[190:193], v[10:13]
	v_mfma_f32_16x16x32_bf16 v[6:9], v[158:161], v[198:201], v[6:9]
	v_mfma_f32_16x16x32_bf16 v[2:5], v[166:169], v[198:201], v[2:5]
	v_mfma_f32_16x16x32_bf16 v[46:49], v[162:165], v[178:181], v[46:49]
	v_mfma_f32_16x16x32_bf16 v[38:41], v[170:173], v[178:181], v[38:41]
	v_mfma_f32_16x16x32_bf16 v[30:33], v[162:165], v[186:189], v[30:33]
	v_mfma_f32_16x16x32_bf16 v[22:25], v[170:173], v[186:189], v[22:25]
	v_mfma_f32_16x16x32_bf16 v[14:17], v[162:165], v[194:197], v[14:17]
	v_mfma_f32_16x16x32_bf16 v[10:13], v[170:173], v[194:197], v[10:13]
	v_mfma_f32_16x16x32_bf16 v[6:9], v[162:165], v[202:205], v[6:9]
	v_mfma_f32_16x16x32_bf16 v[2:5], v[170:173], v[202:205], v[2:5]
	s_nop 0
	s_barrier
	s_add_i32 s62, 0, 0x18000
	s_add_i32 s63, 0, 0x1c000
	v_add_u32_e32 v154, s62, v242
	v_add_u32_e32 v170, s63, v242
	ds_read_b128 v[142:145], v154
	ds_read_b128 v[146:149], v154 offset:1024
	ds_read_b128 v[150:153], v154 offset:2048
	ds_read_b128 v[154:157], v154 offset:3072
	ds_read_b128 v[158:161], v170
	ds_read_b128 v[162:165], v170 offset:1024
	ds_read_b128 v[166:169], v170 offset:2048
	ds_read_b128 v[170:173], v170 offset:3072
	s_add_u32 s34, s34, s16
	s_addc_u32 s35, s35, s17
	s_mov_b32 m0, s40
	v_lshl_add_u64 v[218:219], s[34:35], 0, v[130:131]
	ds_read_b128 v[174:177], v244 offset:32768
	ds_read_b128 v[178:181], v244 offset:33792
	ds_read_b128 v[182:185], v244 offset:34816
	ds_read_b128 v[186:189], v244 offset:35840
	ds_read_b128 v[190:193], v244 offset:36864
	ds_read_b128 v[194:197], v244 offset:37888
	ds_read_b128 v[198:201], v244 offset:38912
	ds_read_b128 v[202:205], v244 offset:39936
	global_load_lds_dwordx4 v[218:219], off
	v_lshl_add_u64 v[218:219], s[34:35], 0, v[134:135]
	s_mov_b32 m0, s41
	s_nop 0
	global_load_lds_dwordx4 v[218:219], off
	s_waitcnt vmcnt(8)
	s_waitcnt lgkmcnt(0)
	s_barrier
	s_nop 0
	s_waitcnt lgkmcnt(0)
	v_mfma_f32_16x16x32_bf16 v[126:129], v[142:145], v[174:177], v[126:129]
	v_mfma_f32_16x16x32_bf16 v[122:125], v[150:153], v[174:177], v[122:125]
	v_mfma_f32_16x16x32_bf16 v[118:121], v[142:145], v[182:185], v[118:121]
	v_mfma_f32_16x16x32_bf16 v[114:117], v[150:153], v[182:185], v[114:117]
	v_mfma_f32_16x16x32_bf16 v[106:109], v[142:145], v[190:193], v[106:109]
	v_mfma_f32_16x16x32_bf16 v[98:101], v[150:153], v[190:193], v[98:101]
	v_mfma_f32_16x16x32_bf16 v[90:93], v[142:145], v[198:201], v[90:93]
	v_mfma_f32_16x16x32_bf16 v[82:85], v[150:153], v[198:201], v[82:85]
	v_mfma_f32_16x16x32_bf16 v[126:129], v[146:149], v[178:181], v[126:129]
	v_mfma_f32_16x16x32_bf16 v[122:125], v[154:157], v[178:181], v[122:125]
	v_mfma_f32_16x16x32_bf16 v[118:121], v[146:149], v[186:189], v[118:121]
	v_mfma_f32_16x16x32_bf16 v[114:117], v[154:157], v[186:189], v[114:117]
	v_mfma_f32_16x16x32_bf16 v[106:109], v[146:149], v[194:197], v[106:109]
	v_mfma_f32_16x16x32_bf16 v[98:101], v[154:157], v[194:197], v[98:101]
	v_mfma_f32_16x16x32_bf16 v[90:93], v[146:149], v[202:205], v[90:93]
	v_mfma_f32_16x16x32_bf16 v[82:85], v[154:157], v[202:205], v[82:85]
	s_nop 0
	s_nop 0
	v_mfma_f32_16x16x32_bf16 v[110:113], v[158:161], v[174:177], v[110:113]
	v_mfma_f32_16x16x32_bf16 v[102:105], v[166:169], v[174:177], v[102:105]
	v_mfma_f32_16x16x32_bf16 v[94:97], v[158:161], v[182:185], v[94:97]
	v_mfma_f32_16x16x32_bf16 v[86:89], v[166:169], v[182:185], v[86:89]
	v_mfma_f32_16x16x32_bf16 v[78:81], v[158:161], v[190:193], v[78:81]
	v_mfma_f32_16x16x32_bf16 v[74:77], v[166:169], v[190:193], v[74:77]
	v_mfma_f32_16x16x32_bf16 v[70:73], v[158:161], v[198:201], v[70:73]
	v_mfma_f32_16x16x32_bf16 v[66:69], v[166:169], v[198:201], v[66:69]
	v_mfma_f32_16x16x32_bf16 v[110:113], v[162:165], v[178:181], v[110:113]
	v_mfma_f32_16x16x32_bf16 v[102:105], v[170:173], v[178:181], v[102:105]
	v_mfma_f32_16x16x32_bf16 v[94:97], v[162:165], v[186:189], v[94:97]
	v_mfma_f32_16x16x32_bf16 v[86:89], v[170:173], v[186:189], v[86:89]
	v_mfma_f32_16x16x32_bf16 v[78:81], v[162:165], v[194:197], v[78:81]
	v_mfma_f32_16x16x32_bf16 v[74:77], v[170:173], v[194:197], v[74:77]
	v_mfma_f32_16x16x32_bf16 v[70:73], v[162:165], v[202:205], v[70:73]
	v_mfma_f32_16x16x32_bf16 v[66:69], v[170:173], v[202:205], v[66:69]
	s_nop 0
	s_barrier
; #define PG8_STAGE(bufoff, gbase, voff) do { _Pragma("unroll") for (int _i = 0; _i < 2; ++_i) \
;         __builtin_amdgcn_global_load_lds((const unsigned*)((const char*)(gbase) + (voff)[_i]), (PG8_LAS unsigned*)(lds + (bufoff) + ldsw + _i * 8192), 16, 0, 0); } while (0)
; #define PG8_LDA(dst, b, h) do { _Pragma("unroll") for (int m = 0; m < 4; ++m) _Pragma("unroll") for (int k = 0; k < 2; ++k) dst[m][k] = *(const PG8_LAS bf16x8*)(lds + PG8_SA(b, h) + aoff + m * 2048 + k * 1024); } while (0)
; #define PG8_MMA(ai, bj, At, Bt) do { __builtin_amdgcn_s_setprio(1); _Pragma("unroll") for (int m = 0; m < 4; ++m) _Pragma("unroll") for (int n = 0; n < 2; ++n) _Pragma("unroll") for (int k = 0; k < 2; ++k) \
;         acc[ai][bj][m][n] = __builtin_amdgcn_mfma_f32_16x16x32_bf16(Bt[n][k], At[m][k], acc[ai][bj][m][n], 0, 0, 0); __builtin_amdgcn_s_setprio(0); } while (0)
; #define PG8_WAIT_V(n) asm volatile("s_waitcnt vmcnt(" #n ")" ::: "memory")
; #define PG8_WAIT_L(n) asm volatile("s_waitcnt lgkmcnt(" #n ")" ::: "memory")
; #define PG8_BAR __builtin_amdgcn_s_barrier()
; #define PG8_SCHED __builtin_amdgcn_sched_barrier(0)
; template <class Epi, class Sched, bool ALIGN_EPI = false, bool SP2 = false>
; __device__ __forceinline__ void gemm_phase(PG8_LAS unsigned char* lds, const Gemm g, const Sched& S, const Epi& E) {
;     ...
;         for (int t = 0; t < nt; t += 2) {
;     ...
;             PG8_LDA(At, 1, 1); PG8_STAGE(PG8_SB(1, 0), b3, voffB); PG8_STAGE(PG8_SB(1, 1), b3 + hstep, voffB); PG8_STAGE(PG8_SA(1, 0), a3, voffA);
;             PG8_WAIT_V(8); PG8_WAIT_L(0); PG8_BAR; PG8_MMA(1, 0, At, B0); PG8_MMA(1, 1, At, B1); PG8_BAR; PG8_SCHED;
	s_add_i32 s34, s62, s37
	v_lshl_add_u64 v[206:207], v[206:207], 0, s[92:93]
	s_mov_b32 m0, s34
	ds_read_b128 v[174:177], v244 offset:49152
	ds_read_b128 v[178:181], v244 offset:50176
	ds_read_b128 v[182:185], v244 offset:51200
	ds_read_b128 v[186:189], v244 offset:52224
	ds_read_b128 v[190:193], v244 offset:53248
	ds_read_b128 v[194:197], v244 offset:54272
	ds_read_b128 v[198:201], v244 offset:55296
	ds_read_b128 v[202:205], v244 offset:56320
	global_load_lds_dwordx4 v[206:207], off
	v_lshl_add_u64 v[206:207], v[208:209], 0, s[92:93]
	s_add_i32 m0, s34, 0x2000
	s_add_i32 s34, s63, s37
	global_load_lds_dwordx4 v[206:207], off
	v_lshl_add_u64 v[206:207], v[210:211], 0, s[92:93]
	s_mov_b32 m0, s34
	s_nop 0
	global_load_lds_dwordx4 v[206:207], off
	v_lshl_add_u64 v[206:207], v[212:213], 0, s[92:93]
	s_add_i32 m0, s34, 0x2000
	s_nop 0
	global_load_lds_dwordx4 v[206:207], off
	v_lshl_add_u64 v[206:207], v[214:215], 0, s[92:93]
	s_mov_b32 m0, s42
	s_nop 0
	global_load_lds_dwordx4 v[206:207], off
	v_lshl_add_u64 v[206:207], v[216:217], 0, s[92:93]
	s_mov_b32 m0, s43
	s_nop 0
	global_load_lds_dwordx4 v[206:207], off
	s_waitcnt vmcnt(8)
	s_waitcnt lgkmcnt(0)
	s_barrier
	s_nop 0
	s_waitcnt lgkmcnt(0)
	v_mfma_f32_16x16x32_bf16 v[62:65], v[142:145], v[174:177], v[62:65]
	v_mfma_f32_16x16x32_bf16 v[58:61], v[150:153], v[174:177], v[58:61]
	v_mfma_f32_16x16x32_bf16 v[54:57], v[142:145], v[182:185], v[54:57]
	v_mfma_f32_16x16x32_bf16 v[50:53], v[150:153], v[182:185], v[50:53]
	v_mfma_f32_16x16x32_bf16 v[42:45], v[142:145], v[190:193], v[42:45]
	v_mfma_f32_16x16x32_bf16 v[34:37], v[150:153], v[190:193], v[34:37]
	v_mfma_f32_16x16x32_bf16 v[26:29], v[142:145], v[198:201], v[26:29]
	v_mfma_f32_16x16x32_bf16 v[18:21], v[150:153], v[198:201], v[18:21]
	v_mfma_f32_16x16x32_bf16 v[62:65], v[146:149], v[178:181], v[62:65]
	v_mfma_f32_16x16x32_bf16 v[58:61], v[154:157], v[178:181], v[58:61]
	v_mfma_f32_16x16x32_bf16 v[54:57], v[146:149], v[186:189], v[54:57]
	v_mfma_f32_16x16x32_bf16 v[50:53], v[154:157], v[186:189], v[50:53]
	v_mfma_f32_16x16x32_bf16 v[42:45], v[146:149], v[194:197], v[42:45]
	v_mfma_f32_16x16x32_bf16 v[34:37], v[154:157], v[194:197], v[34:37]
	v_mfma_f32_16x16x32_bf16 v[26:29], v[146:149], v[202:205], v[26:29]
	v_mfma_f32_16x16x32_bf16 v[18:21], v[154:157], v[202:205], v[18:21]
	s_nop 0
	s_nop 0
	v_mfma_f32_16x16x32_bf16 v[46:49], v[158:161], v[174:177], v[46:49]
	v_mfma_f32_16x16x32_bf16 v[38:41], v[166:169], v[174:177], v[38:41]
	v_mfma_f32_16x16x32_bf16 v[30:33], v[158:161], v[182:185], v[30:33]
	v_mfma_f32_16x16x32_bf16 v[22:25], v[166:169], v[182:185], v[22:25]
	v_mfma_f32_16x16x32_bf16 v[14:17], v[158:161], v[190:193], v[14:17]
	v_mfma_f32_16x16x32_bf16 v[10:13], v[166:169], v[190:193], v[10:13]
	v_mfma_f32_16x16x32_bf16 v[6:9], v[158:161], v[198:201], v[6:9]
	v_mfma_f32_16x16x32_bf16 v[2:5], v[166:169], v[198:201], v[2:5]
	v_mfma_f32_16x16x32_bf16 v[46:49], v[162:165], v[178:181], v[46:49]
	v_mfma_f32_16x16x32_bf16 v[38:41], v[170:173], v[178:181], v[38:41]
	v_mfma_f32_16x16x32_bf16 v[30:33], v[162:165], v[186:189], v[30:33]
	v_mfma_f32_16x16x32_bf16 v[22:25], v[170:173], v[186:189], v[22:25]
	v_mfma_f32_16x16x32_bf16 v[14:17], v[162:165], v[194:197], v[14:17]
	v_mfma_f32_16x16x32_bf16 v[10:13], v[170:173], v[194:197], v[10:13]
	v_mfma_f32_16x16x32_bf16 v[6:9], v[162:165], v[202:205], v[6:9]
	v_mfma_f32_16x16x32_bf16 v[2:5], v[170:173], v[202:205], v[2:5]
	s_nop 0
	s_barrier
	s_add_u32 s59, s59, 0x100
	s_addc_u32 s60, s60, 0
	s_add_u32 s30, s30, 0x100
	s_addc_u32 s31, s31, 0
	s_cmp_ge_i32 s61, s45
	s_mov_b32 s34, s61
	s_cbranch_scc0 .LBB0_4928
;     __device__ __forceinline__ void operator()(const f32x4 (&acc)[2][2][4][2], const Unit& u, int wr, int wc, int fr, int fq) const {
;     ...
;                     const f32x4 o0 = xv[g & 1][rr][bj][0] + acc[ai][bj][m][0] * scale, o1 = xv[g & 1][rr][bj][1] + acc[ai][bj][m][1] * scale;
	v_pk_mul_f32 v[206:207], v[128:129], 0.5 op_sel_hi:[1,0]
	v_pk_mul_f32 v[212:213], v[126:127], 0.5 op_sel_hi:[1,0]
	v_pk_mul_f32 v[210:211], v[124:125], 0.5 op_sel_hi:[1,0]
	v_pk_mul_f32 v[208:209], v[122:123], 0.5 op_sel_hi:[1,0]
	v_pk_mul_f32 v[202:203], v[112:113], 0.5 op_sel_hi:[1,0]
	v_pk_mul_f32 v[200:201], v[110:111], 0.5 op_sel_hi:[1,0]
	v_pk_mul_f32 v[198:199], v[104:105], 0.5 op_sel_hi:[1,0]
	v_pk_mul_f32 v[196:197], v[102:103], 0.5 op_sel_hi:[1,0]
	v_pk_mul_f32 v[190:191], v[120:121], 0.5 op_sel_hi:[1,0]
	v_pk_mul_f32 v[188:189], v[118:119], 0.5 op_sel_hi:[1,0]
	v_pk_mul_f32 v[186:187], v[116:117], 0.5 op_sel_hi:[1,0]
	v_pk_mul_f32 v[184:185], v[114:115], 0.5 op_sel_hi:[1,0]
	v_pk_mul_f32 v[182:183], v[96:97], 0.5 op_sel_hi:[1,0]
	v_pk_mul_f32 v[180:181], v[94:95], 0.5 op_sel_hi:[1,0]
	v_pk_mul_f32 v[178:179], v[88:89], 0.5 op_sel_hi:[1,0]
	v_pk_mul_f32 v[176:177], v[86:87], 0.5 op_sel_hi:[1,0]
	v_pk_mul_f32 v[174:175], v[108:109], 0.5 op_sel_hi:[1,0]
	v_pk_mul_f32 v[172:173], v[106:107], 0.5 op_sel_hi:[1,0]
	v_pk_mul_f32 v[170:171], v[100:101], 0.5 op_sel_hi:[1,0]
	v_pk_mul_f32 v[168:169], v[98:99], 0.5 op_sel_hi:[1,0]
	v_pk_mul_f32 v[166:167], v[80:81], 0.5 op_sel_hi:[1,0]
	v_pk_mul_f32 v[164:165], v[78:79], 0.5 op_sel_hi:[1,0]
	v_pk_mul_f32 v[162:163], v[76:77], 0.5 op_sel_hi:[1,0]
	v_pk_mul_f32 v[160:161], v[74:75], 0.5 op_sel_hi:[1,0]
	v_pk_mul_f32 v[158:159], v[92:93], 0.5 op_sel_hi:[1,0]
	v_pk_mul_f32 v[156:157], v[90:91], 0.5 op_sel_hi:[1,0]
	v_pk_mul_f32 v[154:155], v[84:85], 0.5 op_sel_hi:[1,0]
	v_pk_mul_f32 v[152:153], v[82:83], 0.5 op_sel_hi:[1,0]
	v_pk_mul_f32 v[150:151], v[72:73], 0.5 op_sel_hi:[1,0]
	v_pk_mul_f32 v[148:149], v[70:71], 0.5 op_sel_hi:[1,0]
	v_pk_mul_f32 v[146:147], v[68:69], 0.5 op_sel_hi:[1,0]
	v_pk_mul_f32 v[144:145], v[66:67], 0.5 op_sel_hi:[1,0]
	v_pk_mul_f32 v[128:129], v[64:65], 0.5 op_sel_hi:[1,0]
	v_pk_mul_f32 v[126:127], v[62:63], 0.5 op_sel_hi:[1,0]
	v_pk_mul_f32 v[124:125], v[60:61], 0.5 op_sel_hi:[1,0]
	v_pk_mul_f32 v[122:123], v[58:59], 0.5 op_sel_hi:[1,0]
	v_pk_mul_f32 v[120:121], v[48:49], 0.5 op_sel_hi:[1,0]
	v_pk_mul_f32 v[118:119], v[46:47], 0.5 op_sel_hi:[1,0]
	v_pk_mul_f32 v[116:117], v[40:41], 0.5 op_sel_hi:[1,0]
	v_pk_mul_f32 v[114:115], v[38:39], 0.5 op_sel_hi:[1,0]
	v_pk_mul_f32 v[112:113], v[56:57], 0.5 op_sel_hi:[1,0]
	v_pk_mul_f32 v[110:111], v[54:55], 0.5 op_sel_hi:[1,0]
	v_pk_mul_f32 v[108:109], v[52:53], 0.5 op_sel_hi:[1,0]
	v_pk_mul_f32 v[106:107], v[50:51], 0.5 op_sel_hi:[1,0]
	v_pk_mul_f32 v[104:105], v[32:33], 0.5 op_sel_hi:[1,0]
	v_pk_mul_f32 v[102:103], v[30:31], 0.5 op_sel_hi:[1,0]
	v_pk_mul_f32 v[100:101], v[24:25], 0.5 op_sel_hi:[1,0]
	v_pk_mul_f32 v[98:99], v[22:23], 0.5 op_sel_hi:[1,0]
	v_pk_mul_f32 v[96:97], v[44:45], 0.5 op_sel_hi:[1,0]
	v_pk_mul_f32 v[94:95], v[42:43], 0.5 op_sel_hi:[1,0]
	v_pk_mul_f32 v[92:93], v[36:37], 0.5 op_sel_hi:[1,0]
	v_pk_mul_f32 v[90:91], v[34:35], 0.5 op_sel_hi:[1,0]
	v_pk_mul_f32 v[88:89], v[16:17], 0.5 op_sel_hi:[1,0]
	v_pk_mul_f32 v[86:87], v[14:15], 0.5 op_sel_hi:[1,0]
	v_pk_mul_f32 v[84:85], v[12:13], 0.5 op_sel_hi:[1,0]
	v_pk_mul_f32 v[82:83], v[10:11], 0.5 op_sel_hi:[1,0]
	v_pk_mul_f32 v[80:81], v[28:29], 0.5 op_sel_hi:[1,0]
	v_pk_mul_f32 v[78:79], v[26:27], 0.5 op_sel_hi:[1,0]
	v_pk_mul_f32 v[76:77], v[20:21], 0.5 op_sel_hi:[1,0]
	v_pk_mul_f32 v[74:75], v[18:19], 0.5 op_sel_hi:[1,0]
	v_pk_mul_f32 v[72:73], v[8:9], 0.5 op_sel_hi:[1,0]
	v_pk_mul_f32 v[70:71], v[6:7], 0.5 op_sel_hi:[1,0]
	v_pk_mul_f32 v[68:69], v[4:5], 0.5 op_sel_hi:[1,0]
	v_pk_mul_f32 v[66:67], v[2:3], 0.5 op_sel_hi:[1,0]

; __device__ __forceinline__ void xcd_barrier(const XcdBarrier& b) {
;     asm volatile("s_waitcnt vmcnt(0)" ::: "memory");
;     __syncthreads();
;     if (b.tid == 0u) {
;         unsigned* bar = b.bar;
;         __builtin_amdgcn_s_waitcnt(0);
;         unsigned nloc = b.st[0], nx = b.st[1];
;         if (nloc == 0u) { xcd_barrier_complete(bar, b.x, nloc, nx); b.st[0] = nloc; b.st[1] = nx; }
.LBB0_4953:
	s_mov_b64 s[2:3], s[88:89]
	s_getreg_b32 s4, hwreg(HW_REG_XCC_ID, 0, 4)
	s_waitcnt vmcnt(0)
	s_waitcnt lgkmcnt(0)
	s_setprio 0
	s_barrier
	s_mov_b64 s[0:1], exec
	v_readlane_b32 s6, v252, 2
	v_readlane_b32 s7, v252, 3
	s_and_b64 s[6:7], s[0:1], s[6:7]
	s_mov_b64 exec, s[6:7]
	s_cbranch_execnz .LBB0_4954
	s_getpc_b64 s[98:99]
